# v021 + pooling pass P10: hand-written fast path for whole waves (chunk>=1): all 32 rows + window halo rows of a chunk requested up front and the running sums formed from registers (was one exposed mem
# speedup vs baseline: 1.0109x; 1.0109x over previous
; __device__ __forceinline__ unsigned cvtpk(float lo, float hi) { return pg8::cvt_pk_bf16(lo, hi); }
; __device__ __forceinline__ float bflo(unsigned u) { return __uint_as_float(u << 16); }
; __device__ __forceinline__ float bfhi(unsigned u) { return __uint_as_float(u & 0xffff0000u); }
; __device__ __forceinline__ void pool_pass(const bf16* __restrict__ U, bf16* __restrict__ Y, int gtid, int gthreads) {
;     for (int task = gtid; task < BATCH * 128 * 128; task += gthreads) {
;         const int chg = task & 127, chunk = (task >> 7) & 127, b = task >> 14;
;         const int w = 2 << (chg >> 5);
;         const bf16* up = U + (size_t)b * SEQ * 1024 + chg * 8; bf16* yp = Y + (size_t)b * SEQ * 1024 + chg * 8;
;         const int t0 = chunk * 32;
;         float sum[8];
; #pragma unroll
;         for (int j = 0; j < 8; ++j) sum[j] = 0.f;
;         for (int i = 1; i < w; ++i) { const int t = t0 - i; if (t >= 0) { const v4u v = *(const v4u*)(up + (size_t)t * 1024);
; #pragma unroll
;             for (int j = 0; j < 4; ++j) { sum[2 * j] += bflo(v[j]); sum[2 * j + 1] += bfhi(v[j]); } } }
; #pragma unroll 4
;         for (int t = t0; t < t0 + 32; ++t) {
;             const v4u v = *(const v4u*)(up + (size_t)t * 1024);
;             const int tb = t - w; v4u vb = {0u, 0u, 0u, 0u};
;             if (t > t0 && tb >= 0) vb = *(const v4u*)(up + (size_t)tb * 1024);
;             const float rc = 1.0f / (float)((t + 1 < w) ? (t + 1) : w);
;             v4u o;
; #pragma unroll
;             for (int j = 0; j < 4; ++j) { const float c0 = bflo(v[j]), c1 = bfhi(v[j]);
;                 sum[2 * j] += c0 - bflo(vb[j]); sum[2 * j + 1] += c1 - bfhi(vb[j]);
;                 o[j] = cvtpk(sum[2 * j] * rc - c0, sum[2 * j + 1] * rc - c1); }
;             __builtin_nontemporal_store(o, (v4u*)(yp + (size_t)t * 1024));
.LBB0_931:
	s_cmp_eq_u64 exec, -1
	s_cbranch_scc0 .Lp10_slow
	v_readfirstlane_b32 s15, v155
	s_bfe_u32 s15, s15, 0x70007
	s_cmp_eq_u32 s15, 0
	s_cbranch_scc1 .Lp10_slow
	v_ashrrev_i32_e32 v0, 14, v155
	v_ashrrev_i32_e32 v1, 31, v0
	v_lshlrev_b64 v[0:1], 23, v[0:1]
	v_lshl_add_u64 v[22:23], v[18:19], 0, v[0:1]
	s_lshl_b32 s2, s15, 16
	s_mov_b32 s3, 0
	v_lshl_add_u64 v[2:3], v[22:23], 0, s[2:3]
	s_mov_b32 s16, 0x2000
	s_mov_b32 s17, 0
	s_mov_b32 s12, 0
	s_mov_b32 s13, -1
	s_mov_b64 vcc, s[12:13]
	v_ffbl_b32_e32 v4, v32
	v_lshlrev_b32_e32 v4, 23, v4
	v_sub_u32_e32 v24, 0x3f800000, v4
	v_readfirstlane_b32 s15, v32
	s_cmp_eq_u32 s15, 2
	s_cbranch_scc1 .Lp10_w2
	s_cmp_eq_u32 s15, 8
	s_cbranch_scc1 .Lp10_w8
	s_branch .Lp10_slow
.Lp10_w2:
	s_mov_b32 s2, 0xffff9800
	s_mov_b32 s3, -1
	v_lshl_add_u64 v[4:5], v[2:3], 0, s[2:3]
	v_lshl_add_u64 v[4:5], v[4:5], 0, s[16:17]
	v_lshl_add_u64 v[4:5], v[4:5], 0, s[16:17]
	v_lshl_add_u64 v[4:5], v[4:5], 0, s[16:17]
	s_mov_b64 exec, s[12:13]
	global_load_dwordx4 v[88:91], v[4:5], off offset:-4096
	global_load_dwordx4 v[92:95], v[4:5], off offset:-2048
	s_mov_b64 exec, -1
	global_load_dwordx4 v[96:99], v[4:5], off
	global_load_dwordx4 v[100:103], v[4:5], off offset:2048
	v_lshl_add_u64 v[4:5], v[4:5], 0, s[16:17]
	global_load_dwordx4 v[104:107], v[4:5], off offset:-4096
	global_load_dwordx4 v[108:111], v[4:5], off offset:-2048
	global_load_dwordx4 v[112:115], v[4:5], off
	global_load_dwordx4 v[116:119], v[4:5], off offset:2048
	v_lshl_add_u64 v[4:5], v[4:5], 0, s[16:17]
	global_load_dwordx4 v[120:123], v[4:5], off offset:-4096
	global_load_dwordx4 v[124:127], v[4:5], off offset:-2048
	global_load_dwordx4 v[128:131], v[4:5], off
	global_load_dwordx4 v[132:135], v[4:5], off offset:2048
	v_lshl_add_u64 v[4:5], v[4:5], 0, s[16:17]
	global_load_dwordx4 v[136:139], v[4:5], off offset:-4096
	global_load_dwordx4 v[140:143], v[4:5], off offset:-2048
	global_load_dwordx4 v[144:147], v[4:5], off
	global_load_dwordx4 v[148:151], v[4:5], off offset:2048
	v_lshl_add_u64 v[4:5], v[4:5], 0, s[16:17]
	global_load_dwordx4 v[156:159], v[4:5], off offset:-4096
	global_load_dwordx4 v[160:163], v[4:5], off offset:-2048
	global_load_dwordx4 v[164:167], v[4:5], off
	global_load_dwordx4 v[168:171], v[4:5], off offset:2048
	v_lshl_add_u64 v[4:5], v[4:5], 0, s[16:17]
	global_load_dwordx4 v[172:175], v[4:5], off offset:-4096
	global_load_dwordx4 v[176:179], v[4:5], off offset:-2048
	global_load_dwordx4 v[180:183], v[4:5], off
	global_load_dwordx4 v[184:187], v[4:5], off offset:2048
	v_lshl_add_u64 v[4:5], v[4:5], 0, s[16:17]
	global_load_dwordx4 v[188:191], v[4:5], off offset:-4096
	global_load_dwordx4 v[192:195], v[4:5], off offset:-2048
	global_load_dwordx4 v[196:199], v[4:5], off
	global_load_dwordx4 v[200:203], v[4:5], off offset:2048
	v_lshl_add_u64 v[4:5], v[4:5], 0, s[16:17]
	global_load_dwordx4 v[204:207], v[4:5], off offset:-4096
	global_load_dwordx4 v[208:211], v[4:5], off offset:-2048
	global_load_dwordx4 v[212:215], v[4:5], off
	global_load_dwordx4 v[216:219], v[4:5], off offset:2048
	v_lshl_add_u64 v[4:5], v[4:5], 0, s[16:17]
	global_load_dwordx4 v[220:223], v[4:5], off offset:-4096
	global_load_dwordx4 v[224:227], v[4:5], off offset:-2048
	global_load_dwordx4 v[228:231], v[4:5], off
	s_mov_b32 s2, 0x8001000
	s_mov_b32 s3, 0
	v_lshl_add_u64 v[6:7], v[2:3], 0, s[2:3]
	v_mov_b32_e32 v26, 0
	v_mov_b32_e32 v27, 0
	v_mov_b32_e32 v28, 0
	v_mov_b32_e32 v29, 0
	v_mov_b32_e32 v30, 0
	v_mov_b32_e32 v31, 0
	v_mov_b32_e32 v8, 0
	v_mov_b32_e32 v9, 0
	s_waitcnt vmcnt(32)
	v_lshlrev_b32_e32 v0, 16, v96
	v_and_b32_e32 v1, 0xffff0000, v96
	v_pk_add_f32 v[26:27], v[26:27], v[0:1]
	v_lshlrev_b32_e32 v0, 16, v97
	v_and_b32_e32 v1, 0xffff0000, v97
	v_pk_add_f32 v[28:29], v[28:29], v[0:1]
	v_lshlrev_b32_e32 v0, 16, v98
	v_and_b32_e32 v1, 0xffff0000, v98
	v_pk_add_f32 v[30:31], v[30:31], v[0:1]
	v_lshlrev_b32_e32 v0, 16, v99
	v_and_b32_e32 v1, 0xffff0000, v99
	v_pk_add_f32 v[8:9], v[8:9], v[0:1]
	s_mov_b64 exec, s[12:13]
	v_lshlrev_b32_e32 v0, 16, v92
	v_and_b32_e32 v1, 0xffff0000, v92
	v_pk_add_f32 v[26:27], v[26:27], v[0:1]
	v_lshlrev_b32_e32 v0, 16, v93
	v_and_b32_e32 v1, 0xffff0000, v93
	v_pk_add_f32 v[28:29], v[28:29], v[0:1]
	v_lshlrev_b32_e32 v0, 16, v94
	v_and_b32_e32 v1, 0xffff0000, v94
	v_pk_add_f32 v[30:31], v[30:31], v[0:1]
	v_lshlrev_b32_e32 v0, 16, v95
	v_and_b32_e32 v1, 0xffff0000, v95
	v_pk_add_f32 v[8:9], v[8:9], v[0:1]
	v_lshlrev_b32_e32 v0, 16, v88
	v_and_b32_e32 v1, 0xffff0000, v88
	v_pk_add_f32 v[26:27], v[26:27], v[0:1]
	v_lshlrev_b32_e32 v0, 16, v89
	v_and_b32_e32 v1, 0xffff0000, v89
	v_pk_add_f32 v[28:29], v[28:29], v[0:1]
	v_lshlrev_b32_e32 v0, 16, v90
	v_and_b32_e32 v1, 0xffff0000, v90
	v_pk_add_f32 v[30:31], v[30:31], v[0:1]
	v_lshlrev_b32_e32 v0, 16, v91
	v_and_b32_e32 v1, 0xffff0000, v91
	v_pk_add_f32 v[8:9], v[8:9], v[0:1]
	s_mov_b64 exec, -1
	s_waitcnt vmcnt(31)
	v_lshlrev_b32_e32 v10, 16, v100
	v_and_b32_e32 v11, 0xffff0000, v100
	v_pk_add_f32 v[26:27], v[26:27], v[10:11]
	v_pk_fma_f32 v[0:1], v[24:25], v[26:27], v[10:11] op_sel_hi:[0,1,1] neg_lo:[0,0,1] neg_hi:[0,0,1]
	v_cvt_pk_bf16_f32 v36, v0, v1
	v_lshlrev_b32_e32 v12, 16, v101
	v_and_b32_e32 v13, 0xffff0000, v101
	v_pk_add_f32 v[28:29], v[28:29], v[12:13]
	v_pk_fma_f32 v[0:1], v[24:25], v[28:29], v[12:13] op_sel_hi:[0,1,1] neg_lo:[0,0,1] neg_hi:[0,0,1]
	v_cvt_pk_bf16_f32 v37, v0, v1
	v_lshlrev_b32_e32 v14, 16, v102
	v_and_b32_e32 v15, 0xffff0000, v102
	v_pk_add_f32 v[30:31], v[30:31], v[14:15]
	v_pk_fma_f32 v[0:1], v[24:25], v[30:31], v[14:15] op_sel_hi:[0,1,1] neg_lo:[0,0,1] neg_hi:[0,0,1]
	v_cvt_pk_bf16_f32 v38, v0, v1
	v_lshlrev_b32_e32 v22, 16, v103
	v_and_b32_e32 v23, 0xffff0000, v103
	v_pk_add_f32 v[8:9], v[8:9], v[22:23]
	v_pk_fma_f32 v[0:1], v[24:25], v[8:9], v[22:23] op_sel_hi:[0,1,1] neg_lo:[0,0,1] neg_hi:[0,0,1]
	v_cvt_pk_bf16_f32 v39, v0, v1
	global_store_dwordx4 v[6:7], v[36:39], off offset:-4096 nt
	s_waitcnt vmcnt(31)
; __device__ __forceinline__ unsigned cvtpk(float lo, float hi) { return pg8::cvt_pk_bf16(lo, hi); }
; __device__ __forceinline__ float bflo(unsigned u) { return __uint_as_float(u << 16); }
; __device__ __forceinline__ float bfhi(unsigned u) { return __uint_as_float(u & 0xffff0000u); }
; __device__ __forceinline__ void pool_pass(const bf16* __restrict__ U, bf16* __restrict__ Y, int gtid, int gthreads) {
;     ...
;         for (int t = t0; t < t0 + 32; ++t) {
;             const v4u v = *(const v4u*)(up + (size_t)t * 1024);
;             const int tb = t - w; v4u vb = {0u, 0u, 0u, 0u};
;             if (t > t0 && tb >= 0) vb = *(const v4u*)(up + (size_t)tb * 1024);
;             const float rc = 1.0f / (float)((t + 1 < w) ? (t + 1) : w);
;             v4u o;
; #pragma unroll
;             for (int j = 0; j < 4; ++j) { const float c0 = bflo(v[j]), c1 = bfhi(v[j]);
;                 sum[2 * j] += c0 - bflo(vb[j]); sum[2 * j + 1] += c1 - bfhi(vb[j]);
;                 o[j] = cvtpk(sum[2 * j] * rc - c0, sum[2 * j + 1] * rc - c1); }
;             __builtin_nontemporal_store(o, (v4u*)(yp + (size_t)t * 1024));
	v_lshlrev_b32_e32 v10, 16, v104
	v_and_b32_e32 v11, 0xffff0000, v104
	v_cndmask_b32_e32 v35, v96, v88, vcc
	v_lshlrev_b32_e32 v0, 16, v35
	v_and_b32_e32 v1, 0xffff0000, v35
	v_pk_add_f32 v[0:1], v[10:11], v[0:1] neg_lo:[0,1] neg_hi:[0,1]
	v_pk_add_f32 v[26:27], v[26:27], v[0:1]
	v_pk_fma_f32 v[0:1], v[24:25], v[26:27], v[10:11] op_sel_hi:[0,1,1] neg_lo:[0,0,1] neg_hi:[0,0,1]
	v_cvt_pk_bf16_f32 v36, v0, v1
	v_lshlrev_b32_e32 v12, 16, v105
	v_and_b32_e32 v13, 0xffff0000, v105
	v_cndmask_b32_e32 v35, v97, v89, vcc
	v_lshlrev_b32_e32 v0, 16, v35
	v_and_b32_e32 v1, 0xffff0000, v35
	v_pk_add_f32 v[0:1], v[12:13], v[0:1] neg_lo:[0,1] neg_hi:[0,1]
	v_pk_add_f32 v[28:29], v[28:29], v[0:1]
	v_pk_fma_f32 v[0:1], v[24:25], v[28:29], v[12:13] op_sel_hi:[0,1,1] neg_lo:[0,0,1] neg_hi:[0,0,1]
	v_cvt_pk_bf16_f32 v37, v0, v1
	v_lshlrev_b32_e32 v14, 16, v106
	v_and_b32_e32 v15, 0xffff0000, v106
	v_cndmask_b32_e32 v35, v98, v90, vcc
	v_lshlrev_b32_e32 v0, 16, v35
	v_and_b32_e32 v1, 0xffff0000, v35
	v_pk_add_f32 v[0:1], v[14:15], v[0:1] neg_lo:[0,1] neg_hi:[0,1]
	v_pk_add_f32 v[30:31], v[30:31], v[0:1]
	v_pk_fma_f32 v[0:1], v[24:25], v[30:31], v[14:15] op_sel_hi:[0,1,1] neg_lo:[0,0,1] neg_hi:[0,0,1]
	v_cvt_pk_bf16_f32 v38, v0, v1
	v_lshlrev_b32_e32 v22, 16, v107
	v_and_b32_e32 v23, 0xffff0000, v107
	v_cndmask_b32_e32 v35, v99, v91, vcc
	v_lshlrev_b32_e32 v0, 16, v35
	v_and_b32_e32 v1, 0xffff0000, v35
	v_pk_add_f32 v[0:1], v[22:23], v[0:1] neg_lo:[0,1] neg_hi:[0,1]
	v_pk_add_f32 v[8:9], v[8:9], v[0:1]
	v_pk_fma_f32 v[0:1], v[24:25], v[8:9], v[22:23] op_sel_hi:[0,1,1] neg_lo:[0,0,1] neg_hi:[0,0,1]
	v_cvt_pk_bf16_f32 v39, v0, v1
	global_store_dwordx4 v[6:7], v[36:39], off offset:-2048 nt
	s_waitcnt vmcnt(31)
	v_lshlrev_b32_e32 v10, 16, v108
	v_and_b32_e32 v11, 0xffff0000, v108
	v_cndmask_b32_e32 v35, v100, v92, vcc
	v_lshlrev_b32_e32 v0, 16, v35
	v_and_b32_e32 v1, 0xffff0000, v35
	v_pk_add_f32 v[0:1], v[10:11], v[0:1] neg_lo:[0,1] neg_hi:[0,1]
	v_pk_add_f32 v[26:27], v[26:27], v[0:1]
	v_pk_fma_f32 v[0:1], v[24:25], v[26:27], v[10:11] op_sel_hi:[0,1,1] neg_lo:[0,0,1] neg_hi:[0,0,1]
	v_cvt_pk_bf16_f32 v36, v0, v1
	v_lshlrev_b32_e32 v12, 16, v109
	v_and_b32_e32 v13, 0xffff0000, v109
	v_cndmask_b32_e32 v35, v101, v93, vcc
	v_lshlrev_b32_e32 v0, 16, v35
	v_and_b32_e32 v1, 0xffff0000, v35
	v_pk_add_f32 v[0:1], v[12:13], v[0:1] neg_lo:[0,1] neg_hi:[0,1]
	v_pk_add_f32 v[28:29], v[28:29], v[0:1]
	v_pk_fma_f32 v[0:1], v[24:25], v[28:29], v[12:13] op_sel_hi:[0,1,1] neg_lo:[0,0,1] neg_hi:[0,0,1]
	v_cvt_pk_bf16_f32 v37, v0, v1
	v_lshlrev_b32_e32 v14, 16, v110
	v_and_b32_e32 v15, 0xffff0000, v110
	v_cndmask_b32_e32 v35, v102, v94, vcc
	v_lshlrev_b32_e32 v0, 16, v35
	v_and_b32_e32 v1, 0xffff0000, v35
	v_pk_add_f32 v[0:1], v[14:15], v[0:1] neg_lo:[0,1] neg_hi:[0,1]
	v_pk_add_f32 v[30:31], v[30:31], v[0:1]
	v_pk_fma_f32 v[0:1], v[24:25], v[30:31], v[14:15] op_sel_hi:[0,1,1] neg_lo:[0,0,1] neg_hi:[0,0,1]
	v_cvt_pk_bf16_f32 v38, v0, v1
	v_lshlrev_b32_e32 v22, 16, v111
	v_and_b32_e32 v23, 0xffff0000, v111
	v_cndmask_b32_e32 v35, v103, v95, vcc
	v_lshlrev_b32_e32 v0, 16, v35
	v_and_b32_e32 v1, 0xffff0000, v35
	v_pk_add_f32 v[0:1], v[22:23], v[0:1] neg_lo:[0,1] neg_hi:[0,1]
	v_pk_add_f32 v[8:9], v[8:9], v[0:1]
	v_pk_fma_f32 v[0:1], v[24:25], v[8:9], v[22:23] op_sel_hi:[0,1,1] neg_lo:[0,0,1] neg_hi:[0,0,1]
	v_cvt_pk_bf16_f32 v39, v0, v1
	global_store_dwordx4 v[6:7], v[36:39], off nt
	s_waitcnt vmcnt(31)
	v_lshlrev_b32_e32 v10, 16, v112
	v_and_b32_e32 v11, 0xffff0000, v112
	v_cndmask_b32_e32 v35, v104, v96, vcc
	v_lshlrev_b32_e32 v0, 16, v35
	v_and_b32_e32 v1, 0xffff0000, v35
	v_pk_add_f32 v[0:1], v[10:11], v[0:1] neg_lo:[0,1] neg_hi:[0,1]
	v_pk_add_f32 v[26:27], v[26:27], v[0:1]
	v_pk_fma_f32 v[0:1], v[24:25], v[26:27], v[10:11] op_sel_hi:[0,1,1] neg_lo:[0,0,1] neg_hi:[0,0,1]
	v_cvt_pk_bf16_f32 v36, v0, v1
	v_lshlrev_b32_e32 v12, 16, v113
	v_and_b32_e32 v13, 0xffff0000, v113
	v_cndmask_b32_e32 v35, v105, v97, vcc
	v_lshlrev_b32_e32 v0, 16, v35
	v_and_b32_e32 v1, 0xffff0000, v35
	v_pk_add_f32 v[0:1], v[12:13], v[0:1] neg_lo:[0,1] neg_hi:[0,1]
	v_pk_add_f32 v[28:29], v[28:29], v[0:1]
	v_pk_fma_f32 v[0:1], v[24:25], v[28:29], v[12:13] op_sel_hi:[0,1,1] neg_lo:[0,0,1] neg_hi:[0,0,1]
	v_cvt_pk_bf16_f32 v37, v0, v1
	v_lshlrev_b32_e32 v14, 16, v114
	v_and_b32_e32 v15, 0xffff0000, v114
	v_cndmask_b32_e32 v35, v106, v98, vcc
	v_lshlrev_b32_e32 v0, 16, v35
	v_and_b32_e32 v1, 0xffff0000, v35
	v_pk_add_f32 v[0:1], v[14:15], v[0:1] neg_lo:[0,1] neg_hi:[0,1]
	v_pk_add_f32 v[30:31], v[30:31], v[0:1]
	v_pk_fma_f32 v[0:1], v[24:25], v[30:31], v[14:15] op_sel_hi:[0,1,1] neg_lo:[0,0,1] neg_hi:[0,0,1]
	v_cvt_pk_bf16_f32 v38, v0, v1
	v_lshlrev_b32_e32 v22, 16, v115
	v_and_b32_e32 v23, 0xffff0000, v115
	v_cndmask_b32_e32 v35, v107, v99, vcc
	v_lshlrev_b32_e32 v0, 16, v35
	v_and_b32_e32 v1, 0xffff0000, v35
	v_pk_add_f32 v[0:1], v[22:23], v[0:1] neg_lo:[0,1] neg_hi:[0,1]
	v_pk_add_f32 v[8:9], v[8:9], v[0:1]
	v_pk_fma_f32 v[0:1], v[24:25], v[8:9], v[22:23] op_sel_hi:[0,1,1] neg_lo:[0,0,1] neg_hi:[0,0,1]
	v_cvt_pk_bf16_f32 v39, v0, v1
	global_store_dwordx4 v[6:7], v[36:39], off offset:2048 nt
	s_waitcnt vmcnt(31)
; __device__ __forceinline__ unsigned cvtpk(float lo, float hi) { return pg8::cvt_pk_bf16(lo, hi); }
; __device__ __forceinline__ float bflo(unsigned u) { return __uint_as_float(u << 16); }
; __device__ __forceinline__ float bfhi(unsigned u) { return __uint_as_float(u & 0xffff0000u); }
; __device__ __forceinline__ void pool_pass(const bf16* __restrict__ U, bf16* __restrict__ Y, int gtid, int gthreads) {
;     ...
;         for (int t = t0; t < t0 + 32; ++t) {
;             const v4u v = *(const v4u*)(up + (size_t)t * 1024);
;             const int tb = t - w; v4u vb = {0u, 0u, 0u, 0u};
;             if (t > t0 && tb >= 0) vb = *(const v4u*)(up + (size_t)tb * 1024);
;             const float rc = 1.0f / (float)((t + 1 < w) ? (t + 1) : w);
;             v4u o;
; #pragma unroll
;             for (int j = 0; j < 4; ++j) { const float c0 = bflo(v[j]), c1 = bfhi(v[j]);
;                 sum[2 * j] += c0 - bflo(vb[j]); sum[2 * j + 1] += c1 - bfhi(vb[j]);
;                 o[j] = cvtpk(sum[2 * j] * rc - c0, sum[2 * j + 1] * rc - c1); }
;             __builtin_nontemporal_store(o, (v4u*)(yp + (size_t)t * 1024));
	v_lshlrev_b32_e32 v10, 16, v116
	v_and_b32_e32 v11, 0xffff0000, v116
	v_cndmask_b32_e32 v35, v108, v100, vcc
	v_lshlrev_b32_e32 v0, 16, v35
	v_and_b32_e32 v1, 0xffff0000, v35
	v_pk_add_f32 v[0:1], v[10:11], v[0:1] neg_lo:[0,1] neg_hi:[0,1]
	v_pk_add_f32 v[26:27], v[26:27], v[0:1]
	v_pk_fma_f32 v[0:1], v[24:25], v[26:27], v[10:11] op_sel_hi:[0,1,1] neg_lo:[0,0,1] neg_hi:[0,0,1]
	v_cvt_pk_bf16_f32 v36, v0, v1
	v_lshlrev_b32_e32 v12, 16, v117
	v_and_b32_e32 v13, 0xffff0000, v117
	v_cndmask_b32_e32 v35, v109, v101, vcc
	v_lshlrev_b32_e32 v0, 16, v35
	v_and_b32_e32 v1, 0xffff0000, v35
	v_pk_add_f32 v[0:1], v[12:13], v[0:1] neg_lo:[0,1] neg_hi:[0,1]
	v_pk_add_f32 v[28:29], v[28:29], v[0:1]
	v_pk_fma_f32 v[0:1], v[24:25], v[28:29], v[12:13] op_sel_hi:[0,1,1] neg_lo:[0,0,1] neg_hi:[0,0,1]
	v_cvt_pk_bf16_f32 v37, v0, v1
	v_lshlrev_b32_e32 v14, 16, v118
	v_and_b32_e32 v15, 0xffff0000, v118
	v_cndmask_b32_e32 v35, v110, v102, vcc
	v_lshlrev_b32_e32 v0, 16, v35
	v_and_b32_e32 v1, 0xffff0000, v35
	v_pk_add_f32 v[0:1], v[14:15], v[0:1] neg_lo:[0,1] neg_hi:[0,1]
	v_pk_add_f32 v[30:31], v[30:31], v[0:1]
	v_pk_fma_f32 v[0:1], v[24:25], v[30:31], v[14:15] op_sel_hi:[0,1,1] neg_lo:[0,0,1] neg_hi:[0,0,1]
	v_cvt_pk_bf16_f32 v38, v0, v1
	v_lshlrev_b32_e32 v22, 16, v119
	v_and_b32_e32 v23, 0xffff0000, v119
	v_cndmask_b32_e32 v35, v111, v103, vcc
	v_lshlrev_b32_e32 v0, 16, v35
	v_and_b32_e32 v1, 0xffff0000, v35
	v_pk_add_f32 v[0:1], v[22:23], v[0:1] neg_lo:[0,1] neg_hi:[0,1]
	v_pk_add_f32 v[8:9], v[8:9], v[0:1]
	v_pk_fma_f32 v[0:1], v[24:25], v[8:9], v[22:23] op_sel_hi:[0,1,1] neg_lo:[0,0,1] neg_hi:[0,0,1]
	v_cvt_pk_bf16_f32 v39, v0, v1
	v_lshl_add_u64 v[6:7], v[6:7], 0, s[16:17]
	global_store_dwordx4 v[6:7], v[36:39], off offset:-4096 nt
	s_waitcnt vmcnt(31)
	v_lshlrev_b32_e32 v10, 16, v120
	v_and_b32_e32 v11, 0xffff0000, v120
	v_cndmask_b32_e32 v35, v112, v104, vcc
	v_lshlrev_b32_e32 v0, 16, v35
	v_and_b32_e32 v1, 0xffff0000, v35
	v_pk_add_f32 v[0:1], v[10:11], v[0:1] neg_lo:[0,1] neg_hi:[0,1]
	v_pk_add_f32 v[26:27], v[26:27], v[0:1]
	v_pk_fma_f32 v[0:1], v[24:25], v[26:27], v[10:11] op_sel_hi:[0,1,1] neg_lo:[0,0,1] neg_hi:[0,0,1]
	v_cvt_pk_bf16_f32 v36, v0, v1
	v_lshlrev_b32_e32 v12, 16, v121
	v_and_b32_e32 v13, 0xffff0000, v121
	v_cndmask_b32_e32 v35, v113, v105, vcc
	v_lshlrev_b32_e32 v0, 16, v35
	v_and_b32_e32 v1, 0xffff0000, v35
	v_pk_add_f32 v[0:1], v[12:13], v[0:1] neg_lo:[0,1] neg_hi:[0,1]
	v_pk_add_f32 v[28:29], v[28:29], v[0:1]
	v_pk_fma_f32 v[0:1], v[24:25], v[28:29], v[12:13] op_sel_hi:[0,1,1] neg_lo:[0,0,1] neg_hi:[0,0,1]
	v_cvt_pk_bf16_f32 v37, v0, v1
	v_lshlrev_b32_e32 v14, 16, v122
	v_and_b32_e32 v15, 0xffff0000, v122
	v_cndmask_b32_e32 v35, v114, v106, vcc
	v_lshlrev_b32_e32 v0, 16, v35
	v_and_b32_e32 v1, 0xffff0000, v35
	v_pk_add_f32 v[0:1], v[14:15], v[0:1] neg_lo:[0,1] neg_hi:[0,1]
	v_pk_add_f32 v[30:31], v[30:31], v[0:1]
	v_pk_fma_f32 v[0:1], v[24:25], v[30:31], v[14:15] op_sel_hi:[0,1,1] neg_lo:[0,0,1] neg_hi:[0,0,1]
	v_cvt_pk_bf16_f32 v38, v0, v1
	v_lshlrev_b32_e32 v22, 16, v123
	v_and_b32_e32 v23, 0xffff0000, v123
	v_cndmask_b32_e32 v35, v115, v107, vcc
	v_lshlrev_b32_e32 v0, 16, v35
	v_and_b32_e32 v1, 0xffff0000, v35
	v_pk_add_f32 v[0:1], v[22:23], v[0:1] neg_lo:[0,1] neg_hi:[0,1]
	v_pk_add_f32 v[8:9], v[8:9], v[0:1]
	v_pk_fma_f32 v[0:1], v[24:25], v[8:9], v[22:23] op_sel_hi:[0,1,1] neg_lo:[0,0,1] neg_hi:[0,0,1]
	v_cvt_pk_bf16_f32 v39, v0, v1
	global_store_dwordx4 v[6:7], v[36:39], off offset:-2048 nt
	s_waitcnt vmcnt(31)
	v_lshlrev_b32_e32 v10, 16, v124
	v_and_b32_e32 v11, 0xffff0000, v124
	v_cndmask_b32_e32 v35, v116, v108, vcc
	v_lshlrev_b32_e32 v0, 16, v35
	v_and_b32_e32 v1, 0xffff0000, v35
	v_pk_add_f32 v[0:1], v[10:11], v[0:1] neg_lo:[0,1] neg_hi:[0,1]
	v_pk_add_f32 v[26:27], v[26:27], v[0:1]
	v_pk_fma_f32 v[0:1], v[24:25], v[26:27], v[10:11] op_sel_hi:[0,1,1] neg_lo:[0,0,1] neg_hi:[0,0,1]
	v_cvt_pk_bf16_f32 v36, v0, v1
	v_lshlrev_b32_e32 v12, 16, v125
	v_and_b32_e32 v13, 0xffff0000, v125
	v_cndmask_b32_e32 v35, v117, v109, vcc
	v_lshlrev_b32_e32 v0, 16, v35
	v_and_b32_e32 v1, 0xffff0000, v35
	v_pk_add_f32 v[0:1], v[12:13], v[0:1] neg_lo:[0,1] neg_hi:[0,1]
	v_pk_add_f32 v[28:29], v[28:29], v[0:1]
	v_pk_fma_f32 v[0:1], v[24:25], v[28:29], v[12:13] op_sel_hi:[0,1,1] neg_lo:[0,0,1] neg_hi:[0,0,1]
	v_cvt_pk_bf16_f32 v37, v0, v1
	v_lshlrev_b32_e32 v14, 16, v126
	v_and_b32_e32 v15, 0xffff0000, v126
	v_cndmask_b32_e32 v35, v118, v110, vcc
	v_lshlrev_b32_e32 v0, 16, v35
	v_and_b32_e32 v1, 0xffff0000, v35
	v_pk_add_f32 v[0:1], v[14:15], v[0:1] neg_lo:[0,1] neg_hi:[0,1]
	v_pk_add_f32 v[30:31], v[30:31], v[0:1]
	v_pk_fma_f32 v[0:1], v[24:25], v[30:31], v[14:15] op_sel_hi:[0,1,1] neg_lo:[0,0,1] neg_hi:[0,0,1]
	v_cvt_pk_bf16_f32 v38, v0, v1
	v_lshlrev_b32_e32 v22, 16, v127
	v_and_b32_e32 v23, 0xffff0000, v127
	v_cndmask_b32_e32 v35, v119, v111, vcc
	v_lshlrev_b32_e32 v0, 16, v35
	v_and_b32_e32 v1, 0xffff0000, v35
	v_pk_add_f32 v[0:1], v[22:23], v[0:1] neg_lo:[0,1] neg_hi:[0,1]
	v_pk_add_f32 v[8:9], v[8:9], v[0:1]
	v_pk_fma_f32 v[0:1], v[24:25], v[8:9], v[22:23] op_sel_hi:[0,1,1] neg_lo:[0,0,1] neg_hi:[0,0,1]
	v_cvt_pk_bf16_f32 v39, v0, v1
	global_store_dwordx4 v[6:7], v[36:39], off nt
	s_waitcnt vmcnt(31)
; __device__ __forceinline__ unsigned cvtpk(float lo, float hi) { return pg8::cvt_pk_bf16(lo, hi); }
; __device__ __forceinline__ float bflo(unsigned u) { return __uint_as_float(u << 16); }
; __device__ __forceinline__ float bfhi(unsigned u) { return __uint_as_float(u & 0xffff0000u); }
; __device__ __forceinline__ void pool_pass(const bf16* __restrict__ U, bf16* __restrict__ Y, int gtid, int gthreads) {
;     ...
;         for (int t = t0; t < t0 + 32; ++t) {
;             const v4u v = *(const v4u*)(up + (size_t)t * 1024);
;             const int tb = t - w; v4u vb = {0u, 0u, 0u, 0u};
;             if (t > t0 && tb >= 0) vb = *(const v4u*)(up + (size_t)tb * 1024);
;             const float rc = 1.0f / (float)((t + 1 < w) ? (t + 1) : w);
;             v4u o;
; #pragma unroll
;             for (int j = 0; j < 4; ++j) { const float c0 = bflo(v[j]), c1 = bfhi(v[j]);
;                 sum[2 * j] += c0 - bflo(vb[j]); sum[2 * j + 1] += c1 - bfhi(vb[j]);
;                 o[j] = cvtpk(sum[2 * j] * rc - c0, sum[2 * j + 1] * rc - c1); }
;             __builtin_nontemporal_store(o, (v4u*)(yp + (size_t)t * 1024));
	v_lshlrev_b32_e32 v10, 16, v128
	v_and_b32_e32 v11, 0xffff0000, v128
	v_cndmask_b32_e32 v35, v120, v112, vcc
	v_lshlrev_b32_e32 v0, 16, v35
	v_and_b32_e32 v1, 0xffff0000, v35
	v_pk_add_f32 v[0:1], v[10:11], v[0:1] neg_lo:[0,1] neg_hi:[0,1]
	v_pk_add_f32 v[26:27], v[26:27], v[0:1]
	v_pk_fma_f32 v[0:1], v[24:25], v[26:27], v[10:11] op_sel_hi:[0,1,1] neg_lo:[0,0,1] neg_hi:[0,0,1]
	v_cvt_pk_bf16_f32 v36, v0, v1
	v_lshlrev_b32_e32 v12, 16, v129
	v_and_b32_e32 v13, 0xffff0000, v129
	v_cndmask_b32_e32 v35, v121, v113, vcc
	v_lshlrev_b32_e32 v0, 16, v35
	v_and_b32_e32 v1, 0xffff0000, v35
	v_pk_add_f32 v[0:1], v[12:13], v[0:1] neg_lo:[0,1] neg_hi:[0,1]
	v_pk_add_f32 v[28:29], v[28:29], v[0:1]
	v_pk_fma_f32 v[0:1], v[24:25], v[28:29], v[12:13] op_sel_hi:[0,1,1] neg_lo:[0,0,1] neg_hi:[0,0,1]
	v_cvt_pk_bf16_f32 v37, v0, v1
	v_lshlrev_b32_e32 v14, 16, v130
	v_and_b32_e32 v15, 0xffff0000, v130
	v_cndmask_b32_e32 v35, v122, v114, vcc
	v_lshlrev_b32_e32 v0, 16, v35
	v_and_b32_e32 v1, 0xffff0000, v35
	v_pk_add_f32 v[0:1], v[14:15], v[0:1] neg_lo:[0,1] neg_hi:[0,1]
	v_pk_add_f32 v[30:31], v[30:31], v[0:1]
	v_pk_fma_f32 v[0:1], v[24:25], v[30:31], v[14:15] op_sel_hi:[0,1,1] neg_lo:[0,0,1] neg_hi:[0,0,1]
	v_cvt_pk_bf16_f32 v38, v0, v1
	v_lshlrev_b32_e32 v22, 16, v131
	v_and_b32_e32 v23, 0xffff0000, v131
	v_cndmask_b32_e32 v35, v123, v115, vcc
	v_lshlrev_b32_e32 v0, 16, v35
	v_and_b32_e32 v1, 0xffff0000, v35
	v_pk_add_f32 v[0:1], v[22:23], v[0:1] neg_lo:[0,1] neg_hi:[0,1]
	v_pk_add_f32 v[8:9], v[8:9], v[0:1]
	v_pk_fma_f32 v[0:1], v[24:25], v[8:9], v[22:23] op_sel_hi:[0,1,1] neg_lo:[0,0,1] neg_hi:[0,0,1]
	v_cvt_pk_bf16_f32 v39, v0, v1
	global_store_dwordx4 v[6:7], v[36:39], off offset:2048 nt
	s_waitcnt vmcnt(31)
	v_lshlrev_b32_e32 v10, 16, v132
	v_and_b32_e32 v11, 0xffff0000, v132
	v_cndmask_b32_e32 v35, v124, v116, vcc
	v_lshlrev_b32_e32 v0, 16, v35
	v_and_b32_e32 v1, 0xffff0000, v35
	v_pk_add_f32 v[0:1], v[10:11], v[0:1] neg_lo:[0,1] neg_hi:[0,1]
	v_pk_add_f32 v[26:27], v[26:27], v[0:1]
	v_pk_fma_f32 v[0:1], v[24:25], v[26:27], v[10:11] op_sel_hi:[0,1,1] neg_lo:[0,0,1] neg_hi:[0,0,1]
	v_cvt_pk_bf16_f32 v36, v0, v1
	v_lshlrev_b32_e32 v12, 16, v133
	v_and_b32_e32 v13, 0xffff0000, v133
	v_cndmask_b32_e32 v35, v125, v117, vcc
	v_lshlrev_b32_e32 v0, 16, v35
	v_and_b32_e32 v1, 0xffff0000, v35
	v_pk_add_f32 v[0:1], v[12:13], v[0:1] neg_lo:[0,1] neg_hi:[0,1]
	v_pk_add_f32 v[28:29], v[28:29], v[0:1]
	v_pk_fma_f32 v[0:1], v[24:25], v[28:29], v[12:13] op_sel_hi:[0,1,1] neg_lo:[0,0,1] neg_hi:[0,0,1]
	v_cvt_pk_bf16_f32 v37, v0, v1
	v_lshlrev_b32_e32 v14, 16, v134
	v_and_b32_e32 v15, 0xffff0000, v134
	v_cndmask_b32_e32 v35, v126, v118, vcc
	v_lshlrev_b32_e32 v0, 16, v35
	v_and_b32_e32 v1, 0xffff0000, v35
	v_pk_add_f32 v[0:1], v[14:15], v[0:1] neg_lo:[0,1] neg_hi:[0,1]
	v_pk_add_f32 v[30:31], v[30:31], v[0:1]
	v_pk_fma_f32 v[0:1], v[24:25], v[30:31], v[14:15] op_sel_hi:[0,1,1] neg_lo:[0,0,1] neg_hi:[0,0,1]
	v_cvt_pk_bf16_f32 v38, v0, v1
	v_lshlrev_b32_e32 v22, 16, v135
	v_and_b32_e32 v23, 0xffff0000, v135
	v_cndmask_b32_e32 v35, v127, v119, vcc
	v_lshlrev_b32_e32 v0, 16, v35
	v_and_b32_e32 v1, 0xffff0000, v35
	v_pk_add_f32 v[0:1], v[22:23], v[0:1] neg_lo:[0,1] neg_hi:[0,1]
	v_pk_add_f32 v[8:9], v[8:9], v[0:1]
	v_pk_fma_f32 v[0:1], v[24:25], v[8:9], v[22:23] op_sel_hi:[0,1,1] neg_lo:[0,0,1] neg_hi:[0,0,1]
	v_cvt_pk_bf16_f32 v39, v0, v1
	v_lshl_add_u64 v[6:7], v[6:7], 0, s[16:17]
	global_store_dwordx4 v[6:7], v[36:39], off offset:-4096 nt
	s_waitcnt vmcnt(31)
	v_lshlrev_b32_e32 v10, 16, v136
	v_and_b32_e32 v11, 0xffff0000, v136
	v_cndmask_b32_e32 v35, v128, v120, vcc
	v_lshlrev_b32_e32 v0, 16, v35
	v_and_b32_e32 v1, 0xffff0000, v35
	v_pk_add_f32 v[0:1], v[10:11], v[0:1] neg_lo:[0,1] neg_hi:[0,1]
	v_pk_add_f32 v[26:27], v[26:27], v[0:1]
	v_pk_fma_f32 v[0:1], v[24:25], v[26:27], v[10:11] op_sel_hi:[0,1,1] neg_lo:[0,0,1] neg_hi:[0,0,1]
	v_cvt_pk_bf16_f32 v36, v0, v1
	v_lshlrev_b32_e32 v12, 16, v137
	v_and_b32_e32 v13, 0xffff0000, v137
	v_cndmask_b32_e32 v35, v129, v121, vcc
	v_lshlrev_b32_e32 v0, 16, v35
	v_and_b32_e32 v1, 0xffff0000, v35
	v_pk_add_f32 v[0:1], v[12:13], v[0:1] neg_lo:[0,1] neg_hi:[0,1]
	v_pk_add_f32 v[28:29], v[28:29], v[0:1]
	v_pk_fma_f32 v[0:1], v[24:25], v[28:29], v[12:13] op_sel_hi:[0,1,1] neg_lo:[0,0,1] neg_hi:[0,0,1]
	v_cvt_pk_bf16_f32 v37, v0, v1
	v_lshlrev_b32_e32 v14, 16, v138
	v_and_b32_e32 v15, 0xffff0000, v138
	v_cndmask_b32_e32 v35, v130, v122, vcc
	v_lshlrev_b32_e32 v0, 16, v35
	v_and_b32_e32 v1, 0xffff0000, v35
	v_pk_add_f32 v[0:1], v[14:15], v[0:1] neg_lo:[0,1] neg_hi:[0,1]
	v_pk_add_f32 v[30:31], v[30:31], v[0:1]
	v_pk_fma_f32 v[0:1], v[24:25], v[30:31], v[14:15] op_sel_hi:[0,1,1] neg_lo:[0,0,1] neg_hi:[0,0,1]
	v_cvt_pk_bf16_f32 v38, v0, v1
	v_lshlrev_b32_e32 v22, 16, v139
	v_and_b32_e32 v23, 0xffff0000, v139
	v_cndmask_b32_e32 v35, v131, v123, vcc
	v_lshlrev_b32_e32 v0, 16, v35
	v_and_b32_e32 v1, 0xffff0000, v35
	v_pk_add_f32 v[0:1], v[22:23], v[0:1] neg_lo:[0,1] neg_hi:[0,1]
	v_pk_add_f32 v[8:9], v[8:9], v[0:1]
	v_pk_fma_f32 v[0:1], v[24:25], v[8:9], v[22:23] op_sel_hi:[0,1,1] neg_lo:[0,0,1] neg_hi:[0,0,1]
	v_cvt_pk_bf16_f32 v39, v0, v1
	global_store_dwordx4 v[6:7], v[36:39], off offset:-2048 nt
	s_waitcnt vmcnt(31)
; __device__ __forceinline__ unsigned cvtpk(float lo, float hi) { return pg8::cvt_pk_bf16(lo, hi); }
; __device__ __forceinline__ float bflo(unsigned u) { return __uint_as_float(u << 16); }
; __device__ __forceinline__ float bfhi(unsigned u) { return __uint_as_float(u & 0xffff0000u); }
; __device__ __forceinline__ void pool_pass(const bf16* __restrict__ U, bf16* __restrict__ Y, int gtid, int gthreads) {
;     ...
;         for (int t = t0; t < t0 + 32; ++t) {
;             const v4u v = *(const v4u*)(up + (size_t)t * 1024);
;             const int tb = t - w; v4u vb = {0u, 0u, 0u, 0u};
;             if (t > t0 && tb >= 0) vb = *(const v4u*)(up + (size_t)tb * 1024);
;             const float rc = 1.0f / (float)((t + 1 < w) ? (t + 1) : w);
;             v4u o;
; #pragma unroll
;             for (int j = 0; j < 4; ++j) { const float c0 = bflo(v[j]), c1 = bfhi(v[j]);
;                 sum[2 * j] += c0 - bflo(vb[j]); sum[2 * j + 1] += c1 - bfhi(vb[j]);
;                 o[j] = cvtpk(sum[2 * j] * rc - c0, sum[2 * j + 1] * rc - c1); }
;             __builtin_nontemporal_store(o, (v4u*)(yp + (size_t)t * 1024));
	v_lshlrev_b32_e32 v10, 16, v140
	v_and_b32_e32 v11, 0xffff0000, v140
	v_cndmask_b32_e32 v35, v132, v124, vcc
	v_lshlrev_b32_e32 v0, 16, v35
	v_and_b32_e32 v1, 0xffff0000, v35
	v_pk_add_f32 v[0:1], v[10:11], v[0:1] neg_lo:[0,1] neg_hi:[0,1]
	v_pk_add_f32 v[26:27], v[26:27], v[0:1]
	v_pk_fma_f32 v[0:1], v[24:25], v[26:27], v[10:11] op_sel_hi:[0,1,1] neg_lo:[0,0,1] neg_hi:[0,0,1]
	v_cvt_pk_bf16_f32 v36, v0, v1
	v_lshlrev_b32_e32 v12, 16, v141
	v_and_b32_e32 v13, 0xffff0000, v141
	v_cndmask_b32_e32 v35, v133, v125, vcc
	v_lshlrev_b32_e32 v0, 16, v35
	v_and_b32_e32 v1, 0xffff0000, v35
	v_pk_add_f32 v[0:1], v[12:13], v[0:1] neg_lo:[0,1] neg_hi:[0,1]
	v_pk_add_f32 v[28:29], v[28:29], v[0:1]
	v_pk_fma_f32 v[0:1], v[24:25], v[28:29], v[12:13] op_sel_hi:[0,1,1] neg_lo:[0,0,1] neg_hi:[0,0,1]
	v_cvt_pk_bf16_f32 v37, v0, v1
	v_lshlrev_b32_e32 v14, 16, v142
	v_and_b32_e32 v15, 0xffff0000, v142
	v_cndmask_b32_e32 v35, v134, v126, vcc
	v_lshlrev_b32_e32 v0, 16, v35
	v_and_b32_e32 v1, 0xffff0000, v35
	v_pk_add_f32 v[0:1], v[14:15], v[0:1] neg_lo:[0,1] neg_hi:[0,1]
	v_pk_add_f32 v[30:31], v[30:31], v[0:1]
	v_pk_fma_f32 v[0:1], v[24:25], v[30:31], v[14:15] op_sel_hi:[0,1,1] neg_lo:[0,0,1] neg_hi:[0,0,1]
	v_cvt_pk_bf16_f32 v38, v0, v1
	v_lshlrev_b32_e32 v22, 16, v143
	v_and_b32_e32 v23, 0xffff0000, v143
	v_cndmask_b32_e32 v35, v135, v127, vcc
	v_lshlrev_b32_e32 v0, 16, v35
	v_and_b32_e32 v1, 0xffff0000, v35
	v_pk_add_f32 v[0:1], v[22:23], v[0:1] neg_lo:[0,1] neg_hi:[0,1]
	v_pk_add_f32 v[8:9], v[8:9], v[0:1]
	v_pk_fma_f32 v[0:1], v[24:25], v[8:9], v[22:23] op_sel_hi:[0,1,1] neg_lo:[0,0,1] neg_hi:[0,0,1]
	v_cvt_pk_bf16_f32 v39, v0, v1
	global_store_dwordx4 v[6:7], v[36:39], off nt
	s_waitcnt vmcnt(31)
	v_lshlrev_b32_e32 v10, 16, v144
	v_and_b32_e32 v11, 0xffff0000, v144
	v_cndmask_b32_e32 v35, v136, v128, vcc
	v_lshlrev_b32_e32 v0, 16, v35
	v_and_b32_e32 v1, 0xffff0000, v35
	v_pk_add_f32 v[0:1], v[10:11], v[0:1] neg_lo:[0,1] neg_hi:[0,1]
	v_pk_add_f32 v[26:27], v[26:27], v[0:1]
	v_pk_fma_f32 v[0:1], v[24:25], v[26:27], v[10:11] op_sel_hi:[0,1,1] neg_lo:[0,0,1] neg_hi:[0,0,1]
	v_cvt_pk_bf16_f32 v36, v0, v1
	v_lshlrev_b32_e32 v12, 16, v145
	v_and_b32_e32 v13, 0xffff0000, v145
	v_cndmask_b32_e32 v35, v137, v129, vcc
	v_lshlrev_b32_e32 v0, 16, v35
	v_and_b32_e32 v1, 0xffff0000, v35
	v_pk_add_f32 v[0:1], v[12:13], v[0:1] neg_lo:[0,1] neg_hi:[0,1]
	v_pk_add_f32 v[28:29], v[28:29], v[0:1]
	v_pk_fma_f32 v[0:1], v[24:25], v[28:29], v[12:13] op_sel_hi:[0,1,1] neg_lo:[0,0,1] neg_hi:[0,0,1]
	v_cvt_pk_bf16_f32 v37, v0, v1
	v_lshlrev_b32_e32 v14, 16, v146
	v_and_b32_e32 v15, 0xffff0000, v146
	v_cndmask_b32_e32 v35, v138, v130, vcc
	v_lshlrev_b32_e32 v0, 16, v35
	v_and_b32_e32 v1, 0xffff0000, v35
	v_pk_add_f32 v[0:1], v[14:15], v[0:1] neg_lo:[0,1] neg_hi:[0,1]
	v_pk_add_f32 v[30:31], v[30:31], v[0:1]
	v_pk_fma_f32 v[0:1], v[24:25], v[30:31], v[14:15] op_sel_hi:[0,1,1] neg_lo:[0,0,1] neg_hi:[0,0,1]
	v_cvt_pk_bf16_f32 v38, v0, v1
	v_lshlrev_b32_e32 v22, 16, v147
	v_and_b32_e32 v23, 0xffff0000, v147
	v_cndmask_b32_e32 v35, v139, v131, vcc
	v_lshlrev_b32_e32 v0, 16, v35
	v_and_b32_e32 v1, 0xffff0000, v35
	v_pk_add_f32 v[0:1], v[22:23], v[0:1] neg_lo:[0,1] neg_hi:[0,1]
	v_pk_add_f32 v[8:9], v[8:9], v[0:1]
	v_pk_fma_f32 v[0:1], v[24:25], v[8:9], v[22:23] op_sel_hi:[0,1,1] neg_lo:[0,0,1] neg_hi:[0,0,1]
	v_cvt_pk_bf16_f32 v39, v0, v1
	global_store_dwordx4 v[6:7], v[36:39], off offset:2048 nt
	s_waitcnt vmcnt(31)
	v_lshlrev_b32_e32 v10, 16, v148
	v_and_b32_e32 v11, 0xffff0000, v148
	v_cndmask_b32_e32 v35, v140, v132, vcc
	v_lshlrev_b32_e32 v0, 16, v35
	v_and_b32_e32 v1, 0xffff0000, v35
	v_pk_add_f32 v[0:1], v[10:11], v[0:1] neg_lo:[0,1] neg_hi:[0,1]
	v_pk_add_f32 v[26:27], v[26:27], v[0:1]
	v_pk_fma_f32 v[0:1], v[24:25], v[26:27], v[10:11] op_sel_hi:[0,1,1] neg_lo:[0,0,1] neg_hi:[0,0,1]
	v_cvt_pk_bf16_f32 v36, v0, v1
	v_lshlrev_b32_e32 v12, 16, v149
	v_and_b32_e32 v13, 0xffff0000, v149
	v_cndmask_b32_e32 v35, v141, v133, vcc
	v_lshlrev_b32_e32 v0, 16, v35
	v_and_b32_e32 v1, 0xffff0000, v35
	v_pk_add_f32 v[0:1], v[12:13], v[0:1] neg_lo:[0,1] neg_hi:[0,1]
	v_pk_add_f32 v[28:29], v[28:29], v[0:1]
	v_pk_fma_f32 v[0:1], v[24:25], v[28:29], v[12:13] op_sel_hi:[0,1,1] neg_lo:[0,0,1] neg_hi:[0,0,1]
	v_cvt_pk_bf16_f32 v37, v0, v1
	v_lshlrev_b32_e32 v14, 16, v150
	v_and_b32_e32 v15, 0xffff0000, v150
	v_cndmask_b32_e32 v35, v142, v134, vcc
	v_lshlrev_b32_e32 v0, 16, v35
	v_and_b32_e32 v1, 0xffff0000, v35
	v_pk_add_f32 v[0:1], v[14:15], v[0:1] neg_lo:[0,1] neg_hi:[0,1]
	v_pk_add_f32 v[30:31], v[30:31], v[0:1]
	v_pk_fma_f32 v[0:1], v[24:25], v[30:31], v[14:15] op_sel_hi:[0,1,1] neg_lo:[0,0,1] neg_hi:[0,0,1]
	v_cvt_pk_bf16_f32 v38, v0, v1
	v_lshlrev_b32_e32 v22, 16, v151
	v_and_b32_e32 v23, 0xffff0000, v151
	v_cndmask_b32_e32 v35, v143, v135, vcc
	v_lshlrev_b32_e32 v0, 16, v35
	v_and_b32_e32 v1, 0xffff0000, v35
	v_pk_add_f32 v[0:1], v[22:23], v[0:1] neg_lo:[0,1] neg_hi:[0,1]
	v_pk_add_f32 v[8:9], v[8:9], v[0:1]
	v_pk_fma_f32 v[0:1], v[24:25], v[8:9], v[22:23] op_sel_hi:[0,1,1] neg_lo:[0,0,1] neg_hi:[0,0,1]
	v_cvt_pk_bf16_f32 v39, v0, v1
	v_lshl_add_u64 v[6:7], v[6:7], 0, s[16:17]
	global_store_dwordx4 v[6:7], v[36:39], off offset:-4096 nt
	s_waitcnt vmcnt(31)
; __device__ __forceinline__ unsigned cvtpk(float lo, float hi) { return pg8::cvt_pk_bf16(lo, hi); }
; __device__ __forceinline__ float bflo(unsigned u) { return __uint_as_float(u << 16); }
; __device__ __forceinline__ float bfhi(unsigned u) { return __uint_as_float(u & 0xffff0000u); }
; __device__ __forceinline__ void pool_pass(const bf16* __restrict__ U, bf16* __restrict__ Y, int gtid, int gthreads) {
;     ...
;         for (int t = t0; t < t0 + 32; ++t) {
;             const v4u v = *(const v4u*)(up + (size_t)t * 1024);
;             const int tb = t - w; v4u vb = {0u, 0u, 0u, 0u};
;             if (t > t0 && tb >= 0) vb = *(const v4u*)(up + (size_t)tb * 1024);
;             const float rc = 1.0f / (float)((t + 1 < w) ? (t + 1) : w);
;             v4u o;
; #pragma unroll
;             for (int j = 0; j < 4; ++j) { const float c0 = bflo(v[j]), c1 = bfhi(v[j]);
;                 sum[2 * j] += c0 - bflo(vb[j]); sum[2 * j + 1] += c1 - bfhi(vb[j]);
;                 o[j] = cvtpk(sum[2 * j] * rc - c0, sum[2 * j + 1] * rc - c1); }
;             __builtin_nontemporal_store(o, (v4u*)(yp + (size_t)t * 1024));
	v_lshlrev_b32_e32 v10, 16, v156
	v_and_b32_e32 v11, 0xffff0000, v156
	v_cndmask_b32_e32 v35, v144, v136, vcc
	v_lshlrev_b32_e32 v0, 16, v35
	v_and_b32_e32 v1, 0xffff0000, v35
	v_pk_add_f32 v[0:1], v[10:11], v[0:1] neg_lo:[0,1] neg_hi:[0,1]
	v_pk_add_f32 v[26:27], v[26:27], v[0:1]
	v_pk_fma_f32 v[0:1], v[24:25], v[26:27], v[10:11] op_sel_hi:[0,1,1] neg_lo:[0,0,1] neg_hi:[0,0,1]
	v_cvt_pk_bf16_f32 v36, v0, v1
	v_lshlrev_b32_e32 v12, 16, v157
	v_and_b32_e32 v13, 0xffff0000, v157
	v_cndmask_b32_e32 v35, v145, v137, vcc
	v_lshlrev_b32_e32 v0, 16, v35
	v_and_b32_e32 v1, 0xffff0000, v35
	v_pk_add_f32 v[0:1], v[12:13], v[0:1] neg_lo:[0,1] neg_hi:[0,1]
	v_pk_add_f32 v[28:29], v[28:29], v[0:1]
	v_pk_fma_f32 v[0:1], v[24:25], v[28:29], v[12:13] op_sel_hi:[0,1,1] neg_lo:[0,0,1] neg_hi:[0,0,1]
	v_cvt_pk_bf16_f32 v37, v0, v1
	v_lshlrev_b32_e32 v14, 16, v158
	v_and_b32_e32 v15, 0xffff0000, v158
	v_cndmask_b32_e32 v35, v146, v138, vcc
	v_lshlrev_b32_e32 v0, 16, v35
	v_and_b32_e32 v1, 0xffff0000, v35
	v_pk_add_f32 v[0:1], v[14:15], v[0:1] neg_lo:[0,1] neg_hi:[0,1]
	v_pk_add_f32 v[30:31], v[30:31], v[0:1]
	v_pk_fma_f32 v[0:1], v[24:25], v[30:31], v[14:15] op_sel_hi:[0,1,1] neg_lo:[0,0,1] neg_hi:[0,0,1]
	v_cvt_pk_bf16_f32 v38, v0, v1
	v_lshlrev_b32_e32 v22, 16, v159
	v_and_b32_e32 v23, 0xffff0000, v159
	v_cndmask_b32_e32 v35, v147, v139, vcc
	v_lshlrev_b32_e32 v0, 16, v35
	v_and_b32_e32 v1, 0xffff0000, v35
	v_pk_add_f32 v[0:1], v[22:23], v[0:1] neg_lo:[0,1] neg_hi:[0,1]
	v_pk_add_f32 v[8:9], v[8:9], v[0:1]
	v_pk_fma_f32 v[0:1], v[24:25], v[8:9], v[22:23] op_sel_hi:[0,1,1] neg_lo:[0,0,1] neg_hi:[0,0,1]
	v_cvt_pk_bf16_f32 v39, v0, v1
	global_store_dwordx4 v[6:7], v[36:39], off offset:-2048 nt
	s_waitcnt vmcnt(31)
	v_lshlrev_b32_e32 v10, 16, v160
	v_and_b32_e32 v11, 0xffff0000, v160
	v_cndmask_b32_e32 v35, v148, v140, vcc
	v_lshlrev_b32_e32 v0, 16, v35
	v_and_b32_e32 v1, 0xffff0000, v35
	v_pk_add_f32 v[0:1], v[10:11], v[0:1] neg_lo:[0,1] neg_hi:[0,1]
	v_pk_add_f32 v[26:27], v[26:27], v[0:1]
	v_pk_fma_f32 v[0:1], v[24:25], v[26:27], v[10:11] op_sel_hi:[0,1,1] neg_lo:[0,0,1] neg_hi:[0,0,1]
	v_cvt_pk_bf16_f32 v36, v0, v1
	v_lshlrev_b32_e32 v12, 16, v161
	v_and_b32_e32 v13, 0xffff0000, v161
	v_cndmask_b32_e32 v35, v149, v141, vcc
	v_lshlrev_b32_e32 v0, 16, v35
	v_and_b32_e32 v1, 0xffff0000, v35
	v_pk_add_f32 v[0:1], v[12:13], v[0:1] neg_lo:[0,1] neg_hi:[0,1]
	v_pk_add_f32 v[28:29], v[28:29], v[0:1]
	v_pk_fma_f32 v[0:1], v[24:25], v[28:29], v[12:13] op_sel_hi:[0,1,1] neg_lo:[0,0,1] neg_hi:[0,0,1]
	v_cvt_pk_bf16_f32 v37, v0, v1
	v_lshlrev_b32_e32 v14, 16, v162
	v_and_b32_e32 v15, 0xffff0000, v162
	v_cndmask_b32_e32 v35, v150, v142, vcc
	v_lshlrev_b32_e32 v0, 16, v35
	v_and_b32_e32 v1, 0xffff0000, v35
	v_pk_add_f32 v[0:1], v[14:15], v[0:1] neg_lo:[0,1] neg_hi:[0,1]
	v_pk_add_f32 v[30:31], v[30:31], v[0:1]
	v_pk_fma_f32 v[0:1], v[24:25], v[30:31], v[14:15] op_sel_hi:[0,1,1] neg_lo:[0,0,1] neg_hi:[0,0,1]
	v_cvt_pk_bf16_f32 v38, v0, v1
	v_lshlrev_b32_e32 v22, 16, v163
	v_and_b32_e32 v23, 0xffff0000, v163
	v_cndmask_b32_e32 v35, v151, v143, vcc
	v_lshlrev_b32_e32 v0, 16, v35
	v_and_b32_e32 v1, 0xffff0000, v35
	v_pk_add_f32 v[0:1], v[22:23], v[0:1] neg_lo:[0,1] neg_hi:[0,1]
	v_pk_add_f32 v[8:9], v[8:9], v[0:1]
	v_pk_fma_f32 v[0:1], v[24:25], v[8:9], v[22:23] op_sel_hi:[0,1,1] neg_lo:[0,0,1] neg_hi:[0,0,1]
	v_cvt_pk_bf16_f32 v39, v0, v1
	global_store_dwordx4 v[6:7], v[36:39], off nt
	s_waitcnt vmcnt(31)
	v_lshlrev_b32_e32 v10, 16, v164
	v_and_b32_e32 v11, 0xffff0000, v164
	v_cndmask_b32_e32 v35, v156, v144, vcc
	v_lshlrev_b32_e32 v0, 16, v35
	v_and_b32_e32 v1, 0xffff0000, v35
	v_pk_add_f32 v[0:1], v[10:11], v[0:1] neg_lo:[0,1] neg_hi:[0,1]
	v_pk_add_f32 v[26:27], v[26:27], v[0:1]
	v_pk_fma_f32 v[0:1], v[24:25], v[26:27], v[10:11] op_sel_hi:[0,1,1] neg_lo:[0,0,1] neg_hi:[0,0,1]
	v_cvt_pk_bf16_f32 v36, v0, v1
	v_lshlrev_b32_e32 v12, 16, v165
	v_and_b32_e32 v13, 0xffff0000, v165
	v_cndmask_b32_e32 v35, v157, v145, vcc
	v_lshlrev_b32_e32 v0, 16, v35
	v_and_b32_e32 v1, 0xffff0000, v35
	v_pk_add_f32 v[0:1], v[12:13], v[0:1] neg_lo:[0,1] neg_hi:[0,1]
	v_pk_add_f32 v[28:29], v[28:29], v[0:1]
	v_pk_fma_f32 v[0:1], v[24:25], v[28:29], v[12:13] op_sel_hi:[0,1,1] neg_lo:[0,0,1] neg_hi:[0,0,1]
	v_cvt_pk_bf16_f32 v37, v0, v1
	v_lshlrev_b32_e32 v14, 16, v166
	v_and_b32_e32 v15, 0xffff0000, v166
	v_cndmask_b32_e32 v35, v158, v146, vcc
	v_lshlrev_b32_e32 v0, 16, v35
	v_and_b32_e32 v1, 0xffff0000, v35
	v_pk_add_f32 v[0:1], v[14:15], v[0:1] neg_lo:[0,1] neg_hi:[0,1]
	v_pk_add_f32 v[30:31], v[30:31], v[0:1]
	v_pk_fma_f32 v[0:1], v[24:25], v[30:31], v[14:15] op_sel_hi:[0,1,1] neg_lo:[0,0,1] neg_hi:[0,0,1]
	v_cvt_pk_bf16_f32 v38, v0, v1
	v_lshlrev_b32_e32 v22, 16, v167
	v_and_b32_e32 v23, 0xffff0000, v167
	v_cndmask_b32_e32 v35, v159, v147, vcc
	v_lshlrev_b32_e32 v0, 16, v35
	v_and_b32_e32 v1, 0xffff0000, v35
	v_pk_add_f32 v[0:1], v[22:23], v[0:1] neg_lo:[0,1] neg_hi:[0,1]
	v_pk_add_f32 v[8:9], v[8:9], v[0:1]
	v_pk_fma_f32 v[0:1], v[24:25], v[8:9], v[22:23] op_sel_hi:[0,1,1] neg_lo:[0,0,1] neg_hi:[0,0,1]
	v_cvt_pk_bf16_f32 v39, v0, v1
	global_store_dwordx4 v[6:7], v[36:39], off offset:2048 nt
	s_waitcnt vmcnt(31)
; __device__ __forceinline__ unsigned cvtpk(float lo, float hi) { return pg8::cvt_pk_bf16(lo, hi); }
; __device__ __forceinline__ float bflo(unsigned u) { return __uint_as_float(u << 16); }
; __device__ __forceinline__ float bfhi(unsigned u) { return __uint_as_float(u & 0xffff0000u); }
; __device__ __forceinline__ void pool_pass(const bf16* __restrict__ U, bf16* __restrict__ Y, int gtid, int gthreads) {
;     ...
;         for (int t = t0; t < t0 + 32; ++t) {
;             const v4u v = *(const v4u*)(up + (size_t)t * 1024);
;             const int tb = t - w; v4u vb = {0u, 0u, 0u, 0u};
;             if (t > t0 && tb >= 0) vb = *(const v4u*)(up + (size_t)tb * 1024);
;             const float rc = 1.0f / (float)((t + 1 < w) ? (t + 1) : w);
;             v4u o;
; #pragma unroll
;             for (int j = 0; j < 4; ++j) { const float c0 = bflo(v[j]), c1 = bfhi(v[j]);
;                 sum[2 * j] += c0 - bflo(vb[j]); sum[2 * j + 1] += c1 - bfhi(vb[j]);
;                 o[j] = cvtpk(sum[2 * j] * rc - c0, sum[2 * j + 1] * rc - c1); }
;             __builtin_nontemporal_store(o, (v4u*)(yp + (size_t)t * 1024));
	v_lshlrev_b32_e32 v10, 16, v168
	v_and_b32_e32 v11, 0xffff0000, v168
	v_cndmask_b32_e32 v35, v160, v148, vcc
	v_lshlrev_b32_e32 v0, 16, v35
	v_and_b32_e32 v1, 0xffff0000, v35
	v_pk_add_f32 v[0:1], v[10:11], v[0:1] neg_lo:[0,1] neg_hi:[0,1]
	v_pk_add_f32 v[26:27], v[26:27], v[0:1]
	v_pk_fma_f32 v[0:1], v[24:25], v[26:27], v[10:11] op_sel_hi:[0,1,1] neg_lo:[0,0,1] neg_hi:[0,0,1]
	v_cvt_pk_bf16_f32 v36, v0, v1
	v_lshlrev_b32_e32 v12, 16, v169
	v_and_b32_e32 v13, 0xffff0000, v169
	v_cndmask_b32_e32 v35, v161, v149, vcc
	v_lshlrev_b32_e32 v0, 16, v35
	v_and_b32_e32 v1, 0xffff0000, v35
	v_pk_add_f32 v[0:1], v[12:13], v[0:1] neg_lo:[0,1] neg_hi:[0,1]
	v_pk_add_f32 v[28:29], v[28:29], v[0:1]
	v_pk_fma_f32 v[0:1], v[24:25], v[28:29], v[12:13] op_sel_hi:[0,1,1] neg_lo:[0,0,1] neg_hi:[0,0,1]
	v_cvt_pk_bf16_f32 v37, v0, v1
	v_lshlrev_b32_e32 v14, 16, v170
	v_and_b32_e32 v15, 0xffff0000, v170
	v_cndmask_b32_e32 v35, v162, v150, vcc
	v_lshlrev_b32_e32 v0, 16, v35
	v_and_b32_e32 v1, 0xffff0000, v35
	v_pk_add_f32 v[0:1], v[14:15], v[0:1] neg_lo:[0,1] neg_hi:[0,1]
	v_pk_add_f32 v[30:31], v[30:31], v[0:1]
	v_pk_fma_f32 v[0:1], v[24:25], v[30:31], v[14:15] op_sel_hi:[0,1,1] neg_lo:[0,0,1] neg_hi:[0,0,1]
	v_cvt_pk_bf16_f32 v38, v0, v1
	v_lshlrev_b32_e32 v22, 16, v171
	v_and_b32_e32 v23, 0xffff0000, v171
	v_cndmask_b32_e32 v35, v163, v151, vcc
	v_lshlrev_b32_e32 v0, 16, v35
	v_and_b32_e32 v1, 0xffff0000, v35
	v_pk_add_f32 v[0:1], v[22:23], v[0:1] neg_lo:[0,1] neg_hi:[0,1]
	v_pk_add_f32 v[8:9], v[8:9], v[0:1]
	v_pk_fma_f32 v[0:1], v[24:25], v[8:9], v[22:23] op_sel_hi:[0,1,1] neg_lo:[0,0,1] neg_hi:[0,0,1]
	v_cvt_pk_bf16_f32 v39, v0, v1
	v_lshl_add_u64 v[6:7], v[6:7], 0, s[16:17]
	global_store_dwordx4 v[6:7], v[36:39], off offset:-4096 nt
	s_waitcnt vmcnt(31)
	v_lshlrev_b32_e32 v10, 16, v172
	v_and_b32_e32 v11, 0xffff0000, v172
	v_cndmask_b32_e32 v35, v164, v156, vcc
	v_lshlrev_b32_e32 v0, 16, v35
	v_and_b32_e32 v1, 0xffff0000, v35
	v_pk_add_f32 v[0:1], v[10:11], v[0:1] neg_lo:[0,1] neg_hi:[0,1]
	v_pk_add_f32 v[26:27], v[26:27], v[0:1]
	v_pk_fma_f32 v[0:1], v[24:25], v[26:27], v[10:11] op_sel_hi:[0,1,1] neg_lo:[0,0,1] neg_hi:[0,0,1]
	v_cvt_pk_bf16_f32 v36, v0, v1
	v_lshlrev_b32_e32 v12, 16, v173
	v_and_b32_e32 v13, 0xffff0000, v173
	v_cndmask_b32_e32 v35, v165, v157, vcc
	v_lshlrev_b32_e32 v0, 16, v35
	v_and_b32_e32 v1, 0xffff0000, v35
	v_pk_add_f32 v[0:1], v[12:13], v[0:1] neg_lo:[0,1] neg_hi:[0,1]
	v_pk_add_f32 v[28:29], v[28:29], v[0:1]
	v_pk_fma_f32 v[0:1], v[24:25], v[28:29], v[12:13] op_sel_hi:[0,1,1] neg_lo:[0,0,1] neg_hi:[0,0,1]
	v_cvt_pk_bf16_f32 v37, v0, v1
	v_lshlrev_b32_e32 v14, 16, v174
	v_and_b32_e32 v15, 0xffff0000, v174
	v_cndmask_b32_e32 v35, v166, v158, vcc
	v_lshlrev_b32_e32 v0, 16, v35
	v_and_b32_e32 v1, 0xffff0000, v35
	v_pk_add_f32 v[0:1], v[14:15], v[0:1] neg_lo:[0,1] neg_hi:[0,1]
	v_pk_add_f32 v[30:31], v[30:31], v[0:1]
	v_pk_fma_f32 v[0:1], v[24:25], v[30:31], v[14:15] op_sel_hi:[0,1,1] neg_lo:[0,0,1] neg_hi:[0,0,1]
	v_cvt_pk_bf16_f32 v38, v0, v1
	v_lshlrev_b32_e32 v22, 16, v175
	v_and_b32_e32 v23, 0xffff0000, v175
	v_cndmask_b32_e32 v35, v167, v159, vcc
	v_lshlrev_b32_e32 v0, 16, v35
	v_and_b32_e32 v1, 0xffff0000, v35
	v_pk_add_f32 v[0:1], v[22:23], v[0:1] neg_lo:[0,1] neg_hi:[0,1]
	v_pk_add_f32 v[8:9], v[8:9], v[0:1]
	v_pk_fma_f32 v[0:1], v[24:25], v[8:9], v[22:23] op_sel_hi:[0,1,1] neg_lo:[0,0,1] neg_hi:[0,0,1]
	v_cvt_pk_bf16_f32 v39, v0, v1
	global_store_dwordx4 v[6:7], v[36:39], off offset:-2048 nt
	s_waitcnt vmcnt(31)
	v_lshlrev_b32_e32 v10, 16, v176
	v_and_b32_e32 v11, 0xffff0000, v176
	v_cndmask_b32_e32 v35, v168, v160, vcc
	v_lshlrev_b32_e32 v0, 16, v35
	v_and_b32_e32 v1, 0xffff0000, v35
	v_pk_add_f32 v[0:1], v[10:11], v[0:1] neg_lo:[0,1] neg_hi:[0,1]
	v_pk_add_f32 v[26:27], v[26:27], v[0:1]
	v_pk_fma_f32 v[0:1], v[24:25], v[26:27], v[10:11] op_sel_hi:[0,1,1] neg_lo:[0,0,1] neg_hi:[0,0,1]
	v_cvt_pk_bf16_f32 v36, v0, v1
	v_lshlrev_b32_e32 v12, 16, v177
	v_and_b32_e32 v13, 0xffff0000, v177
	v_cndmask_b32_e32 v35, v169, v161, vcc
	v_lshlrev_b32_e32 v0, 16, v35
	v_and_b32_e32 v1, 0xffff0000, v35
	v_pk_add_f32 v[0:1], v[12:13], v[0:1] neg_lo:[0,1] neg_hi:[0,1]
	v_pk_add_f32 v[28:29], v[28:29], v[0:1]
	v_pk_fma_f32 v[0:1], v[24:25], v[28:29], v[12:13] op_sel_hi:[0,1,1] neg_lo:[0,0,1] neg_hi:[0,0,1]
	v_cvt_pk_bf16_f32 v37, v0, v1
	v_lshlrev_b32_e32 v14, 16, v178
	v_and_b32_e32 v15, 0xffff0000, v178
	v_cndmask_b32_e32 v35, v170, v162, vcc
	v_lshlrev_b32_e32 v0, 16, v35
	v_and_b32_e32 v1, 0xffff0000, v35
	v_pk_add_f32 v[0:1], v[14:15], v[0:1] neg_lo:[0,1] neg_hi:[0,1]
	v_pk_add_f32 v[30:31], v[30:31], v[0:1]
	v_pk_fma_f32 v[0:1], v[24:25], v[30:31], v[14:15] op_sel_hi:[0,1,1] neg_lo:[0,0,1] neg_hi:[0,0,1]
	v_cvt_pk_bf16_f32 v38, v0, v1
	v_lshlrev_b32_e32 v22, 16, v179
	v_and_b32_e32 v23, 0xffff0000, v179
	v_cndmask_b32_e32 v35, v171, v163, vcc
	v_lshlrev_b32_e32 v0, 16, v35
	v_and_b32_e32 v1, 0xffff0000, v35
	v_pk_add_f32 v[0:1], v[22:23], v[0:1] neg_lo:[0,1] neg_hi:[0,1]
	v_pk_add_f32 v[8:9], v[8:9], v[0:1]
	v_pk_fma_f32 v[0:1], v[24:25], v[8:9], v[22:23] op_sel_hi:[0,1,1] neg_lo:[0,0,1] neg_hi:[0,0,1]
	v_cvt_pk_bf16_f32 v39, v0, v1
	global_store_dwordx4 v[6:7], v[36:39], off nt
	s_waitcnt vmcnt(31)
; __device__ __forceinline__ unsigned cvtpk(float lo, float hi) { return pg8::cvt_pk_bf16(lo, hi); }
; __device__ __forceinline__ float bflo(unsigned u) { return __uint_as_float(u << 16); }
; __device__ __forceinline__ float bfhi(unsigned u) { return __uint_as_float(u & 0xffff0000u); }
; __device__ __forceinline__ void pool_pass(const bf16* __restrict__ U, bf16* __restrict__ Y, int gtid, int gthreads) {
;     ...
;         for (int t = t0; t < t0 + 32; ++t) {
;             const v4u v = *(const v4u*)(up + (size_t)t * 1024);
;             const int tb = t - w; v4u vb = {0u, 0u, 0u, 0u};
;             if (t > t0 && tb >= 0) vb = *(const v4u*)(up + (size_t)tb * 1024);
;             const float rc = 1.0f / (float)((t + 1 < w) ? (t + 1) : w);
;             v4u o;
; #pragma unroll
;             for (int j = 0; j < 4; ++j) { const float c0 = bflo(v[j]), c1 = bfhi(v[j]);
;                 sum[2 * j] += c0 - bflo(vb[j]); sum[2 * j + 1] += c1 - bfhi(vb[j]);
;                 o[j] = cvtpk(sum[2 * j] * rc - c0, sum[2 * j + 1] * rc - c1); }
;             __builtin_nontemporal_store(o, (v4u*)(yp + (size_t)t * 1024));
	v_lshlrev_b32_e32 v10, 16, v180
	v_and_b32_e32 v11, 0xffff0000, v180
	v_cndmask_b32_e32 v35, v172, v164, vcc
	v_lshlrev_b32_e32 v0, 16, v35
	v_and_b32_e32 v1, 0xffff0000, v35
	v_pk_add_f32 v[0:1], v[10:11], v[0:1] neg_lo:[0,1] neg_hi:[0,1]
	v_pk_add_f32 v[26:27], v[26:27], v[0:1]
	v_pk_fma_f32 v[0:1], v[24:25], v[26:27], v[10:11] op_sel_hi:[0,1,1] neg_lo:[0,0,1] neg_hi:[0,0,1]
	v_cvt_pk_bf16_f32 v36, v0, v1
	v_lshlrev_b32_e32 v12, 16, v181
	v_and_b32_e32 v13, 0xffff0000, v181
	v_cndmask_b32_e32 v35, v173, v165, vcc
	v_lshlrev_b32_e32 v0, 16, v35
	v_and_b32_e32 v1, 0xffff0000, v35
	v_pk_add_f32 v[0:1], v[12:13], v[0:1] neg_lo:[0,1] neg_hi:[0,1]
	v_pk_add_f32 v[28:29], v[28:29], v[0:1]
	v_pk_fma_f32 v[0:1], v[24:25], v[28:29], v[12:13] op_sel_hi:[0,1,1] neg_lo:[0,0,1] neg_hi:[0,0,1]
	v_cvt_pk_bf16_f32 v37, v0, v1
	v_lshlrev_b32_e32 v14, 16, v182
	v_and_b32_e32 v15, 0xffff0000, v182
	v_cndmask_b32_e32 v35, v174, v166, vcc
	v_lshlrev_b32_e32 v0, 16, v35
	v_and_b32_e32 v1, 0xffff0000, v35
	v_pk_add_f32 v[0:1], v[14:15], v[0:1] neg_lo:[0,1] neg_hi:[0,1]
	v_pk_add_f32 v[30:31], v[30:31], v[0:1]
	v_pk_fma_f32 v[0:1], v[24:25], v[30:31], v[14:15] op_sel_hi:[0,1,1] neg_lo:[0,0,1] neg_hi:[0,0,1]
	v_cvt_pk_bf16_f32 v38, v0, v1
	v_lshlrev_b32_e32 v22, 16, v183
	v_and_b32_e32 v23, 0xffff0000, v183
	v_cndmask_b32_e32 v35, v175, v167, vcc
	v_lshlrev_b32_e32 v0, 16, v35
	v_and_b32_e32 v1, 0xffff0000, v35
	v_pk_add_f32 v[0:1], v[22:23], v[0:1] neg_lo:[0,1] neg_hi:[0,1]
	v_pk_add_f32 v[8:9], v[8:9], v[0:1]
	v_pk_fma_f32 v[0:1], v[24:25], v[8:9], v[22:23] op_sel_hi:[0,1,1] neg_lo:[0,0,1] neg_hi:[0,0,1]
	v_cvt_pk_bf16_f32 v39, v0, v1
	global_store_dwordx4 v[6:7], v[36:39], off offset:2048 nt
	s_waitcnt vmcnt(31)
	v_lshlrev_b32_e32 v10, 16, v184
	v_and_b32_e32 v11, 0xffff0000, v184
	v_cndmask_b32_e32 v35, v176, v168, vcc
	v_lshlrev_b32_e32 v0, 16, v35
	v_and_b32_e32 v1, 0xffff0000, v35
	v_pk_add_f32 v[0:1], v[10:11], v[0:1] neg_lo:[0,1] neg_hi:[0,1]
	v_pk_add_f32 v[26:27], v[26:27], v[0:1]
	v_pk_fma_f32 v[0:1], v[24:25], v[26:27], v[10:11] op_sel_hi:[0,1,1] neg_lo:[0,0,1] neg_hi:[0,0,1]
	v_cvt_pk_bf16_f32 v36, v0, v1
	v_lshlrev_b32_e32 v12, 16, v185
	v_and_b32_e32 v13, 0xffff0000, v185
	v_cndmask_b32_e32 v35, v177, v169, vcc
	v_lshlrev_b32_e32 v0, 16, v35
	v_and_b32_e32 v1, 0xffff0000, v35
	v_pk_add_f32 v[0:1], v[12:13], v[0:1] neg_lo:[0,1] neg_hi:[0,1]
	v_pk_add_f32 v[28:29], v[28:29], v[0:1]
	v_pk_fma_f32 v[0:1], v[24:25], v[28:29], v[12:13] op_sel_hi:[0,1,1] neg_lo:[0,0,1] neg_hi:[0,0,1]
	v_cvt_pk_bf16_f32 v37, v0, v1
	v_lshlrev_b32_e32 v14, 16, v186
	v_and_b32_e32 v15, 0xffff0000, v186
	v_cndmask_b32_e32 v35, v178, v170, vcc
	v_lshlrev_b32_e32 v0, 16, v35
	v_and_b32_e32 v1, 0xffff0000, v35
	v_pk_add_f32 v[0:1], v[14:15], v[0:1] neg_lo:[0,1] neg_hi:[0,1]
	v_pk_add_f32 v[30:31], v[30:31], v[0:1]
	v_pk_fma_f32 v[0:1], v[24:25], v[30:31], v[14:15] op_sel_hi:[0,1,1] neg_lo:[0,0,1] neg_hi:[0,0,1]
	v_cvt_pk_bf16_f32 v38, v0, v1
	v_lshlrev_b32_e32 v22, 16, v187
	v_and_b32_e32 v23, 0xffff0000, v187
	v_cndmask_b32_e32 v35, v179, v171, vcc
	v_lshlrev_b32_e32 v0, 16, v35
	v_and_b32_e32 v1, 0xffff0000, v35
	v_pk_add_f32 v[0:1], v[22:23], v[0:1] neg_lo:[0,1] neg_hi:[0,1]
	v_pk_add_f32 v[8:9], v[8:9], v[0:1]
	v_pk_fma_f32 v[0:1], v[24:25], v[8:9], v[22:23] op_sel_hi:[0,1,1] neg_lo:[0,0,1] neg_hi:[0,0,1]
	v_cvt_pk_bf16_f32 v39, v0, v1
	v_lshl_add_u64 v[6:7], v[6:7], 0, s[16:17]
	global_store_dwordx4 v[6:7], v[36:39], off offset:-4096 nt
	s_waitcnt vmcnt(31)
	v_lshlrev_b32_e32 v10, 16, v188
	v_and_b32_e32 v11, 0xffff0000, v188
	v_cndmask_b32_e32 v35, v180, v172, vcc
	v_lshlrev_b32_e32 v0, 16, v35
	v_and_b32_e32 v1, 0xffff0000, v35
	v_pk_add_f32 v[0:1], v[10:11], v[0:1] neg_lo:[0,1] neg_hi:[0,1]
	v_pk_add_f32 v[26:27], v[26:27], v[0:1]
	v_pk_fma_f32 v[0:1], v[24:25], v[26:27], v[10:11] op_sel_hi:[0,1,1] neg_lo:[0,0,1] neg_hi:[0,0,1]
	v_cvt_pk_bf16_f32 v36, v0, v1
	v_lshlrev_b32_e32 v12, 16, v189
	v_and_b32_e32 v13, 0xffff0000, v189
	v_cndmask_b32_e32 v35, v181, v173, vcc
	v_lshlrev_b32_e32 v0, 16, v35
	v_and_b32_e32 v1, 0xffff0000, v35
	v_pk_add_f32 v[0:1], v[12:13], v[0:1] neg_lo:[0,1] neg_hi:[0,1]
	v_pk_add_f32 v[28:29], v[28:29], v[0:1]
	v_pk_fma_f32 v[0:1], v[24:25], v[28:29], v[12:13] op_sel_hi:[0,1,1] neg_lo:[0,0,1] neg_hi:[0,0,1]
	v_cvt_pk_bf16_f32 v37, v0, v1
	v_lshlrev_b32_e32 v14, 16, v190
	v_and_b32_e32 v15, 0xffff0000, v190
	v_cndmask_b32_e32 v35, v182, v174, vcc
	v_lshlrev_b32_e32 v0, 16, v35
	v_and_b32_e32 v1, 0xffff0000, v35
	v_pk_add_f32 v[0:1], v[14:15], v[0:1] neg_lo:[0,1] neg_hi:[0,1]
	v_pk_add_f32 v[30:31], v[30:31], v[0:1]
	v_pk_fma_f32 v[0:1], v[24:25], v[30:31], v[14:15] op_sel_hi:[0,1,1] neg_lo:[0,0,1] neg_hi:[0,0,1]
	v_cvt_pk_bf16_f32 v38, v0, v1
	v_lshlrev_b32_e32 v22, 16, v191
	v_and_b32_e32 v23, 0xffff0000, v191
	v_cndmask_b32_e32 v35, v183, v175, vcc
	v_lshlrev_b32_e32 v0, 16, v35
	v_and_b32_e32 v1, 0xffff0000, v35
	v_pk_add_f32 v[0:1], v[22:23], v[0:1] neg_lo:[0,1] neg_hi:[0,1]
	v_pk_add_f32 v[8:9], v[8:9], v[0:1]
	v_pk_fma_f32 v[0:1], v[24:25], v[8:9], v[22:23] op_sel_hi:[0,1,1] neg_lo:[0,0,1] neg_hi:[0,0,1]
	v_cvt_pk_bf16_f32 v39, v0, v1
	global_store_dwordx4 v[6:7], v[36:39], off offset:-2048 nt
	s_waitcnt vmcnt(31)
; __device__ __forceinline__ unsigned cvtpk(float lo, float hi) { return pg8::cvt_pk_bf16(lo, hi); }
; __device__ __forceinline__ float bflo(unsigned u) { return __uint_as_float(u << 16); }
; __device__ __forceinline__ float bfhi(unsigned u) { return __uint_as_float(u & 0xffff0000u); }
; __device__ __forceinline__ void pool_pass(const bf16* __restrict__ U, bf16* __restrict__ Y, int gtid, int gthreads) {
;     ...
;         for (int t = t0; t < t0 + 32; ++t) {
;             const v4u v = *(const v4u*)(up + (size_t)t * 1024);
;             const int tb = t - w; v4u vb = {0u, 0u, 0u, 0u};
;             if (t > t0 && tb >= 0) vb = *(const v4u*)(up + (size_t)tb * 1024);
;             const float rc = 1.0f / (float)((t + 1 < w) ? (t + 1) : w);
;             v4u o;
; #pragma unroll
;             for (int j = 0; j < 4; ++j) { const float c0 = bflo(v[j]), c1 = bfhi(v[j]);
;                 sum[2 * j] += c0 - bflo(vb[j]); sum[2 * j + 1] += c1 - bfhi(vb[j]);
;                 o[j] = cvtpk(sum[2 * j] * rc - c0, sum[2 * j + 1] * rc - c1); }
;             __builtin_nontemporal_store(o, (v4u*)(yp + (size_t)t * 1024));
	v_lshlrev_b32_e32 v10, 16, v192
	v_and_b32_e32 v11, 0xffff0000, v192
	v_cndmask_b32_e32 v35, v184, v176, vcc
	v_lshlrev_b32_e32 v0, 16, v35
	v_and_b32_e32 v1, 0xffff0000, v35
	v_pk_add_f32 v[0:1], v[10:11], v[0:1] neg_lo:[0,1] neg_hi:[0,1]
	v_pk_add_f32 v[26:27], v[26:27], v[0:1]
	v_pk_fma_f32 v[0:1], v[24:25], v[26:27], v[10:11] op_sel_hi:[0,1,1] neg_lo:[0,0,1] neg_hi:[0,0,1]
	v_cvt_pk_bf16_f32 v36, v0, v1
	v_lshlrev_b32_e32 v12, 16, v193
	v_and_b32_e32 v13, 0xffff0000, v193
	v_cndmask_b32_e32 v35, v185, v177, vcc
	v_lshlrev_b32_e32 v0, 16, v35
	v_and_b32_e32 v1, 0xffff0000, v35
	v_pk_add_f32 v[0:1], v[12:13], v[0:1] neg_lo:[0,1] neg_hi:[0,1]
	v_pk_add_f32 v[28:29], v[28:29], v[0:1]
	v_pk_fma_f32 v[0:1], v[24:25], v[28:29], v[12:13] op_sel_hi:[0,1,1] neg_lo:[0,0,1] neg_hi:[0,0,1]
	v_cvt_pk_bf16_f32 v37, v0, v1
	v_lshlrev_b32_e32 v14, 16, v194
	v_and_b32_e32 v15, 0xffff0000, v194
	v_cndmask_b32_e32 v35, v186, v178, vcc
	v_lshlrev_b32_e32 v0, 16, v35
	v_and_b32_e32 v1, 0xffff0000, v35
	v_pk_add_f32 v[0:1], v[14:15], v[0:1] neg_lo:[0,1] neg_hi:[0,1]
	v_pk_add_f32 v[30:31], v[30:31], v[0:1]
	v_pk_fma_f32 v[0:1], v[24:25], v[30:31], v[14:15] op_sel_hi:[0,1,1] neg_lo:[0,0,1] neg_hi:[0,0,1]
	v_cvt_pk_bf16_f32 v38, v0, v1
	v_lshlrev_b32_e32 v22, 16, v195
	v_and_b32_e32 v23, 0xffff0000, v195
	v_cndmask_b32_e32 v35, v187, v179, vcc
	v_lshlrev_b32_e32 v0, 16, v35
	v_and_b32_e32 v1, 0xffff0000, v35
	v_pk_add_f32 v[0:1], v[22:23], v[0:1] neg_lo:[0,1] neg_hi:[0,1]
	v_pk_add_f32 v[8:9], v[8:9], v[0:1]
	v_pk_fma_f32 v[0:1], v[24:25], v[8:9], v[22:23] op_sel_hi:[0,1,1] neg_lo:[0,0,1] neg_hi:[0,0,1]
	v_cvt_pk_bf16_f32 v39, v0, v1
	global_store_dwordx4 v[6:7], v[36:39], off nt
	s_waitcnt vmcnt(31)
	v_lshlrev_b32_e32 v10, 16, v196
	v_and_b32_e32 v11, 0xffff0000, v196
	v_cndmask_b32_e32 v35, v188, v180, vcc
	v_lshlrev_b32_e32 v0, 16, v35
	v_and_b32_e32 v1, 0xffff0000, v35
	v_pk_add_f32 v[0:1], v[10:11], v[0:1] neg_lo:[0,1] neg_hi:[0,1]
	v_pk_add_f32 v[26:27], v[26:27], v[0:1]
	v_pk_fma_f32 v[0:1], v[24:25], v[26:27], v[10:11] op_sel_hi:[0,1,1] neg_lo:[0,0,1] neg_hi:[0,0,1]
	v_cvt_pk_bf16_f32 v36, v0, v1
	v_lshlrev_b32_e32 v12, 16, v197
	v_and_b32_e32 v13, 0xffff0000, v197
	v_cndmask_b32_e32 v35, v189, v181, vcc
	v_lshlrev_b32_e32 v0, 16, v35
	v_and_b32_e32 v1, 0xffff0000, v35
	v_pk_add_f32 v[0:1], v[12:13], v[0:1] neg_lo:[0,1] neg_hi:[0,1]
	v_pk_add_f32 v[28:29], v[28:29], v[0:1]
	v_pk_fma_f32 v[0:1], v[24:25], v[28:29], v[12:13] op_sel_hi:[0,1,1] neg_lo:[0,0,1] neg_hi:[0,0,1]
	v_cvt_pk_bf16_f32 v37, v0, v1
	v_lshlrev_b32_e32 v14, 16, v198
	v_and_b32_e32 v15, 0xffff0000, v198
	v_cndmask_b32_e32 v35, v190, v182, vcc
	v_lshlrev_b32_e32 v0, 16, v35
	v_and_b32_e32 v1, 0xffff0000, v35
	v_pk_add_f32 v[0:1], v[14:15], v[0:1] neg_lo:[0,1] neg_hi:[0,1]
	v_pk_add_f32 v[30:31], v[30:31], v[0:1]
	v_pk_fma_f32 v[0:1], v[24:25], v[30:31], v[14:15] op_sel_hi:[0,1,1] neg_lo:[0,0,1] neg_hi:[0,0,1]
	v_cvt_pk_bf16_f32 v38, v0, v1
	v_lshlrev_b32_e32 v22, 16, v199
	v_and_b32_e32 v23, 0xffff0000, v199
	v_cndmask_b32_e32 v35, v191, v183, vcc
	v_lshlrev_b32_e32 v0, 16, v35
	v_and_b32_e32 v1, 0xffff0000, v35
	v_pk_add_f32 v[0:1], v[22:23], v[0:1] neg_lo:[0,1] neg_hi:[0,1]
	v_pk_add_f32 v[8:9], v[8:9], v[0:1]
	v_pk_fma_f32 v[0:1], v[24:25], v[8:9], v[22:23] op_sel_hi:[0,1,1] neg_lo:[0,0,1] neg_hi:[0,0,1]
	v_cvt_pk_bf16_f32 v39, v0, v1
	global_store_dwordx4 v[6:7], v[36:39], off offset:2048 nt
	s_waitcnt vmcnt(31)
	v_lshlrev_b32_e32 v10, 16, v200
	v_and_b32_e32 v11, 0xffff0000, v200
	v_cndmask_b32_e32 v35, v192, v184, vcc
	v_lshlrev_b32_e32 v0, 16, v35
	v_and_b32_e32 v1, 0xffff0000, v35
	v_pk_add_f32 v[0:1], v[10:11], v[0:1] neg_lo:[0,1] neg_hi:[0,1]
	v_pk_add_f32 v[26:27], v[26:27], v[0:1]
	v_pk_fma_f32 v[0:1], v[24:25], v[26:27], v[10:11] op_sel_hi:[0,1,1] neg_lo:[0,0,1] neg_hi:[0,0,1]
	v_cvt_pk_bf16_f32 v36, v0, v1
	v_lshlrev_b32_e32 v12, 16, v201
	v_and_b32_e32 v13, 0xffff0000, v201
	v_cndmask_b32_e32 v35, v193, v185, vcc
	v_lshlrev_b32_e32 v0, 16, v35
	v_and_b32_e32 v1, 0xffff0000, v35
	v_pk_add_f32 v[0:1], v[12:13], v[0:1] neg_lo:[0,1] neg_hi:[0,1]
	v_pk_add_f32 v[28:29], v[28:29], v[0:1]
	v_pk_fma_f32 v[0:1], v[24:25], v[28:29], v[12:13] op_sel_hi:[0,1,1] neg_lo:[0,0,1] neg_hi:[0,0,1]
	v_cvt_pk_bf16_f32 v37, v0, v1
	v_lshlrev_b32_e32 v14, 16, v202
	v_and_b32_e32 v15, 0xffff0000, v202
	v_cndmask_b32_e32 v35, v194, v186, vcc
	v_lshlrev_b32_e32 v0, 16, v35
	v_and_b32_e32 v1, 0xffff0000, v35
	v_pk_add_f32 v[0:1], v[14:15], v[0:1] neg_lo:[0,1] neg_hi:[0,1]
	v_pk_add_f32 v[30:31], v[30:31], v[0:1]
	v_pk_fma_f32 v[0:1], v[24:25], v[30:31], v[14:15] op_sel_hi:[0,1,1] neg_lo:[0,0,1] neg_hi:[0,0,1]
	v_cvt_pk_bf16_f32 v38, v0, v1
	v_lshlrev_b32_e32 v22, 16, v203
	v_and_b32_e32 v23, 0xffff0000, v203
	v_cndmask_b32_e32 v35, v195, v187, vcc
	v_lshlrev_b32_e32 v0, 16, v35
	v_and_b32_e32 v1, 0xffff0000, v35
	v_pk_add_f32 v[0:1], v[22:23], v[0:1] neg_lo:[0,1] neg_hi:[0,1]
	v_pk_add_f32 v[8:9], v[8:9], v[0:1]
	v_pk_fma_f32 v[0:1], v[24:25], v[8:9], v[22:23] op_sel_hi:[0,1,1] neg_lo:[0,0,1] neg_hi:[0,0,1]
	v_cvt_pk_bf16_f32 v39, v0, v1
	v_lshl_add_u64 v[6:7], v[6:7], 0, s[16:17]
	global_store_dwordx4 v[6:7], v[36:39], off offset:-4096 nt
	s_waitcnt vmcnt(31)
; __device__ __forceinline__ unsigned cvtpk(float lo, float hi) { return pg8::cvt_pk_bf16(lo, hi); }
; __device__ __forceinline__ float bflo(unsigned u) { return __uint_as_float(u << 16); }
; __device__ __forceinline__ float bfhi(unsigned u) { return __uint_as_float(u & 0xffff0000u); }
; __device__ __forceinline__ void pool_pass(const bf16* __restrict__ U, bf16* __restrict__ Y, int gtid, int gthreads) {
;     ...
;         for (int t = t0; t < t0 + 32; ++t) {
;             const v4u v = *(const v4u*)(up + (size_t)t * 1024);
;             const int tb = t - w; v4u vb = {0u, 0u, 0u, 0u};
;             if (t > t0 && tb >= 0) vb = *(const v4u*)(up + (size_t)tb * 1024);
;             const float rc = 1.0f / (float)((t + 1 < w) ? (t + 1) : w);
;             v4u o;
; #pragma unroll
;             for (int j = 0; j < 4; ++j) { const float c0 = bflo(v[j]), c1 = bfhi(v[j]);
;                 sum[2 * j] += c0 - bflo(vb[j]); sum[2 * j + 1] += c1 - bfhi(vb[j]);
;                 o[j] = cvtpk(sum[2 * j] * rc - c0, sum[2 * j + 1] * rc - c1); }
;             __builtin_nontemporal_store(o, (v4u*)(yp + (size_t)t * 1024));
	v_lshlrev_b32_e32 v10, 16, v204
	v_and_b32_e32 v11, 0xffff0000, v204
	v_cndmask_b32_e32 v35, v196, v188, vcc
	v_lshlrev_b32_e32 v0, 16, v35
	v_and_b32_e32 v1, 0xffff0000, v35
	v_pk_add_f32 v[0:1], v[10:11], v[0:1] neg_lo:[0,1] neg_hi:[0,1]
	v_pk_add_f32 v[26:27], v[26:27], v[0:1]
	v_pk_fma_f32 v[0:1], v[24:25], v[26:27], v[10:11] op_sel_hi:[0,1,1] neg_lo:[0,0,1] neg_hi:[0,0,1]
	v_cvt_pk_bf16_f32 v36, v0, v1
	v_lshlrev_b32_e32 v12, 16, v205
	v_and_b32_e32 v13, 0xffff0000, v205
	v_cndmask_b32_e32 v35, v197, v189, vcc
	v_lshlrev_b32_e32 v0, 16, v35
	v_and_b32_e32 v1, 0xffff0000, v35
	v_pk_add_f32 v[0:1], v[12:13], v[0:1] neg_lo:[0,1] neg_hi:[0,1]
	v_pk_add_f32 v[28:29], v[28:29], v[0:1]
	v_pk_fma_f32 v[0:1], v[24:25], v[28:29], v[12:13] op_sel_hi:[0,1,1] neg_lo:[0,0,1] neg_hi:[0,0,1]
	v_cvt_pk_bf16_f32 v37, v0, v1
	v_lshlrev_b32_e32 v14, 16, v206
	v_and_b32_e32 v15, 0xffff0000, v206
	v_cndmask_b32_e32 v35, v198, v190, vcc
	v_lshlrev_b32_e32 v0, 16, v35
	v_and_b32_e32 v1, 0xffff0000, v35
	v_pk_add_f32 v[0:1], v[14:15], v[0:1] neg_lo:[0,1] neg_hi:[0,1]
	v_pk_add_f32 v[30:31], v[30:31], v[0:1]
	v_pk_fma_f32 v[0:1], v[24:25], v[30:31], v[14:15] op_sel_hi:[0,1,1] neg_lo:[0,0,1] neg_hi:[0,0,1]
	v_cvt_pk_bf16_f32 v38, v0, v1
	v_lshlrev_b32_e32 v22, 16, v207
	v_and_b32_e32 v23, 0xffff0000, v207
	v_cndmask_b32_e32 v35, v199, v191, vcc
	v_lshlrev_b32_e32 v0, 16, v35
	v_and_b32_e32 v1, 0xffff0000, v35
	v_pk_add_f32 v[0:1], v[22:23], v[0:1] neg_lo:[0,1] neg_hi:[0,1]
	v_pk_add_f32 v[8:9], v[8:9], v[0:1]
	v_pk_fma_f32 v[0:1], v[24:25], v[8:9], v[22:23] op_sel_hi:[0,1,1] neg_lo:[0,0,1] neg_hi:[0,0,1]
	v_cvt_pk_bf16_f32 v39, v0, v1
	global_store_dwordx4 v[6:7], v[36:39], off offset:-2048 nt
	s_waitcnt vmcnt(31)
	v_lshlrev_b32_e32 v10, 16, v208
	v_and_b32_e32 v11, 0xffff0000, v208
	v_cndmask_b32_e32 v35, v200, v192, vcc
	v_lshlrev_b32_e32 v0, 16, v35
	v_and_b32_e32 v1, 0xffff0000, v35
	v_pk_add_f32 v[0:1], v[10:11], v[0:1] neg_lo:[0,1] neg_hi:[0,1]
	v_pk_add_f32 v[26:27], v[26:27], v[0:1]
	v_pk_fma_f32 v[0:1], v[24:25], v[26:27], v[10:11] op_sel_hi:[0,1,1] neg_lo:[0,0,1] neg_hi:[0,0,1]
	v_cvt_pk_bf16_f32 v36, v0, v1
	v_lshlrev_b32_e32 v12, 16, v209
	v_and_b32_e32 v13, 0xffff0000, v209
	v_cndmask_b32_e32 v35, v201, v193, vcc
	v_lshlrev_b32_e32 v0, 16, v35
	v_and_b32_e32 v1, 0xffff0000, v35
	v_pk_add_f32 v[0:1], v[12:13], v[0:1] neg_lo:[0,1] neg_hi:[0,1]
	v_pk_add_f32 v[28:29], v[28:29], v[0:1]
	v_pk_fma_f32 v[0:1], v[24:25], v[28:29], v[12:13] op_sel_hi:[0,1,1] neg_lo:[0,0,1] neg_hi:[0,0,1]
	v_cvt_pk_bf16_f32 v37, v0, v1
	v_lshlrev_b32_e32 v14, 16, v210
	v_and_b32_e32 v15, 0xffff0000, v210
	v_cndmask_b32_e32 v35, v202, v194, vcc
	v_lshlrev_b32_e32 v0, 16, v35
	v_and_b32_e32 v1, 0xffff0000, v35
	v_pk_add_f32 v[0:1], v[14:15], v[0:1] neg_lo:[0,1] neg_hi:[0,1]
	v_pk_add_f32 v[30:31], v[30:31], v[0:1]
	v_pk_fma_f32 v[0:1], v[24:25], v[30:31], v[14:15] op_sel_hi:[0,1,1] neg_lo:[0,0,1] neg_hi:[0,0,1]
	v_cvt_pk_bf16_f32 v38, v0, v1
	v_lshlrev_b32_e32 v22, 16, v211
	v_and_b32_e32 v23, 0xffff0000, v211
	v_cndmask_b32_e32 v35, v203, v195, vcc
	v_lshlrev_b32_e32 v0, 16, v35
	v_and_b32_e32 v1, 0xffff0000, v35
	v_pk_add_f32 v[0:1], v[22:23], v[0:1] neg_lo:[0,1] neg_hi:[0,1]
	v_pk_add_f32 v[8:9], v[8:9], v[0:1]
	v_pk_fma_f32 v[0:1], v[24:25], v[8:9], v[22:23] op_sel_hi:[0,1,1] neg_lo:[0,0,1] neg_hi:[0,0,1]
	v_cvt_pk_bf16_f32 v39, v0, v1
	global_store_dwordx4 v[6:7], v[36:39], off nt
	s_waitcnt vmcnt(31)
	v_lshlrev_b32_e32 v10, 16, v212
	v_and_b32_e32 v11, 0xffff0000, v212
	v_cndmask_b32_e32 v35, v204, v196, vcc
	v_lshlrev_b32_e32 v0, 16, v35
	v_and_b32_e32 v1, 0xffff0000, v35
	v_pk_add_f32 v[0:1], v[10:11], v[0:1] neg_lo:[0,1] neg_hi:[0,1]
	v_pk_add_f32 v[26:27], v[26:27], v[0:1]
	v_pk_fma_f32 v[0:1], v[24:25], v[26:27], v[10:11] op_sel_hi:[0,1,1] neg_lo:[0,0,1] neg_hi:[0,0,1]
	v_cvt_pk_bf16_f32 v36, v0, v1
	v_lshlrev_b32_e32 v12, 16, v213
	v_and_b32_e32 v13, 0xffff0000, v213
	v_cndmask_b32_e32 v35, v205, v197, vcc
	v_lshlrev_b32_e32 v0, 16, v35
	v_and_b32_e32 v1, 0xffff0000, v35
	v_pk_add_f32 v[0:1], v[12:13], v[0:1] neg_lo:[0,1] neg_hi:[0,1]
	v_pk_add_f32 v[28:29], v[28:29], v[0:1]
	v_pk_fma_f32 v[0:1], v[24:25], v[28:29], v[12:13] op_sel_hi:[0,1,1] neg_lo:[0,0,1] neg_hi:[0,0,1]
	v_cvt_pk_bf16_f32 v37, v0, v1
	v_lshlrev_b32_e32 v14, 16, v214
	v_and_b32_e32 v15, 0xffff0000, v214
	v_cndmask_b32_e32 v35, v206, v198, vcc
	v_lshlrev_b32_e32 v0, 16, v35
	v_and_b32_e32 v1, 0xffff0000, v35
	v_pk_add_f32 v[0:1], v[14:15], v[0:1] neg_lo:[0,1] neg_hi:[0,1]
	v_pk_add_f32 v[30:31], v[30:31], v[0:1]
	v_pk_fma_f32 v[0:1], v[24:25], v[30:31], v[14:15] op_sel_hi:[0,1,1] neg_lo:[0,0,1] neg_hi:[0,0,1]
	v_cvt_pk_bf16_f32 v38, v0, v1
	v_lshlrev_b32_e32 v22, 16, v215
	v_and_b32_e32 v23, 0xffff0000, v215
	v_cndmask_b32_e32 v35, v207, v199, vcc
	v_lshlrev_b32_e32 v0, 16, v35
	v_and_b32_e32 v1, 0xffff0000, v35
	v_pk_add_f32 v[0:1], v[22:23], v[0:1] neg_lo:[0,1] neg_hi:[0,1]
	v_pk_add_f32 v[8:9], v[8:9], v[0:1]
	v_pk_fma_f32 v[0:1], v[24:25], v[8:9], v[22:23] op_sel_hi:[0,1,1] neg_lo:[0,0,1] neg_hi:[0,0,1]
	v_cvt_pk_bf16_f32 v39, v0, v1
	global_store_dwordx4 v[6:7], v[36:39], off offset:2048 nt
	s_waitcnt vmcnt(31)
; __device__ __forceinline__ unsigned cvtpk(float lo, float hi) { return pg8::cvt_pk_bf16(lo, hi); }
; __device__ __forceinline__ float bflo(unsigned u) { return __uint_as_float(u << 16); }
; __device__ __forceinline__ float bfhi(unsigned u) { return __uint_as_float(u & 0xffff0000u); }
; __device__ __forceinline__ void pool_pass(const bf16* __restrict__ U, bf16* __restrict__ Y, int gtid, int gthreads) {
;     for (int task = gtid; task < BATCH * 128 * 128; task += gthreads) {
;     ...
;         for (int t = t0; t < t0 + 32; ++t) {
;             const v4u v = *(const v4u*)(up + (size_t)t * 1024);
;             const int tb = t - w; v4u vb = {0u, 0u, 0u, 0u};
;             if (t > t0 && tb >= 0) vb = *(const v4u*)(up + (size_t)tb * 1024);
;             const float rc = 1.0f / (float)((t + 1 < w) ? (t + 1) : w);
;             v4u o;
; #pragma unroll
;             for (int j = 0; j < 4; ++j) { const float c0 = bflo(v[j]), c1 = bfhi(v[j]);
;                 sum[2 * j] += c0 - bflo(vb[j]); sum[2 * j + 1] += c1 - bfhi(vb[j]);
;                 o[j] = cvtpk(sum[2 * j] * rc - c0, sum[2 * j + 1] * rc - c1); }
;             __builtin_nontemporal_store(o, (v4u*)(yp + (size_t)t * 1024));
	v_lshlrev_b32_e32 v10, 16, v216
	v_and_b32_e32 v11, 0xffff0000, v216
	v_cndmask_b32_e32 v35, v208, v200, vcc
	v_lshlrev_b32_e32 v0, 16, v35
	v_and_b32_e32 v1, 0xffff0000, v35
	v_pk_add_f32 v[0:1], v[10:11], v[0:1] neg_lo:[0,1] neg_hi:[0,1]
	v_pk_add_f32 v[26:27], v[26:27], v[0:1]
	v_pk_fma_f32 v[0:1], v[24:25], v[26:27], v[10:11] op_sel_hi:[0,1,1] neg_lo:[0,0,1] neg_hi:[0,0,1]
	v_cvt_pk_bf16_f32 v36, v0, v1
	v_lshlrev_b32_e32 v12, 16, v217
	v_and_b32_e32 v13, 0xffff0000, v217
	v_cndmask_b32_e32 v35, v209, v201, vcc
	v_lshlrev_b32_e32 v0, 16, v35
	v_and_b32_e32 v1, 0xffff0000, v35
	v_pk_add_f32 v[0:1], v[12:13], v[0:1] neg_lo:[0,1] neg_hi:[0,1]
	v_pk_add_f32 v[28:29], v[28:29], v[0:1]
	v_pk_fma_f32 v[0:1], v[24:25], v[28:29], v[12:13] op_sel_hi:[0,1,1] neg_lo:[0,0,1] neg_hi:[0,0,1]
	v_cvt_pk_bf16_f32 v37, v0, v1
	v_lshlrev_b32_e32 v14, 16, v218
	v_and_b32_e32 v15, 0xffff0000, v218
	v_cndmask_b32_e32 v35, v210, v202, vcc
	v_lshlrev_b32_e32 v0, 16, v35
	v_and_b32_e32 v1, 0xffff0000, v35
	v_pk_add_f32 v[0:1], v[14:15], v[0:1] neg_lo:[0,1] neg_hi:[0,1]
	v_pk_add_f32 v[30:31], v[30:31], v[0:1]
	v_pk_fma_f32 v[0:1], v[24:25], v[30:31], v[14:15] op_sel_hi:[0,1,1] neg_lo:[0,0,1] neg_hi:[0,0,1]
	v_cvt_pk_bf16_f32 v38, v0, v1
	v_lshlrev_b32_e32 v22, 16, v219
	v_and_b32_e32 v23, 0xffff0000, v219
	v_cndmask_b32_e32 v35, v211, v203, vcc
	v_lshlrev_b32_e32 v0, 16, v35
	v_and_b32_e32 v1, 0xffff0000, v35
	v_pk_add_f32 v[0:1], v[22:23], v[0:1] neg_lo:[0,1] neg_hi:[0,1]
	v_pk_add_f32 v[8:9], v[8:9], v[0:1]
	v_pk_fma_f32 v[0:1], v[24:25], v[8:9], v[22:23] op_sel_hi:[0,1,1] neg_lo:[0,0,1] neg_hi:[0,0,1]
	v_cvt_pk_bf16_f32 v39, v0, v1
	v_lshl_add_u64 v[6:7], v[6:7], 0, s[16:17]
	global_store_dwordx4 v[6:7], v[36:39], off offset:-4096 nt
	s_waitcnt vmcnt(31)
	v_lshlrev_b32_e32 v10, 16, v220
	v_and_b32_e32 v11, 0xffff0000, v220
	v_cndmask_b32_e32 v35, v212, v204, vcc
	v_lshlrev_b32_e32 v0, 16, v35
	v_and_b32_e32 v1, 0xffff0000, v35
	v_pk_add_f32 v[0:1], v[10:11], v[0:1] neg_lo:[0,1] neg_hi:[0,1]
	v_pk_add_f32 v[26:27], v[26:27], v[0:1]
	v_pk_fma_f32 v[0:1], v[24:25], v[26:27], v[10:11] op_sel_hi:[0,1,1] neg_lo:[0,0,1] neg_hi:[0,0,1]
	v_cvt_pk_bf16_f32 v36, v0, v1
	v_lshlrev_b32_e32 v12, 16, v221
	v_and_b32_e32 v13, 0xffff0000, v221
	v_cndmask_b32_e32 v35, v213, v205, vcc
	v_lshlrev_b32_e32 v0, 16, v35
	v_and_b32_e32 v1, 0xffff0000, v35
	v_pk_add_f32 v[0:1], v[12:13], v[0:1] neg_lo:[0,1] neg_hi:[0,1]
	v_pk_add_f32 v[28:29], v[28:29], v[0:1]
	v_pk_fma_f32 v[0:1], v[24:25], v[28:29], v[12:13] op_sel_hi:[0,1,1] neg_lo:[0,0,1] neg_hi:[0,0,1]
	v_cvt_pk_bf16_f32 v37, v0, v1
	v_lshlrev_b32_e32 v14, 16, v222
	v_and_b32_e32 v15, 0xffff0000, v222
	v_cndmask_b32_e32 v35, v214, v206, vcc
	v_lshlrev_b32_e32 v0, 16, v35
	v_and_b32_e32 v1, 0xffff0000, v35
	v_pk_add_f32 v[0:1], v[14:15], v[0:1] neg_lo:[0,1] neg_hi:[0,1]
	v_pk_add_f32 v[30:31], v[30:31], v[0:1]
	v_pk_fma_f32 v[0:1], v[24:25], v[30:31], v[14:15] op_sel_hi:[0,1,1] neg_lo:[0,0,1] neg_hi:[0,0,1]
	v_cvt_pk_bf16_f32 v38, v0, v1
	v_lshlrev_b32_e32 v22, 16, v223
	v_and_b32_e32 v23, 0xffff0000, v223
	v_cndmask_b32_e32 v35, v215, v207, vcc
	v_lshlrev_b32_e32 v0, 16, v35
	v_and_b32_e32 v1, 0xffff0000, v35
	v_pk_add_f32 v[0:1], v[22:23], v[0:1] neg_lo:[0,1] neg_hi:[0,1]
	v_pk_add_f32 v[8:9], v[8:9], v[0:1]
	v_pk_fma_f32 v[0:1], v[24:25], v[8:9], v[22:23] op_sel_hi:[0,1,1] neg_lo:[0,0,1] neg_hi:[0,0,1]
	v_cvt_pk_bf16_f32 v39, v0, v1
	global_store_dwordx4 v[6:7], v[36:39], off offset:-2048 nt
	s_waitcnt vmcnt(31)
	v_lshlrev_b32_e32 v10, 16, v224
	v_and_b32_e32 v11, 0xffff0000, v224
	v_cndmask_b32_e32 v35, v216, v208, vcc
	v_lshlrev_b32_e32 v0, 16, v35
	v_and_b32_e32 v1, 0xffff0000, v35
	v_pk_add_f32 v[0:1], v[10:11], v[0:1] neg_lo:[0,1] neg_hi:[0,1]
	v_pk_add_f32 v[26:27], v[26:27], v[0:1]
	v_pk_fma_f32 v[0:1], v[24:25], v[26:27], v[10:11] op_sel_hi:[0,1,1] neg_lo:[0,0,1] neg_hi:[0,0,1]
	v_cvt_pk_bf16_f32 v36, v0, v1
	v_lshlrev_b32_e32 v12, 16, v225
	v_and_b32_e32 v13, 0xffff0000, v225
	v_cndmask_b32_e32 v35, v217, v209, vcc
	v_lshlrev_b32_e32 v0, 16, v35
	v_and_b32_e32 v1, 0xffff0000, v35
	v_pk_add_f32 v[0:1], v[12:13], v[0:1] neg_lo:[0,1] neg_hi:[0,1]
	v_pk_add_f32 v[28:29], v[28:29], v[0:1]
	v_pk_fma_f32 v[0:1], v[24:25], v[28:29], v[12:13] op_sel_hi:[0,1,1] neg_lo:[0,0,1] neg_hi:[0,0,1]
	v_cvt_pk_bf16_f32 v37, v0, v1
	v_lshlrev_b32_e32 v14, 16, v226
	v_and_b32_e32 v15, 0xffff0000, v226
	v_cndmask_b32_e32 v35, v218, v210, vcc
	v_lshlrev_b32_e32 v0, 16, v35
	v_and_b32_e32 v1, 0xffff0000, v35
	v_pk_add_f32 v[0:1], v[14:15], v[0:1] neg_lo:[0,1] neg_hi:[0,1]
	v_pk_add_f32 v[30:31], v[30:31], v[0:1]
	v_pk_fma_f32 v[0:1], v[24:25], v[30:31], v[14:15] op_sel_hi:[0,1,1] neg_lo:[0,0,1] neg_hi:[0,0,1]
	v_cvt_pk_bf16_f32 v38, v0, v1
	v_lshlrev_b32_e32 v22, 16, v227
	v_and_b32_e32 v23, 0xffff0000, v227
	v_cndmask_b32_e32 v35, v219, v211, vcc
	v_lshlrev_b32_e32 v0, 16, v35
	v_and_b32_e32 v1, 0xffff0000, v35
	v_pk_add_f32 v[0:1], v[22:23], v[0:1] neg_lo:[0,1] neg_hi:[0,1]
	v_pk_add_f32 v[8:9], v[8:9], v[0:1]
	v_pk_fma_f32 v[0:1], v[24:25], v[8:9], v[22:23] op_sel_hi:[0,1,1] neg_lo:[0,0,1] neg_hi:[0,0,1]
	v_cvt_pk_bf16_f32 v39, v0, v1
	global_store_dwordx4 v[6:7], v[36:39], off nt
	s_waitcnt vmcnt(31)
	v_lshlrev_b32_e32 v10, 16, v228
	v_and_b32_e32 v11, 0xffff0000, v228
	v_cndmask_b32_e32 v35, v220, v212, vcc
	v_lshlrev_b32_e32 v0, 16, v35
	v_and_b32_e32 v1, 0xffff0000, v35
	v_pk_add_f32 v[0:1], v[10:11], v[0:1] neg_lo:[0,1] neg_hi:[0,1]
	v_pk_add_f32 v[26:27], v[26:27], v[0:1]
	v_pk_fma_f32 v[0:1], v[24:25], v[26:27], v[10:11] op_sel_hi:[0,1,1] neg_lo:[0,0,1] neg_hi:[0,0,1]
	v_cvt_pk_bf16_f32 v36, v0, v1
	v_lshlrev_b32_e32 v12, 16, v229
	v_and_b32_e32 v13, 0xffff0000, v229
	v_cndmask_b32_e32 v35, v221, v213, vcc
	v_lshlrev_b32_e32 v0, 16, v35
	v_and_b32_e32 v1, 0xffff0000, v35
	v_pk_add_f32 v[0:1], v[12:13], v[0:1] neg_lo:[0,1] neg_hi:[0,1]
	v_pk_add_f32 v[28:29], v[28:29], v[0:1]
	v_pk_fma_f32 v[0:1], v[24:25], v[28:29], v[12:13] op_sel_hi:[0,1,1] neg_lo:[0,0,1] neg_hi:[0,0,1]
	v_cvt_pk_bf16_f32 v37, v0, v1
	v_lshlrev_b32_e32 v14, 16, v230
	v_and_b32_e32 v15, 0xffff0000, v230
	v_cndmask_b32_e32 v35, v222, v214, vcc
	v_lshlrev_b32_e32 v0, 16, v35
	v_and_b32_e32 v1, 0xffff0000, v35
	v_pk_add_f32 v[0:1], v[14:15], v[0:1] neg_lo:[0,1] neg_hi:[0,1]
	v_pk_add_f32 v[30:31], v[30:31], v[0:1]
	v_pk_fma_f32 v[0:1], v[24:25], v[30:31], v[14:15] op_sel_hi:[0,1,1] neg_lo:[0,0,1] neg_hi:[0,0,1]
	v_cvt_pk_bf16_f32 v38, v0, v1
	v_lshlrev_b32_e32 v22, 16, v231
	v_and_b32_e32 v23, 0xffff0000, v231
	v_cndmask_b32_e32 v35, v223, v215, vcc
	v_lshlrev_b32_e32 v0, 16, v35
	v_and_b32_e32 v1, 0xffff0000, v35
	v_pk_add_f32 v[0:1], v[22:23], v[0:1] neg_lo:[0,1] neg_hi:[0,1]
	v_pk_add_f32 v[8:9], v[8:9], v[0:1]
	v_pk_fma_f32 v[0:1], v[24:25], v[8:9], v[22:23] op_sel_hi:[0,1,1] neg_lo:[0,0,1] neg_hi:[0,0,1]
	v_cvt_pk_bf16_f32 v39, v0, v1
	global_store_dwordx4 v[6:7], v[36:39], off offset:2048 nt
	s_branch .LBB0_930
; __device__ __forceinline__ float bflo(unsigned u) { return __uint_as_float(u << 16); }
; __device__ __forceinline__ float bfhi(unsigned u) { return __uint_as_float(u & 0xffff0000u); }
; __device__ __forceinline__ void pool_pass(const bf16* __restrict__ U, bf16* __restrict__ Y, int gtid, int gthreads) {
;     ...
;         const bf16* up = U + (size_t)b * SEQ * 1024 + chg * 8; bf16* yp = Y + (size_t)b * SEQ * 1024 + chg * 8;
;         const int t0 = chunk * 32;
;         float sum[8];
; #pragma unroll
;         for (int j = 0; j < 8; ++j) sum[j] = 0.f;
;         for (int i = 1; i < w; ++i) { const int t = t0 - i; if (t >= 0) { const v4u v = *(const v4u*)(up + (size_t)t * 1024);
; #pragma unroll
;             for (int j = 0; j < 4; ++j) { sum[2 * j] += bflo(v[j]); sum[2 * j + 1] += bfhi(v[j]); } } }
; #pragma unroll 4
;         for (int t = t0; t < t0 + 32; ++t) {
;             const v4u v = *(const v4u*)(up + (size_t)t * 1024);
;             const int tb = t - w; v4u vb = {0u, 0u, 0u, 0u};
;             if (t > t0 && tb >= 0) vb = *(const v4u*)(up + (size_t)tb * 1024);
.Lp10_w8:
	s_mov_b32 s2, 0xffff9800
	s_mov_b32 s3, -1
	v_lshl_add_u64 v[4:5], v[2:3], 0, s[2:3]
	s_mov_b64 exec, s[12:13]
	global_load_dwordx4 v[40:43], v[4:5], off offset:-4096
	global_load_dwordx4 v[44:47], v[4:5], off offset:-2048
	global_load_dwordx4 v[48:51], v[4:5], off
	global_load_dwordx4 v[52:55], v[4:5], off offset:2048
	s_mov_b64 exec, -1
	v_lshl_add_u64 v[4:5], v[4:5], 0, s[16:17]
	s_mov_b64 exec, s[12:13]
	global_load_dwordx4 v[56:59], v[4:5], off offset:-4096
	global_load_dwordx4 v[60:63], v[4:5], off offset:-2048
	global_load_dwordx4 v[64:67], v[4:5], off
	global_load_dwordx4 v[68:71], v[4:5], off offset:2048
	s_mov_b64 exec, -1
	v_lshl_add_u64 v[4:5], v[4:5], 0, s[16:17]
	global_load_dwordx4 v[72:75], v[4:5], off offset:-4096
	global_load_dwordx4 v[76:79], v[4:5], off offset:-2048
	global_load_dwordx4 v[80:83], v[4:5], off
	global_load_dwordx4 v[84:87], v[4:5], off offset:2048
	v_lshl_add_u64 v[4:5], v[4:5], 0, s[16:17]
	global_load_dwordx4 v[88:91], v[4:5], off offset:-4096
	global_load_dwordx4 v[92:95], v[4:5], off offset:-2048
	global_load_dwordx4 v[96:99], v[4:5], off
	global_load_dwordx4 v[100:103], v[4:5], off offset:2048
	v_lshl_add_u64 v[4:5], v[4:5], 0, s[16:17]
	global_load_dwordx4 v[104:107], v[4:5], off offset:-4096
	global_load_dwordx4 v[108:111], v[4:5], off offset:-2048
	global_load_dwordx4 v[112:115], v[4:5], off
	global_load_dwordx4 v[116:119], v[4:5], off offset:2048
	v_lshl_add_u64 v[4:5], v[4:5], 0, s[16:17]
	global_load_dwordx4 v[120:123], v[4:5], off offset:-4096
	global_load_dwordx4 v[124:127], v[4:5], off offset:-2048
	global_load_dwordx4 v[128:131], v[4:5], off
	global_load_dwordx4 v[132:135], v[4:5], off offset:2048
	v_lshl_add_u64 v[4:5], v[4:5], 0, s[16:17]
	global_load_dwordx4 v[136:139], v[4:5], off offset:-4096
	global_load_dwordx4 v[140:143], v[4:5], off offset:-2048
	global_load_dwordx4 v[144:147], v[4:5], off
	global_load_dwordx4 v[148:151], v[4:5], off offset:2048
	v_lshl_add_u64 v[4:5], v[4:5], 0, s[16:17]
	global_load_dwordx4 v[156:159], v[4:5], off offset:-4096
	global_load_dwordx4 v[160:163], v[4:5], off offset:-2048
	global_load_dwordx4 v[164:167], v[4:5], off
	global_load_dwordx4 v[168:171], v[4:5], off offset:2048
	v_lshl_add_u64 v[4:5], v[4:5], 0, s[16:17]
	global_load_dwordx4 v[172:175], v[4:5], off offset:-4096
	global_load_dwordx4 v[176:179], v[4:5], off offset:-2048
	global_load_dwordx4 v[180:183], v[4:5], off
	global_load_dwordx4 v[184:187], v[4:5], off offset:2048
	v_lshl_add_u64 v[4:5], v[4:5], 0, s[16:17]
	global_load_dwordx4 v[188:191], v[4:5], off offset:-4096
	global_load_dwordx4 v[192:195], v[4:5], off offset:-2048
	global_load_dwordx4 v[196:199], v[4:5], off
	global_load_dwordx4 v[200:203], v[4:5], off offset:2048
	v_lshl_add_u64 v[4:5], v[4:5], 0, s[16:17]
	global_load_dwordx4 v[204:207], v[4:5], off offset:-4096
	global_load_dwordx4 v[208:211], v[4:5], off offset:-2048
	global_load_dwordx4 v[212:215], v[4:5], off
	global_load_dwordx4 v[216:219], v[4:5], off offset:2048
	v_lshl_add_u64 v[4:5], v[4:5], 0, s[16:17]
	global_load_dwordx4 v[220:223], v[4:5], off offset:-4096
	global_load_dwordx4 v[224:227], v[4:5], off offset:-2048
	global_load_dwordx4 v[228:231], v[4:5], off
	s_mov_b32 s2, 0x8001000
	s_mov_b32 s3, 0
	v_lshl_add_u64 v[6:7], v[2:3], 0, s[2:3]
	v_mov_b32_e32 v26, 0
	v_mov_b32_e32 v27, 0
	v_mov_b32_e32 v28, 0
	v_mov_b32_e32 v29, 0
	v_mov_b32_e32 v30, 0
	v_mov_b32_e32 v31, 0
	v_mov_b32_e32 v8, 0
	v_mov_b32_e32 v9, 0
	s_waitcnt vmcnt(32)
	v_lshlrev_b32_e32 v0, 16, v96
	v_and_b32_e32 v1, 0xffff0000, v96
	v_pk_add_f32 v[26:27], v[26:27], v[0:1]
	v_lshlrev_b32_e32 v0, 16, v97
	v_and_b32_e32 v1, 0xffff0000, v97
	v_pk_add_f32 v[28:29], v[28:29], v[0:1]
	v_lshlrev_b32_e32 v0, 16, v98
	v_and_b32_e32 v1, 0xffff0000, v98
	v_pk_add_f32 v[30:31], v[30:31], v[0:1]
	v_lshlrev_b32_e32 v0, 16, v99
	v_and_b32_e32 v1, 0xffff0000, v99
	v_pk_add_f32 v[8:9], v[8:9], v[0:1]
	v_lshlrev_b32_e32 v0, 16, v92
	v_and_b32_e32 v1, 0xffff0000, v92
	v_pk_add_f32 v[26:27], v[26:27], v[0:1]
	v_lshlrev_b32_e32 v0, 16, v93
	v_and_b32_e32 v1, 0xffff0000, v93
	v_pk_add_f32 v[28:29], v[28:29], v[0:1]
	v_lshlrev_b32_e32 v0, 16, v94
	v_and_b32_e32 v1, 0xffff0000, v94
	v_pk_add_f32 v[30:31], v[30:31], v[0:1]
	v_lshlrev_b32_e32 v0, 16, v95
	v_and_b32_e32 v1, 0xffff0000, v95
	v_pk_add_f32 v[8:9], v[8:9], v[0:1]
	v_lshlrev_b32_e32 v0, 16, v88
	v_and_b32_e32 v1, 0xffff0000, v88
	v_pk_add_f32 v[26:27], v[26:27], v[0:1]
	v_lshlrev_b32_e32 v0, 16, v89
	v_and_b32_e32 v1, 0xffff0000, v89
	v_pk_add_f32 v[28:29], v[28:29], v[0:1]
	v_lshlrev_b32_e32 v0, 16, v90
	v_and_b32_e32 v1, 0xffff0000, v90
	v_pk_add_f32 v[30:31], v[30:31], v[0:1]
	v_lshlrev_b32_e32 v0, 16, v91
	v_and_b32_e32 v1, 0xffff0000, v91
	v_pk_add_f32 v[8:9], v[8:9], v[0:1]
	v_lshlrev_b32_e32 v0, 16, v84
	v_and_b32_e32 v1, 0xffff0000, v84
	v_pk_add_f32 v[26:27], v[26:27], v[0:1]
	v_lshlrev_b32_e32 v0, 16, v85
	v_and_b32_e32 v1, 0xffff0000, v85
	v_pk_add_f32 v[28:29], v[28:29], v[0:1]
	v_lshlrev_b32_e32 v0, 16, v86
	v_and_b32_e32 v1, 0xffff0000, v86
	v_pk_add_f32 v[30:31], v[30:31], v[0:1]
	v_lshlrev_b32_e32 v0, 16, v87
	v_and_b32_e32 v1, 0xffff0000, v87
	v_pk_add_f32 v[8:9], v[8:9], v[0:1]
	v_lshlrev_b32_e32 v0, 16, v80
	v_and_b32_e32 v1, 0xffff0000, v80
	v_pk_add_f32 v[26:27], v[26:27], v[0:1]
	v_lshlrev_b32_e32 v0, 16, v81
	v_and_b32_e32 v1, 0xffff0000, v81
	v_pk_add_f32 v[28:29], v[28:29], v[0:1]
	v_lshlrev_b32_e32 v0, 16, v82
	v_and_b32_e32 v1, 0xffff0000, v82
	v_pk_add_f32 v[30:31], v[30:31], v[0:1]
	v_lshlrev_b32_e32 v0, 16, v83
	v_and_b32_e32 v1, 0xffff0000, v83
	v_pk_add_f32 v[8:9], v[8:9], v[0:1]
	v_lshlrev_b32_e32 v0, 16, v76
; __device__ __forceinline__ unsigned cvtpk(float lo, float hi) { return pg8::cvt_pk_bf16(lo, hi); }
; __device__ __forceinline__ float bflo(unsigned u) { return __uint_as_float(u << 16); }
; __device__ __forceinline__ float bfhi(unsigned u) { return __uint_as_float(u & 0xffff0000u); }
; __device__ __forceinline__ void pool_pass(const bf16* __restrict__ U, bf16* __restrict__ Y, int gtid, int gthreads) {
;     ...
;         for (int i = 1; i < w; ++i) { const int t = t0 - i; if (t >= 0) { const v4u v = *(const v4u*)(up + (size_t)t * 1024);
; #pragma unroll
;             for (int j = 0; j < 4; ++j) { sum[2 * j] += bflo(v[j]); sum[2 * j + 1] += bfhi(v[j]); } } }
; #pragma unroll 4
;         for (int t = t0; t < t0 + 32; ++t) {
;             const v4u v = *(const v4u*)(up + (size_t)t * 1024);
;             const int tb = t - w; v4u vb = {0u, 0u, 0u, 0u};
;             if (t > t0 && tb >= 0) vb = *(const v4u*)(up + (size_t)tb * 1024);
;             const float rc = 1.0f / (float)((t + 1 < w) ? (t + 1) : w);
;             v4u o;
; #pragma unroll
;             for (int j = 0; j < 4; ++j) { const float c0 = bflo(v[j]), c1 = bfhi(v[j]);
;                 sum[2 * j] += c0 - bflo(vb[j]); sum[2 * j + 1] += c1 - bfhi(vb[j]);
;                 o[j] = cvtpk(sum[2 * j] * rc - c0, sum[2 * j + 1] * rc - c1); }
;             __builtin_nontemporal_store(o, (v4u*)(yp + (size_t)t * 1024));
	v_and_b32_e32 v1, 0xffff0000, v76
	v_pk_add_f32 v[26:27], v[26:27], v[0:1]
	v_lshlrev_b32_e32 v0, 16, v77
	v_and_b32_e32 v1, 0xffff0000, v77
	v_pk_add_f32 v[28:29], v[28:29], v[0:1]
	v_lshlrev_b32_e32 v0, 16, v78
	v_and_b32_e32 v1, 0xffff0000, v78
	v_pk_add_f32 v[30:31], v[30:31], v[0:1]
	v_lshlrev_b32_e32 v0, 16, v79
	v_and_b32_e32 v1, 0xffff0000, v79
	v_pk_add_f32 v[8:9], v[8:9], v[0:1]
	v_lshlrev_b32_e32 v0, 16, v72
	v_and_b32_e32 v1, 0xffff0000, v72
	v_pk_add_f32 v[26:27], v[26:27], v[0:1]
	v_lshlrev_b32_e32 v0, 16, v73
	v_and_b32_e32 v1, 0xffff0000, v73
	v_pk_add_f32 v[28:29], v[28:29], v[0:1]
	v_lshlrev_b32_e32 v0, 16, v74
	v_and_b32_e32 v1, 0xffff0000, v74
	v_pk_add_f32 v[30:31], v[30:31], v[0:1]
	v_lshlrev_b32_e32 v0, 16, v75
	v_and_b32_e32 v1, 0xffff0000, v75
	v_pk_add_f32 v[8:9], v[8:9], v[0:1]
	s_mov_b64 exec, s[12:13]
	v_lshlrev_b32_e32 v0, 16, v68
	v_and_b32_e32 v1, 0xffff0000, v68
	v_pk_add_f32 v[26:27], v[26:27], v[0:1]
	v_lshlrev_b32_e32 v0, 16, v69
	v_and_b32_e32 v1, 0xffff0000, v69
	v_pk_add_f32 v[28:29], v[28:29], v[0:1]
	v_lshlrev_b32_e32 v0, 16, v70
	v_and_b32_e32 v1, 0xffff0000, v70
	v_pk_add_f32 v[30:31], v[30:31], v[0:1]
	v_lshlrev_b32_e32 v0, 16, v71
	v_and_b32_e32 v1, 0xffff0000, v71
	v_pk_add_f32 v[8:9], v[8:9], v[0:1]
	v_lshlrev_b32_e32 v0, 16, v64
	v_and_b32_e32 v1, 0xffff0000, v64
	v_pk_add_f32 v[26:27], v[26:27], v[0:1]
	v_lshlrev_b32_e32 v0, 16, v65
	v_and_b32_e32 v1, 0xffff0000, v65
	v_pk_add_f32 v[28:29], v[28:29], v[0:1]
	v_lshlrev_b32_e32 v0, 16, v66
	v_and_b32_e32 v1, 0xffff0000, v66
	v_pk_add_f32 v[30:31], v[30:31], v[0:1]
	v_lshlrev_b32_e32 v0, 16, v67
	v_and_b32_e32 v1, 0xffff0000, v67
	v_pk_add_f32 v[8:9], v[8:9], v[0:1]
	v_lshlrev_b32_e32 v0, 16, v60
	v_and_b32_e32 v1, 0xffff0000, v60
	v_pk_add_f32 v[26:27], v[26:27], v[0:1]
	v_lshlrev_b32_e32 v0, 16, v61
	v_and_b32_e32 v1, 0xffff0000, v61
	v_pk_add_f32 v[28:29], v[28:29], v[0:1]
	v_lshlrev_b32_e32 v0, 16, v62
	v_and_b32_e32 v1, 0xffff0000, v62
	v_pk_add_f32 v[30:31], v[30:31], v[0:1]
	v_lshlrev_b32_e32 v0, 16, v63
	v_and_b32_e32 v1, 0xffff0000, v63
	v_pk_add_f32 v[8:9], v[8:9], v[0:1]
	v_lshlrev_b32_e32 v0, 16, v56
	v_and_b32_e32 v1, 0xffff0000, v56
	v_pk_add_f32 v[26:27], v[26:27], v[0:1]
	v_lshlrev_b32_e32 v0, 16, v57
	v_and_b32_e32 v1, 0xffff0000, v57
	v_pk_add_f32 v[28:29], v[28:29], v[0:1]
	v_lshlrev_b32_e32 v0, 16, v58
	v_and_b32_e32 v1, 0xffff0000, v58
	v_pk_add_f32 v[30:31], v[30:31], v[0:1]
	v_lshlrev_b32_e32 v0, 16, v59
	v_and_b32_e32 v1, 0xffff0000, v59
	v_pk_add_f32 v[8:9], v[8:9], v[0:1]
	v_lshlrev_b32_e32 v0, 16, v52
	v_and_b32_e32 v1, 0xffff0000, v52
	v_pk_add_f32 v[26:27], v[26:27], v[0:1]
	v_lshlrev_b32_e32 v0, 16, v53
	v_and_b32_e32 v1, 0xffff0000, v53
	v_pk_add_f32 v[28:29], v[28:29], v[0:1]
	v_lshlrev_b32_e32 v0, 16, v54
	v_and_b32_e32 v1, 0xffff0000, v54
	v_pk_add_f32 v[30:31], v[30:31], v[0:1]
	v_lshlrev_b32_e32 v0, 16, v55
	v_and_b32_e32 v1, 0xffff0000, v55
	v_pk_add_f32 v[8:9], v[8:9], v[0:1]
	v_lshlrev_b32_e32 v0, 16, v48
	v_and_b32_e32 v1, 0xffff0000, v48
	v_pk_add_f32 v[26:27], v[26:27], v[0:1]
	v_lshlrev_b32_e32 v0, 16, v49
	v_and_b32_e32 v1, 0xffff0000, v49
	v_pk_add_f32 v[28:29], v[28:29], v[0:1]
	v_lshlrev_b32_e32 v0, 16, v50
	v_and_b32_e32 v1, 0xffff0000, v50
	v_pk_add_f32 v[30:31], v[30:31], v[0:1]
	v_lshlrev_b32_e32 v0, 16, v51
	v_and_b32_e32 v1, 0xffff0000, v51
	v_pk_add_f32 v[8:9], v[8:9], v[0:1]
	v_lshlrev_b32_e32 v0, 16, v44
	v_and_b32_e32 v1, 0xffff0000, v44
	v_pk_add_f32 v[26:27], v[26:27], v[0:1]
	v_lshlrev_b32_e32 v0, 16, v45
	v_and_b32_e32 v1, 0xffff0000, v45
	v_pk_add_f32 v[28:29], v[28:29], v[0:1]
	v_lshlrev_b32_e32 v0, 16, v46
	v_and_b32_e32 v1, 0xffff0000, v46
	v_pk_add_f32 v[30:31], v[30:31], v[0:1]
	v_lshlrev_b32_e32 v0, 16, v47
	v_and_b32_e32 v1, 0xffff0000, v47
	v_pk_add_f32 v[8:9], v[8:9], v[0:1]
	v_lshlrev_b32_e32 v0, 16, v40
	v_and_b32_e32 v1, 0xffff0000, v40
	v_pk_add_f32 v[26:27], v[26:27], v[0:1]
	v_lshlrev_b32_e32 v0, 16, v41
	v_and_b32_e32 v1, 0xffff0000, v41
	v_pk_add_f32 v[28:29], v[28:29], v[0:1]
	v_lshlrev_b32_e32 v0, 16, v42
	v_and_b32_e32 v1, 0xffff0000, v42
	v_pk_add_f32 v[30:31], v[30:31], v[0:1]
	v_lshlrev_b32_e32 v0, 16, v43
	v_and_b32_e32 v1, 0xffff0000, v43
	v_pk_add_f32 v[8:9], v[8:9], v[0:1]
	s_mov_b64 exec, -1
	s_waitcnt vmcnt(31)
	v_lshlrev_b32_e32 v10, 16, v100
	v_and_b32_e32 v11, 0xffff0000, v100
	v_pk_add_f32 v[26:27], v[26:27], v[10:11]
	v_pk_fma_f32 v[0:1], v[24:25], v[26:27], v[10:11] op_sel_hi:[0,1,1] neg_lo:[0,0,1] neg_hi:[0,0,1]
	v_cvt_pk_bf16_f32 v36, v0, v1
	v_lshlrev_b32_e32 v12, 16, v101
	v_and_b32_e32 v13, 0xffff0000, v101
	v_pk_add_f32 v[28:29], v[28:29], v[12:13]
	v_pk_fma_f32 v[0:1], v[24:25], v[28:29], v[12:13] op_sel_hi:[0,1,1] neg_lo:[0,0,1] neg_hi:[0,0,1]
	v_cvt_pk_bf16_f32 v37, v0, v1
	v_lshlrev_b32_e32 v14, 16, v102
	v_and_b32_e32 v15, 0xffff0000, v102
	v_pk_add_f32 v[30:31], v[30:31], v[14:15]
	v_pk_fma_f32 v[0:1], v[24:25], v[30:31], v[14:15] op_sel_hi:[0,1,1] neg_lo:[0,0,1] neg_hi:[0,0,1]
	v_cvt_pk_bf16_f32 v38, v0, v1
	v_lshlrev_b32_e32 v22, 16, v103
	v_and_b32_e32 v23, 0xffff0000, v103
	v_pk_add_f32 v[8:9], v[8:9], v[22:23]
	v_pk_fma_f32 v[0:1], v[24:25], v[8:9], v[22:23] op_sel_hi:[0,1,1] neg_lo:[0,0,1] neg_hi:[0,0,1]
	v_cvt_pk_bf16_f32 v39, v0, v1
	global_store_dwordx4 v[6:7], v[36:39], off offset:-4096 nt
	s_waitcnt vmcnt(31)
; __device__ __forceinline__ unsigned cvtpk(float lo, float hi) { return pg8::cvt_pk_bf16(lo, hi); }
; __device__ __forceinline__ float bflo(unsigned u) { return __uint_as_float(u << 16); }
; __device__ __forceinline__ float bfhi(unsigned u) { return __uint_as_float(u & 0xffff0000u); }
; __device__ __forceinline__ void pool_pass(const bf16* __restrict__ U, bf16* __restrict__ Y, int gtid, int gthreads) {
;     ...
;         for (int t = t0; t < t0 + 32; ++t) {
;             const v4u v = *(const v4u*)(up + (size_t)t * 1024);
;             const int tb = t - w; v4u vb = {0u, 0u, 0u, 0u};
;             if (t > t0 && tb >= 0) vb = *(const v4u*)(up + (size_t)tb * 1024);
;             const float rc = 1.0f / (float)((t + 1 < w) ? (t + 1) : w);
;             v4u o;
; #pragma unroll
;             for (int j = 0; j < 4; ++j) { const float c0 = bflo(v[j]), c1 = bfhi(v[j]);
;                 sum[2 * j] += c0 - bflo(vb[j]); sum[2 * j + 1] += c1 - bfhi(vb[j]);
;                 o[j] = cvtpk(sum[2 * j] * rc - c0, sum[2 * j + 1] * rc - c1); }
;             __builtin_nontemporal_store(o, (v4u*)(yp + (size_t)t * 1024));
	v_lshlrev_b32_e32 v10, 16, v104
	v_and_b32_e32 v11, 0xffff0000, v104
	v_cndmask_b32_e32 v35, v72, v40, vcc
	v_lshlrev_b32_e32 v0, 16, v35
	v_and_b32_e32 v1, 0xffff0000, v35
	v_pk_add_f32 v[0:1], v[10:11], v[0:1] neg_lo:[0,1] neg_hi:[0,1]
	v_pk_add_f32 v[26:27], v[26:27], v[0:1]
	v_pk_fma_f32 v[0:1], v[24:25], v[26:27], v[10:11] op_sel_hi:[0,1,1] neg_lo:[0,0,1] neg_hi:[0,0,1]
	v_cvt_pk_bf16_f32 v36, v0, v1
	v_lshlrev_b32_e32 v12, 16, v105
	v_and_b32_e32 v13, 0xffff0000, v105
	v_cndmask_b32_e32 v35, v73, v41, vcc
	v_lshlrev_b32_e32 v0, 16, v35
	v_and_b32_e32 v1, 0xffff0000, v35
	v_pk_add_f32 v[0:1], v[12:13], v[0:1] neg_lo:[0,1] neg_hi:[0,1]
	v_pk_add_f32 v[28:29], v[28:29], v[0:1]
	v_pk_fma_f32 v[0:1], v[24:25], v[28:29], v[12:13] op_sel_hi:[0,1,1] neg_lo:[0,0,1] neg_hi:[0,0,1]
	v_cvt_pk_bf16_f32 v37, v0, v1
	v_lshlrev_b32_e32 v14, 16, v106
	v_and_b32_e32 v15, 0xffff0000, v106
	v_cndmask_b32_e32 v35, v74, v42, vcc
	v_lshlrev_b32_e32 v0, 16, v35
	v_and_b32_e32 v1, 0xffff0000, v35
	v_pk_add_f32 v[0:1], v[14:15], v[0:1] neg_lo:[0,1] neg_hi:[0,1]
	v_pk_add_f32 v[30:31], v[30:31], v[0:1]
	v_pk_fma_f32 v[0:1], v[24:25], v[30:31], v[14:15] op_sel_hi:[0,1,1] neg_lo:[0,0,1] neg_hi:[0,0,1]
	v_cvt_pk_bf16_f32 v38, v0, v1
	v_lshlrev_b32_e32 v22, 16, v107
	v_and_b32_e32 v23, 0xffff0000, v107
	v_cndmask_b32_e32 v35, v75, v43, vcc
	v_lshlrev_b32_e32 v0, 16, v35
	v_and_b32_e32 v1, 0xffff0000, v35
	v_pk_add_f32 v[0:1], v[22:23], v[0:1] neg_lo:[0,1] neg_hi:[0,1]
	v_pk_add_f32 v[8:9], v[8:9], v[0:1]
	v_pk_fma_f32 v[0:1], v[24:25], v[8:9], v[22:23] op_sel_hi:[0,1,1] neg_lo:[0,0,1] neg_hi:[0,0,1]
	v_cvt_pk_bf16_f32 v39, v0, v1
	global_store_dwordx4 v[6:7], v[36:39], off offset:-2048 nt
	s_waitcnt vmcnt(31)
	v_lshlrev_b32_e32 v10, 16, v108
	v_and_b32_e32 v11, 0xffff0000, v108
	v_cndmask_b32_e32 v35, v76, v44, vcc
	v_lshlrev_b32_e32 v0, 16, v35
	v_and_b32_e32 v1, 0xffff0000, v35
	v_pk_add_f32 v[0:1], v[10:11], v[0:1] neg_lo:[0,1] neg_hi:[0,1]
	v_pk_add_f32 v[26:27], v[26:27], v[0:1]
	v_pk_fma_f32 v[0:1], v[24:25], v[26:27], v[10:11] op_sel_hi:[0,1,1] neg_lo:[0,0,1] neg_hi:[0,0,1]
	v_cvt_pk_bf16_f32 v36, v0, v1
	v_lshlrev_b32_e32 v12, 16, v109
	v_and_b32_e32 v13, 0xffff0000, v109
	v_cndmask_b32_e32 v35, v77, v45, vcc
	v_lshlrev_b32_e32 v0, 16, v35
	v_and_b32_e32 v1, 0xffff0000, v35
	v_pk_add_f32 v[0:1], v[12:13], v[0:1] neg_lo:[0,1] neg_hi:[0,1]
	v_pk_add_f32 v[28:29], v[28:29], v[0:1]
	v_pk_fma_f32 v[0:1], v[24:25], v[28:29], v[12:13] op_sel_hi:[0,1,1] neg_lo:[0,0,1] neg_hi:[0,0,1]
	v_cvt_pk_bf16_f32 v37, v0, v1
	v_lshlrev_b32_e32 v14, 16, v110
	v_and_b32_e32 v15, 0xffff0000, v110
	v_cndmask_b32_e32 v35, v78, v46, vcc
	v_lshlrev_b32_e32 v0, 16, v35
	v_and_b32_e32 v1, 0xffff0000, v35
	v_pk_add_f32 v[0:1], v[14:15], v[0:1] neg_lo:[0,1] neg_hi:[0,1]
	v_pk_add_f32 v[30:31], v[30:31], v[0:1]
	v_pk_fma_f32 v[0:1], v[24:25], v[30:31], v[14:15] op_sel_hi:[0,1,1] neg_lo:[0,0,1] neg_hi:[0,0,1]
	v_cvt_pk_bf16_f32 v38, v0, v1
	v_lshlrev_b32_e32 v22, 16, v111
	v_and_b32_e32 v23, 0xffff0000, v111
	v_cndmask_b32_e32 v35, v79, v47, vcc
	v_lshlrev_b32_e32 v0, 16, v35
	v_and_b32_e32 v1, 0xffff0000, v35
	v_pk_add_f32 v[0:1], v[22:23], v[0:1] neg_lo:[0,1] neg_hi:[0,1]
	v_pk_add_f32 v[8:9], v[8:9], v[0:1]
	v_pk_fma_f32 v[0:1], v[24:25], v[8:9], v[22:23] op_sel_hi:[0,1,1] neg_lo:[0,0,1] neg_hi:[0,0,1]
	v_cvt_pk_bf16_f32 v39, v0, v1
	global_store_dwordx4 v[6:7], v[36:39], off nt
	s_waitcnt vmcnt(31)
	v_lshlrev_b32_e32 v10, 16, v112
	v_and_b32_e32 v11, 0xffff0000, v112
	v_cndmask_b32_e32 v35, v80, v48, vcc
	v_lshlrev_b32_e32 v0, 16, v35
	v_and_b32_e32 v1, 0xffff0000, v35
	v_pk_add_f32 v[0:1], v[10:11], v[0:1] neg_lo:[0,1] neg_hi:[0,1]
	v_pk_add_f32 v[26:27], v[26:27], v[0:1]
	v_pk_fma_f32 v[0:1], v[24:25], v[26:27], v[10:11] op_sel_hi:[0,1,1] neg_lo:[0,0,1] neg_hi:[0,0,1]
	v_cvt_pk_bf16_f32 v36, v0, v1
	v_lshlrev_b32_e32 v12, 16, v113
	v_and_b32_e32 v13, 0xffff0000, v113
	v_cndmask_b32_e32 v35, v81, v49, vcc
	v_lshlrev_b32_e32 v0, 16, v35
	v_and_b32_e32 v1, 0xffff0000, v35
	v_pk_add_f32 v[0:1], v[12:13], v[0:1] neg_lo:[0,1] neg_hi:[0,1]
	v_pk_add_f32 v[28:29], v[28:29], v[0:1]
	v_pk_fma_f32 v[0:1], v[24:25], v[28:29], v[12:13] op_sel_hi:[0,1,1] neg_lo:[0,0,1] neg_hi:[0,0,1]
	v_cvt_pk_bf16_f32 v37, v0, v1
	v_lshlrev_b32_e32 v14, 16, v114
	v_and_b32_e32 v15, 0xffff0000, v114
	v_cndmask_b32_e32 v35, v82, v50, vcc
	v_lshlrev_b32_e32 v0, 16, v35
	v_and_b32_e32 v1, 0xffff0000, v35
	v_pk_add_f32 v[0:1], v[14:15], v[0:1] neg_lo:[0,1] neg_hi:[0,1]
	v_pk_add_f32 v[30:31], v[30:31], v[0:1]
	v_pk_fma_f32 v[0:1], v[24:25], v[30:31], v[14:15] op_sel_hi:[0,1,1] neg_lo:[0,0,1] neg_hi:[0,0,1]
	v_cvt_pk_bf16_f32 v38, v0, v1
	v_lshlrev_b32_e32 v22, 16, v115
	v_and_b32_e32 v23, 0xffff0000, v115
	v_cndmask_b32_e32 v35, v83, v51, vcc
	v_lshlrev_b32_e32 v0, 16, v35
	v_and_b32_e32 v1, 0xffff0000, v35
	v_pk_add_f32 v[0:1], v[22:23], v[0:1] neg_lo:[0,1] neg_hi:[0,1]
	v_pk_add_f32 v[8:9], v[8:9], v[0:1]
	v_pk_fma_f32 v[0:1], v[24:25], v[8:9], v[22:23] op_sel_hi:[0,1,1] neg_lo:[0,0,1] neg_hi:[0,0,1]
	v_cvt_pk_bf16_f32 v39, v0, v1
	global_store_dwordx4 v[6:7], v[36:39], off offset:2048 nt
	s_waitcnt vmcnt(31)
; __device__ __forceinline__ unsigned cvtpk(float lo, float hi) { return pg8::cvt_pk_bf16(lo, hi); }
; __device__ __forceinline__ float bflo(unsigned u) { return __uint_as_float(u << 16); }
; __device__ __forceinline__ float bfhi(unsigned u) { return __uint_as_float(u & 0xffff0000u); }
; __device__ __forceinline__ void pool_pass(const bf16* __restrict__ U, bf16* __restrict__ Y, int gtid, int gthreads) {
;     ...
;         for (int t = t0; t < t0 + 32; ++t) {
;             const v4u v = *(const v4u*)(up + (size_t)t * 1024);
;             const int tb = t - w; v4u vb = {0u, 0u, 0u, 0u};
;             if (t > t0 && tb >= 0) vb = *(const v4u*)(up + (size_t)tb * 1024);
;             const float rc = 1.0f / (float)((t + 1 < w) ? (t + 1) : w);
;             v4u o;
; #pragma unroll
;             for (int j = 0; j < 4; ++j) { const float c0 = bflo(v[j]), c1 = bfhi(v[j]);
;                 sum[2 * j] += c0 - bflo(vb[j]); sum[2 * j + 1] += c1 - bfhi(vb[j]);
;                 o[j] = cvtpk(sum[2 * j] * rc - c0, sum[2 * j + 1] * rc - c1); }
;             __builtin_nontemporal_store(o, (v4u*)(yp + (size_t)t * 1024));
	v_lshlrev_b32_e32 v10, 16, v116
	v_and_b32_e32 v11, 0xffff0000, v116
	v_cndmask_b32_e32 v35, v84, v52, vcc
	v_lshlrev_b32_e32 v0, 16, v35
	v_and_b32_e32 v1, 0xffff0000, v35
	v_pk_add_f32 v[0:1], v[10:11], v[0:1] neg_lo:[0,1] neg_hi:[0,1]
	v_pk_add_f32 v[26:27], v[26:27], v[0:1]
	v_pk_fma_f32 v[0:1], v[24:25], v[26:27], v[10:11] op_sel_hi:[0,1,1] neg_lo:[0,0,1] neg_hi:[0,0,1]
	v_cvt_pk_bf16_f32 v36, v0, v1
	v_lshlrev_b32_e32 v12, 16, v117
	v_and_b32_e32 v13, 0xffff0000, v117
	v_cndmask_b32_e32 v35, v85, v53, vcc
	v_lshlrev_b32_e32 v0, 16, v35
	v_and_b32_e32 v1, 0xffff0000, v35
	v_pk_add_f32 v[0:1], v[12:13], v[0:1] neg_lo:[0,1] neg_hi:[0,1]
	v_pk_add_f32 v[28:29], v[28:29], v[0:1]
	v_pk_fma_f32 v[0:1], v[24:25], v[28:29], v[12:13] op_sel_hi:[0,1,1] neg_lo:[0,0,1] neg_hi:[0,0,1]
	v_cvt_pk_bf16_f32 v37, v0, v1
	v_lshlrev_b32_e32 v14, 16, v118
	v_and_b32_e32 v15, 0xffff0000, v118
	v_cndmask_b32_e32 v35, v86, v54, vcc
	v_lshlrev_b32_e32 v0, 16, v35
	v_and_b32_e32 v1, 0xffff0000, v35
	v_pk_add_f32 v[0:1], v[14:15], v[0:1] neg_lo:[0,1] neg_hi:[0,1]
	v_pk_add_f32 v[30:31], v[30:31], v[0:1]
	v_pk_fma_f32 v[0:1], v[24:25], v[30:31], v[14:15] op_sel_hi:[0,1,1] neg_lo:[0,0,1] neg_hi:[0,0,1]
	v_cvt_pk_bf16_f32 v38, v0, v1
	v_lshlrev_b32_e32 v22, 16, v119
	v_and_b32_e32 v23, 0xffff0000, v119
	v_cndmask_b32_e32 v35, v87, v55, vcc
	v_lshlrev_b32_e32 v0, 16, v35
	v_and_b32_e32 v1, 0xffff0000, v35
	v_pk_add_f32 v[0:1], v[22:23], v[0:1] neg_lo:[0,1] neg_hi:[0,1]
	v_pk_add_f32 v[8:9], v[8:9], v[0:1]
	v_pk_fma_f32 v[0:1], v[24:25], v[8:9], v[22:23] op_sel_hi:[0,1,1] neg_lo:[0,0,1] neg_hi:[0,0,1]
	v_cvt_pk_bf16_f32 v39, v0, v1
	v_lshl_add_u64 v[6:7], v[6:7], 0, s[16:17]
	global_store_dwordx4 v[6:7], v[36:39], off offset:-4096 nt
	s_waitcnt vmcnt(31)
	v_lshlrev_b32_e32 v10, 16, v120
	v_and_b32_e32 v11, 0xffff0000, v120
	v_cndmask_b32_e32 v35, v88, v56, vcc
	v_lshlrev_b32_e32 v0, 16, v35
	v_and_b32_e32 v1, 0xffff0000, v35
	v_pk_add_f32 v[0:1], v[10:11], v[0:1] neg_lo:[0,1] neg_hi:[0,1]
	v_pk_add_f32 v[26:27], v[26:27], v[0:1]
	v_pk_fma_f32 v[0:1], v[24:25], v[26:27], v[10:11] op_sel_hi:[0,1,1] neg_lo:[0,0,1] neg_hi:[0,0,1]
	v_cvt_pk_bf16_f32 v36, v0, v1
	v_lshlrev_b32_e32 v12, 16, v121
	v_and_b32_e32 v13, 0xffff0000, v121
	v_cndmask_b32_e32 v35, v89, v57, vcc
	v_lshlrev_b32_e32 v0, 16, v35
	v_and_b32_e32 v1, 0xffff0000, v35
	v_pk_add_f32 v[0:1], v[12:13], v[0:1] neg_lo:[0,1] neg_hi:[0,1]
	v_pk_add_f32 v[28:29], v[28:29], v[0:1]
	v_pk_fma_f32 v[0:1], v[24:25], v[28:29], v[12:13] op_sel_hi:[0,1,1] neg_lo:[0,0,1] neg_hi:[0,0,1]
	v_cvt_pk_bf16_f32 v37, v0, v1
	v_lshlrev_b32_e32 v14, 16, v122
	v_and_b32_e32 v15, 0xffff0000, v122
	v_cndmask_b32_e32 v35, v90, v58, vcc
	v_lshlrev_b32_e32 v0, 16, v35
	v_and_b32_e32 v1, 0xffff0000, v35
	v_pk_add_f32 v[0:1], v[14:15], v[0:1] neg_lo:[0,1] neg_hi:[0,1]
	v_pk_add_f32 v[30:31], v[30:31], v[0:1]
	v_pk_fma_f32 v[0:1], v[24:25], v[30:31], v[14:15] op_sel_hi:[0,1,1] neg_lo:[0,0,1] neg_hi:[0,0,1]
	v_cvt_pk_bf16_f32 v38, v0, v1
	v_lshlrev_b32_e32 v22, 16, v123
	v_and_b32_e32 v23, 0xffff0000, v123
	v_cndmask_b32_e32 v35, v91, v59, vcc
	v_lshlrev_b32_e32 v0, 16, v35
	v_and_b32_e32 v1, 0xffff0000, v35
	v_pk_add_f32 v[0:1], v[22:23], v[0:1] neg_lo:[0,1] neg_hi:[0,1]
	v_pk_add_f32 v[8:9], v[8:9], v[0:1]
	v_pk_fma_f32 v[0:1], v[24:25], v[8:9], v[22:23] op_sel_hi:[0,1,1] neg_lo:[0,0,1] neg_hi:[0,0,1]
	v_cvt_pk_bf16_f32 v39, v0, v1
	global_store_dwordx4 v[6:7], v[36:39], off offset:-2048 nt
	s_waitcnt vmcnt(31)
	v_lshlrev_b32_e32 v10, 16, v124
	v_and_b32_e32 v11, 0xffff0000, v124
	v_cndmask_b32_e32 v35, v92, v60, vcc
	v_lshlrev_b32_e32 v0, 16, v35
	v_and_b32_e32 v1, 0xffff0000, v35
	v_pk_add_f32 v[0:1], v[10:11], v[0:1] neg_lo:[0,1] neg_hi:[0,1]
	v_pk_add_f32 v[26:27], v[26:27], v[0:1]
	v_pk_fma_f32 v[0:1], v[24:25], v[26:27], v[10:11] op_sel_hi:[0,1,1] neg_lo:[0,0,1] neg_hi:[0,0,1]
	v_cvt_pk_bf16_f32 v36, v0, v1
	v_lshlrev_b32_e32 v12, 16, v125
	v_and_b32_e32 v13, 0xffff0000, v125
	v_cndmask_b32_e32 v35, v93, v61, vcc
	v_lshlrev_b32_e32 v0, 16, v35
	v_and_b32_e32 v1, 0xffff0000, v35
	v_pk_add_f32 v[0:1], v[12:13], v[0:1] neg_lo:[0,1] neg_hi:[0,1]
	v_pk_add_f32 v[28:29], v[28:29], v[0:1]
	v_pk_fma_f32 v[0:1], v[24:25], v[28:29], v[12:13] op_sel_hi:[0,1,1] neg_lo:[0,0,1] neg_hi:[0,0,1]
	v_cvt_pk_bf16_f32 v37, v0, v1
	v_lshlrev_b32_e32 v14, 16, v126
	v_and_b32_e32 v15, 0xffff0000, v126
	v_cndmask_b32_e32 v35, v94, v62, vcc
	v_lshlrev_b32_e32 v0, 16, v35
	v_and_b32_e32 v1, 0xffff0000, v35
	v_pk_add_f32 v[0:1], v[14:15], v[0:1] neg_lo:[0,1] neg_hi:[0,1]
	v_pk_add_f32 v[30:31], v[30:31], v[0:1]
	v_pk_fma_f32 v[0:1], v[24:25], v[30:31], v[14:15] op_sel_hi:[0,1,1] neg_lo:[0,0,1] neg_hi:[0,0,1]
	v_cvt_pk_bf16_f32 v38, v0, v1
	v_lshlrev_b32_e32 v22, 16, v127
	v_and_b32_e32 v23, 0xffff0000, v127
	v_cndmask_b32_e32 v35, v95, v63, vcc
	v_lshlrev_b32_e32 v0, 16, v35
	v_and_b32_e32 v1, 0xffff0000, v35
	v_pk_add_f32 v[0:1], v[22:23], v[0:1] neg_lo:[0,1] neg_hi:[0,1]
	v_pk_add_f32 v[8:9], v[8:9], v[0:1]
	v_pk_fma_f32 v[0:1], v[24:25], v[8:9], v[22:23] op_sel_hi:[0,1,1] neg_lo:[0,0,1] neg_hi:[0,0,1]
	v_cvt_pk_bf16_f32 v39, v0, v1
	global_store_dwordx4 v[6:7], v[36:39], off nt
	s_waitcnt vmcnt(31)
; __device__ __forceinline__ unsigned cvtpk(float lo, float hi) { return pg8::cvt_pk_bf16(lo, hi); }
; __device__ __forceinline__ float bflo(unsigned u) { return __uint_as_float(u << 16); }
; __device__ __forceinline__ float bfhi(unsigned u) { return __uint_as_float(u & 0xffff0000u); }
; __device__ __forceinline__ void pool_pass(const bf16* __restrict__ U, bf16* __restrict__ Y, int gtid, int gthreads) {
;     ...
;         for (int t = t0; t < t0 + 32; ++t) {
;             const v4u v = *(const v4u*)(up + (size_t)t * 1024);
;             const int tb = t - w; v4u vb = {0u, 0u, 0u, 0u};
;             if (t > t0 && tb >= 0) vb = *(const v4u*)(up + (size_t)tb * 1024);
;             const float rc = 1.0f / (float)((t + 1 < w) ? (t + 1) : w);
;             v4u o;
; #pragma unroll
;             for (int j = 0; j < 4; ++j) { const float c0 = bflo(v[j]), c1 = bfhi(v[j]);
;                 sum[2 * j] += c0 - bflo(vb[j]); sum[2 * j + 1] += c1 - bfhi(vb[j]);
;                 o[j] = cvtpk(sum[2 * j] * rc - c0, sum[2 * j + 1] * rc - c1); }
;             __builtin_nontemporal_store(o, (v4u*)(yp + (size_t)t * 1024));
	v_lshlrev_b32_e32 v10, 16, v128
	v_and_b32_e32 v11, 0xffff0000, v128
	v_cndmask_b32_e32 v35, v96, v64, vcc
	v_lshlrev_b32_e32 v0, 16, v35
	v_and_b32_e32 v1, 0xffff0000, v35
	v_pk_add_f32 v[0:1], v[10:11], v[0:1] neg_lo:[0,1] neg_hi:[0,1]
	v_pk_add_f32 v[26:27], v[26:27], v[0:1]
	v_pk_fma_f32 v[0:1], v[24:25], v[26:27], v[10:11] op_sel_hi:[0,1,1] neg_lo:[0,0,1] neg_hi:[0,0,1]
	v_cvt_pk_bf16_f32 v36, v0, v1
	v_lshlrev_b32_e32 v12, 16, v129
	v_and_b32_e32 v13, 0xffff0000, v129
	v_cndmask_b32_e32 v35, v97, v65, vcc
	v_lshlrev_b32_e32 v0, 16, v35
	v_and_b32_e32 v1, 0xffff0000, v35
	v_pk_add_f32 v[0:1], v[12:13], v[0:1] neg_lo:[0,1] neg_hi:[0,1]
	v_pk_add_f32 v[28:29], v[28:29], v[0:1]
	v_pk_fma_f32 v[0:1], v[24:25], v[28:29], v[12:13] op_sel_hi:[0,1,1] neg_lo:[0,0,1] neg_hi:[0,0,1]
	v_cvt_pk_bf16_f32 v37, v0, v1
	v_lshlrev_b32_e32 v14, 16, v130
	v_and_b32_e32 v15, 0xffff0000, v130
	v_cndmask_b32_e32 v35, v98, v66, vcc
	v_lshlrev_b32_e32 v0, 16, v35
	v_and_b32_e32 v1, 0xffff0000, v35
	v_pk_add_f32 v[0:1], v[14:15], v[0:1] neg_lo:[0,1] neg_hi:[0,1]
	v_pk_add_f32 v[30:31], v[30:31], v[0:1]
	v_pk_fma_f32 v[0:1], v[24:25], v[30:31], v[14:15] op_sel_hi:[0,1,1] neg_lo:[0,0,1] neg_hi:[0,0,1]
	v_cvt_pk_bf16_f32 v38, v0, v1
	v_lshlrev_b32_e32 v22, 16, v131
	v_and_b32_e32 v23, 0xffff0000, v131
	v_cndmask_b32_e32 v35, v99, v67, vcc
	v_lshlrev_b32_e32 v0, 16, v35
	v_and_b32_e32 v1, 0xffff0000, v35
	v_pk_add_f32 v[0:1], v[22:23], v[0:1] neg_lo:[0,1] neg_hi:[0,1]
	v_pk_add_f32 v[8:9], v[8:9], v[0:1]
	v_pk_fma_f32 v[0:1], v[24:25], v[8:9], v[22:23] op_sel_hi:[0,1,1] neg_lo:[0,0,1] neg_hi:[0,0,1]
	v_cvt_pk_bf16_f32 v39, v0, v1
	global_store_dwordx4 v[6:7], v[36:39], off offset:2048 nt
	s_waitcnt vmcnt(31)
	v_lshlrev_b32_e32 v10, 16, v132
	v_and_b32_e32 v11, 0xffff0000, v132
	v_cndmask_b32_e32 v35, v100, v68, vcc
	v_lshlrev_b32_e32 v0, 16, v35
	v_and_b32_e32 v1, 0xffff0000, v35
	v_pk_add_f32 v[0:1], v[10:11], v[0:1] neg_lo:[0,1] neg_hi:[0,1]
	v_pk_add_f32 v[26:27], v[26:27], v[0:1]
	v_pk_fma_f32 v[0:1], v[24:25], v[26:27], v[10:11] op_sel_hi:[0,1,1] neg_lo:[0,0,1] neg_hi:[0,0,1]
	v_cvt_pk_bf16_f32 v36, v0, v1
	v_lshlrev_b32_e32 v12, 16, v133
	v_and_b32_e32 v13, 0xffff0000, v133
	v_cndmask_b32_e32 v35, v101, v69, vcc
	v_lshlrev_b32_e32 v0, 16, v35
	v_and_b32_e32 v1, 0xffff0000, v35
	v_pk_add_f32 v[0:1], v[12:13], v[0:1] neg_lo:[0,1] neg_hi:[0,1]
	v_pk_add_f32 v[28:29], v[28:29], v[0:1]
	v_pk_fma_f32 v[0:1], v[24:25], v[28:29], v[12:13] op_sel_hi:[0,1,1] neg_lo:[0,0,1] neg_hi:[0,0,1]
	v_cvt_pk_bf16_f32 v37, v0, v1
	v_lshlrev_b32_e32 v14, 16, v134
	v_and_b32_e32 v15, 0xffff0000, v134
	v_cndmask_b32_e32 v35, v102, v70, vcc
	v_lshlrev_b32_e32 v0, 16, v35
	v_and_b32_e32 v1, 0xffff0000, v35
	v_pk_add_f32 v[0:1], v[14:15], v[0:1] neg_lo:[0,1] neg_hi:[0,1]
	v_pk_add_f32 v[30:31], v[30:31], v[0:1]
	v_pk_fma_f32 v[0:1], v[24:25], v[30:31], v[14:15] op_sel_hi:[0,1,1] neg_lo:[0,0,1] neg_hi:[0,0,1]
	v_cvt_pk_bf16_f32 v38, v0, v1
	v_lshlrev_b32_e32 v22, 16, v135
	v_and_b32_e32 v23, 0xffff0000, v135
	v_cndmask_b32_e32 v35, v103, v71, vcc
	v_lshlrev_b32_e32 v0, 16, v35
	v_and_b32_e32 v1, 0xffff0000, v35
	v_pk_add_f32 v[0:1], v[22:23], v[0:1] neg_lo:[0,1] neg_hi:[0,1]
	v_pk_add_f32 v[8:9], v[8:9], v[0:1]
	v_pk_fma_f32 v[0:1], v[24:25], v[8:9], v[22:23] op_sel_hi:[0,1,1] neg_lo:[0,0,1] neg_hi:[0,0,1]
	v_cvt_pk_bf16_f32 v39, v0, v1
	v_lshl_add_u64 v[6:7], v[6:7], 0, s[16:17]
	global_store_dwordx4 v[6:7], v[36:39], off offset:-4096 nt
	s_waitcnt vmcnt(31)
	v_lshlrev_b32_e32 v10, 16, v136
	v_and_b32_e32 v11, 0xffff0000, v136
	v_cndmask_b32_e32 v35, v104, v72, vcc
	v_lshlrev_b32_e32 v0, 16, v35
	v_and_b32_e32 v1, 0xffff0000, v35
	v_pk_add_f32 v[0:1], v[10:11], v[0:1] neg_lo:[0,1] neg_hi:[0,1]
	v_pk_add_f32 v[26:27], v[26:27], v[0:1]
	v_pk_fma_f32 v[0:1], v[24:25], v[26:27], v[10:11] op_sel_hi:[0,1,1] neg_lo:[0,0,1] neg_hi:[0,0,1]
	v_cvt_pk_bf16_f32 v36, v0, v1
	v_lshlrev_b32_e32 v12, 16, v137
	v_and_b32_e32 v13, 0xffff0000, v137
	v_cndmask_b32_e32 v35, v105, v73, vcc
	v_lshlrev_b32_e32 v0, 16, v35
	v_and_b32_e32 v1, 0xffff0000, v35
	v_pk_add_f32 v[0:1], v[12:13], v[0:1] neg_lo:[0,1] neg_hi:[0,1]
	v_pk_add_f32 v[28:29], v[28:29], v[0:1]
	v_pk_fma_f32 v[0:1], v[24:25], v[28:29], v[12:13] op_sel_hi:[0,1,1] neg_lo:[0,0,1] neg_hi:[0,0,1]
	v_cvt_pk_bf16_f32 v37, v0, v1
	v_lshlrev_b32_e32 v14, 16, v138
	v_and_b32_e32 v15, 0xffff0000, v138
	v_cndmask_b32_e32 v35, v106, v74, vcc
	v_lshlrev_b32_e32 v0, 16, v35
	v_and_b32_e32 v1, 0xffff0000, v35
	v_pk_add_f32 v[0:1], v[14:15], v[0:1] neg_lo:[0,1] neg_hi:[0,1]
	v_pk_add_f32 v[30:31], v[30:31], v[0:1]
	v_pk_fma_f32 v[0:1], v[24:25], v[30:31], v[14:15] op_sel_hi:[0,1,1] neg_lo:[0,0,1] neg_hi:[0,0,1]
	v_cvt_pk_bf16_f32 v38, v0, v1
	v_lshlrev_b32_e32 v22, 16, v139
	v_and_b32_e32 v23, 0xffff0000, v139
	v_cndmask_b32_e32 v35, v107, v75, vcc
	v_lshlrev_b32_e32 v0, 16, v35
	v_and_b32_e32 v1, 0xffff0000, v35
	v_pk_add_f32 v[0:1], v[22:23], v[0:1] neg_lo:[0,1] neg_hi:[0,1]
	v_pk_add_f32 v[8:9], v[8:9], v[0:1]
	v_pk_fma_f32 v[0:1], v[24:25], v[8:9], v[22:23] op_sel_hi:[0,1,1] neg_lo:[0,0,1] neg_hi:[0,0,1]
	v_cvt_pk_bf16_f32 v39, v0, v1
	global_store_dwordx4 v[6:7], v[36:39], off offset:-2048 nt
	s_waitcnt vmcnt(31)
; __device__ __forceinline__ unsigned cvtpk(float lo, float hi) { return pg8::cvt_pk_bf16(lo, hi); }
; __device__ __forceinline__ float bflo(unsigned u) { return __uint_as_float(u << 16); }
; __device__ __forceinline__ float bfhi(unsigned u) { return __uint_as_float(u & 0xffff0000u); }
; __device__ __forceinline__ void pool_pass(const bf16* __restrict__ U, bf16* __restrict__ Y, int gtid, int gthreads) {
;     ...
;         for (int t = t0; t < t0 + 32; ++t) {
;             const v4u v = *(const v4u*)(up + (size_t)t * 1024);
;             const int tb = t - w; v4u vb = {0u, 0u, 0u, 0u};
;             if (t > t0 && tb >= 0) vb = *(const v4u*)(up + (size_t)tb * 1024);
;             const float rc = 1.0f / (float)((t + 1 < w) ? (t + 1) : w);
;             v4u o;
; #pragma unroll
;             for (int j = 0; j < 4; ++j) { const float c0 = bflo(v[j]), c1 = bfhi(v[j]);
;                 sum[2 * j] += c0 - bflo(vb[j]); sum[2 * j + 1] += c1 - bfhi(vb[j]);
;                 o[j] = cvtpk(sum[2 * j] * rc - c0, sum[2 * j + 1] * rc - c1); }
;             __builtin_nontemporal_store(o, (v4u*)(yp + (size_t)t * 1024));
	v_lshlrev_b32_e32 v10, 16, v140
	v_and_b32_e32 v11, 0xffff0000, v140
	v_cndmask_b32_e32 v35, v108, v76, vcc
	v_lshlrev_b32_e32 v0, 16, v35
	v_and_b32_e32 v1, 0xffff0000, v35
	v_pk_add_f32 v[0:1], v[10:11], v[0:1] neg_lo:[0,1] neg_hi:[0,1]
	v_pk_add_f32 v[26:27], v[26:27], v[0:1]
	v_pk_fma_f32 v[0:1], v[24:25], v[26:27], v[10:11] op_sel_hi:[0,1,1] neg_lo:[0,0,1] neg_hi:[0,0,1]
	v_cvt_pk_bf16_f32 v36, v0, v1
	v_lshlrev_b32_e32 v12, 16, v141
	v_and_b32_e32 v13, 0xffff0000, v141
	v_cndmask_b32_e32 v35, v109, v77, vcc
	v_lshlrev_b32_e32 v0, 16, v35
	v_and_b32_e32 v1, 0xffff0000, v35
	v_pk_add_f32 v[0:1], v[12:13], v[0:1] neg_lo:[0,1] neg_hi:[0,1]
	v_pk_add_f32 v[28:29], v[28:29], v[0:1]
	v_pk_fma_f32 v[0:1], v[24:25], v[28:29], v[12:13] op_sel_hi:[0,1,1] neg_lo:[0,0,1] neg_hi:[0,0,1]
	v_cvt_pk_bf16_f32 v37, v0, v1
	v_lshlrev_b32_e32 v14, 16, v142
	v_and_b32_e32 v15, 0xffff0000, v142
	v_cndmask_b32_e32 v35, v110, v78, vcc
	v_lshlrev_b32_e32 v0, 16, v35
	v_and_b32_e32 v1, 0xffff0000, v35
	v_pk_add_f32 v[0:1], v[14:15], v[0:1] neg_lo:[0,1] neg_hi:[0,1]
	v_pk_add_f32 v[30:31], v[30:31], v[0:1]
	v_pk_fma_f32 v[0:1], v[24:25], v[30:31], v[14:15] op_sel_hi:[0,1,1] neg_lo:[0,0,1] neg_hi:[0,0,1]
	v_cvt_pk_bf16_f32 v38, v0, v1
	v_lshlrev_b32_e32 v22, 16, v143
	v_and_b32_e32 v23, 0xffff0000, v143
	v_cndmask_b32_e32 v35, v111, v79, vcc
	v_lshlrev_b32_e32 v0, 16, v35
	v_and_b32_e32 v1, 0xffff0000, v35
	v_pk_add_f32 v[0:1], v[22:23], v[0:1] neg_lo:[0,1] neg_hi:[0,1]
	v_pk_add_f32 v[8:9], v[8:9], v[0:1]
	v_pk_fma_f32 v[0:1], v[24:25], v[8:9], v[22:23] op_sel_hi:[0,1,1] neg_lo:[0,0,1] neg_hi:[0,0,1]
	v_cvt_pk_bf16_f32 v39, v0, v1
	global_store_dwordx4 v[6:7], v[36:39], off nt
	s_waitcnt vmcnt(31)
	v_lshlrev_b32_e32 v10, 16, v144
	v_and_b32_e32 v11, 0xffff0000, v144
	v_cndmask_b32_e32 v35, v112, v80, vcc
	v_lshlrev_b32_e32 v0, 16, v35
	v_and_b32_e32 v1, 0xffff0000, v35
	v_pk_add_f32 v[0:1], v[10:11], v[0:1] neg_lo:[0,1] neg_hi:[0,1]
	v_pk_add_f32 v[26:27], v[26:27], v[0:1]
	v_pk_fma_f32 v[0:1], v[24:25], v[26:27], v[10:11] op_sel_hi:[0,1,1] neg_lo:[0,0,1] neg_hi:[0,0,1]
	v_cvt_pk_bf16_f32 v36, v0, v1
	v_lshlrev_b32_e32 v12, 16, v145
	v_and_b32_e32 v13, 0xffff0000, v145
	v_cndmask_b32_e32 v35, v113, v81, vcc
	v_lshlrev_b32_e32 v0, 16, v35
	v_and_b32_e32 v1, 0xffff0000, v35
	v_pk_add_f32 v[0:1], v[12:13], v[0:1] neg_lo:[0,1] neg_hi:[0,1]
	v_pk_add_f32 v[28:29], v[28:29], v[0:1]
	v_pk_fma_f32 v[0:1], v[24:25], v[28:29], v[12:13] op_sel_hi:[0,1,1] neg_lo:[0,0,1] neg_hi:[0,0,1]
	v_cvt_pk_bf16_f32 v37, v0, v1
	v_lshlrev_b32_e32 v14, 16, v146
	v_and_b32_e32 v15, 0xffff0000, v146
	v_cndmask_b32_e32 v35, v114, v82, vcc
	v_lshlrev_b32_e32 v0, 16, v35
	v_and_b32_e32 v1, 0xffff0000, v35
	v_pk_add_f32 v[0:1], v[14:15], v[0:1] neg_lo:[0,1] neg_hi:[0,1]
	v_pk_add_f32 v[30:31], v[30:31], v[0:1]
	v_pk_fma_f32 v[0:1], v[24:25], v[30:31], v[14:15] op_sel_hi:[0,1,1] neg_lo:[0,0,1] neg_hi:[0,0,1]
	v_cvt_pk_bf16_f32 v38, v0, v1
	v_lshlrev_b32_e32 v22, 16, v147
	v_and_b32_e32 v23, 0xffff0000, v147
	v_cndmask_b32_e32 v35, v115, v83, vcc
	v_lshlrev_b32_e32 v0, 16, v35
	v_and_b32_e32 v1, 0xffff0000, v35
	v_pk_add_f32 v[0:1], v[22:23], v[0:1] neg_lo:[0,1] neg_hi:[0,1]
	v_pk_add_f32 v[8:9], v[8:9], v[0:1]
	v_pk_fma_f32 v[0:1], v[24:25], v[8:9], v[22:23] op_sel_hi:[0,1,1] neg_lo:[0,0,1] neg_hi:[0,0,1]
	v_cvt_pk_bf16_f32 v39, v0, v1
	global_store_dwordx4 v[6:7], v[36:39], off offset:2048 nt
	s_waitcnt vmcnt(31)
	v_lshlrev_b32_e32 v10, 16, v148
	v_and_b32_e32 v11, 0xffff0000, v148
	v_cndmask_b32_e32 v35, v116, v84, vcc
	v_lshlrev_b32_e32 v0, 16, v35
	v_and_b32_e32 v1, 0xffff0000, v35
	v_pk_add_f32 v[0:1], v[10:11], v[0:1] neg_lo:[0,1] neg_hi:[0,1]
	v_pk_add_f32 v[26:27], v[26:27], v[0:1]
	v_pk_fma_f32 v[0:1], v[24:25], v[26:27], v[10:11] op_sel_hi:[0,1,1] neg_lo:[0,0,1] neg_hi:[0,0,1]
	v_cvt_pk_bf16_f32 v36, v0, v1
	v_lshlrev_b32_e32 v12, 16, v149
	v_and_b32_e32 v13, 0xffff0000, v149
	v_cndmask_b32_e32 v35, v117, v85, vcc
	v_lshlrev_b32_e32 v0, 16, v35
	v_and_b32_e32 v1, 0xffff0000, v35
	v_pk_add_f32 v[0:1], v[12:13], v[0:1] neg_lo:[0,1] neg_hi:[0,1]
	v_pk_add_f32 v[28:29], v[28:29], v[0:1]
	v_pk_fma_f32 v[0:1], v[24:25], v[28:29], v[12:13] op_sel_hi:[0,1,1] neg_lo:[0,0,1] neg_hi:[0,0,1]
	v_cvt_pk_bf16_f32 v37, v0, v1
	v_lshlrev_b32_e32 v14, 16, v150
	v_and_b32_e32 v15, 0xffff0000, v150
	v_cndmask_b32_e32 v35, v118, v86, vcc
	v_lshlrev_b32_e32 v0, 16, v35
	v_and_b32_e32 v1, 0xffff0000, v35
	v_pk_add_f32 v[0:1], v[14:15], v[0:1] neg_lo:[0,1] neg_hi:[0,1]
	v_pk_add_f32 v[30:31], v[30:31], v[0:1]
	v_pk_fma_f32 v[0:1], v[24:25], v[30:31], v[14:15] op_sel_hi:[0,1,1] neg_lo:[0,0,1] neg_hi:[0,0,1]
	v_cvt_pk_bf16_f32 v38, v0, v1
	v_lshlrev_b32_e32 v22, 16, v151
	v_and_b32_e32 v23, 0xffff0000, v151
	v_cndmask_b32_e32 v35, v119, v87, vcc
	v_lshlrev_b32_e32 v0, 16, v35
	v_and_b32_e32 v1, 0xffff0000, v35
	v_pk_add_f32 v[0:1], v[22:23], v[0:1] neg_lo:[0,1] neg_hi:[0,1]
	v_pk_add_f32 v[8:9], v[8:9], v[0:1]
	v_pk_fma_f32 v[0:1], v[24:25], v[8:9], v[22:23] op_sel_hi:[0,1,1] neg_lo:[0,0,1] neg_hi:[0,0,1]
	v_cvt_pk_bf16_f32 v39, v0, v1
	v_lshl_add_u64 v[6:7], v[6:7], 0, s[16:17]
	global_store_dwordx4 v[6:7], v[36:39], off offset:-4096 nt
	s_waitcnt vmcnt(31)
; __device__ __forceinline__ unsigned cvtpk(float lo, float hi) { return pg8::cvt_pk_bf16(lo, hi); }
; __device__ __forceinline__ float bflo(unsigned u) { return __uint_as_float(u << 16); }
; __device__ __forceinline__ float bfhi(unsigned u) { return __uint_as_float(u & 0xffff0000u); }
; __device__ __forceinline__ void pool_pass(const bf16* __restrict__ U, bf16* __restrict__ Y, int gtid, int gthreads) {
;     ...
;         for (int t = t0; t < t0 + 32; ++t) {
;             const v4u v = *(const v4u*)(up + (size_t)t * 1024);
;             const int tb = t - w; v4u vb = {0u, 0u, 0u, 0u};
;             if (t > t0 && tb >= 0) vb = *(const v4u*)(up + (size_t)tb * 1024);
;             const float rc = 1.0f / (float)((t + 1 < w) ? (t + 1) : w);
;             v4u o;
; #pragma unroll
;             for (int j = 0; j < 4; ++j) { const float c0 = bflo(v[j]), c1 = bfhi(v[j]);
;                 sum[2 * j] += c0 - bflo(vb[j]); sum[2 * j + 1] += c1 - bfhi(vb[j]);
;                 o[j] = cvtpk(sum[2 * j] * rc - c0, sum[2 * j + 1] * rc - c1); }
;             __builtin_nontemporal_store(o, (v4u*)(yp + (size_t)t * 1024));
	v_lshlrev_b32_e32 v10, 16, v156
	v_and_b32_e32 v11, 0xffff0000, v156
	v_cndmask_b32_e32 v35, v120, v88, vcc
	v_lshlrev_b32_e32 v0, 16, v35
	v_and_b32_e32 v1, 0xffff0000, v35
	v_pk_add_f32 v[0:1], v[10:11], v[0:1] neg_lo:[0,1] neg_hi:[0,1]
	v_pk_add_f32 v[26:27], v[26:27], v[0:1]
	v_pk_fma_f32 v[0:1], v[24:25], v[26:27], v[10:11] op_sel_hi:[0,1,1] neg_lo:[0,0,1] neg_hi:[0,0,1]
	v_cvt_pk_bf16_f32 v36, v0, v1
	v_lshlrev_b32_e32 v12, 16, v157
	v_and_b32_e32 v13, 0xffff0000, v157
	v_cndmask_b32_e32 v35, v121, v89, vcc
	v_lshlrev_b32_e32 v0, 16, v35
	v_and_b32_e32 v1, 0xffff0000, v35
	v_pk_add_f32 v[0:1], v[12:13], v[0:1] neg_lo:[0,1] neg_hi:[0,1]
	v_pk_add_f32 v[28:29], v[28:29], v[0:1]
	v_pk_fma_f32 v[0:1], v[24:25], v[28:29], v[12:13] op_sel_hi:[0,1,1] neg_lo:[0,0,1] neg_hi:[0,0,1]
	v_cvt_pk_bf16_f32 v37, v0, v1
	v_lshlrev_b32_e32 v14, 16, v158
	v_and_b32_e32 v15, 0xffff0000, v158
	v_cndmask_b32_e32 v35, v122, v90, vcc
	v_lshlrev_b32_e32 v0, 16, v35
	v_and_b32_e32 v1, 0xffff0000, v35
	v_pk_add_f32 v[0:1], v[14:15], v[0:1] neg_lo:[0,1] neg_hi:[0,1]
	v_pk_add_f32 v[30:31], v[30:31], v[0:1]
	v_pk_fma_f32 v[0:1], v[24:25], v[30:31], v[14:15] op_sel_hi:[0,1,1] neg_lo:[0,0,1] neg_hi:[0,0,1]
	v_cvt_pk_bf16_f32 v38, v0, v1
	v_lshlrev_b32_e32 v22, 16, v159
	v_and_b32_e32 v23, 0xffff0000, v159
	v_cndmask_b32_e32 v35, v123, v91, vcc
	v_lshlrev_b32_e32 v0, 16, v35
	v_and_b32_e32 v1, 0xffff0000, v35
	v_pk_add_f32 v[0:1], v[22:23], v[0:1] neg_lo:[0,1] neg_hi:[0,1]
	v_pk_add_f32 v[8:9], v[8:9], v[0:1]
	v_pk_fma_f32 v[0:1], v[24:25], v[8:9], v[22:23] op_sel_hi:[0,1,1] neg_lo:[0,0,1] neg_hi:[0,0,1]
	v_cvt_pk_bf16_f32 v39, v0, v1
	global_store_dwordx4 v[6:7], v[36:39], off offset:-2048 nt
	s_waitcnt vmcnt(31)
	v_lshlrev_b32_e32 v10, 16, v160
	v_and_b32_e32 v11, 0xffff0000, v160
	v_cndmask_b32_e32 v35, v124, v92, vcc
	v_lshlrev_b32_e32 v0, 16, v35
	v_and_b32_e32 v1, 0xffff0000, v35
	v_pk_add_f32 v[0:1], v[10:11], v[0:1] neg_lo:[0,1] neg_hi:[0,1]
	v_pk_add_f32 v[26:27], v[26:27], v[0:1]
	v_pk_fma_f32 v[0:1], v[24:25], v[26:27], v[10:11] op_sel_hi:[0,1,1] neg_lo:[0,0,1] neg_hi:[0,0,1]
	v_cvt_pk_bf16_f32 v36, v0, v1
	v_lshlrev_b32_e32 v12, 16, v161
	v_and_b32_e32 v13, 0xffff0000, v161
	v_cndmask_b32_e32 v35, v125, v93, vcc
	v_lshlrev_b32_e32 v0, 16, v35
	v_and_b32_e32 v1, 0xffff0000, v35
	v_pk_add_f32 v[0:1], v[12:13], v[0:1] neg_lo:[0,1] neg_hi:[0,1]
	v_pk_add_f32 v[28:29], v[28:29], v[0:1]
	v_pk_fma_f32 v[0:1], v[24:25], v[28:29], v[12:13] op_sel_hi:[0,1,1] neg_lo:[0,0,1] neg_hi:[0,0,1]
	v_cvt_pk_bf16_f32 v37, v0, v1
	v_lshlrev_b32_e32 v14, 16, v162
	v_and_b32_e32 v15, 0xffff0000, v162
	v_cndmask_b32_e32 v35, v126, v94, vcc
	v_lshlrev_b32_e32 v0, 16, v35
	v_and_b32_e32 v1, 0xffff0000, v35
	v_pk_add_f32 v[0:1], v[14:15], v[0:1] neg_lo:[0,1] neg_hi:[0,1]
	v_pk_add_f32 v[30:31], v[30:31], v[0:1]
	v_pk_fma_f32 v[0:1], v[24:25], v[30:31], v[14:15] op_sel_hi:[0,1,1] neg_lo:[0,0,1] neg_hi:[0,0,1]
	v_cvt_pk_bf16_f32 v38, v0, v1
	v_lshlrev_b32_e32 v22, 16, v163
	v_and_b32_e32 v23, 0xffff0000, v163
	v_cndmask_b32_e32 v35, v127, v95, vcc
	v_lshlrev_b32_e32 v0, 16, v35
	v_and_b32_e32 v1, 0xffff0000, v35
	v_pk_add_f32 v[0:1], v[22:23], v[0:1] neg_lo:[0,1] neg_hi:[0,1]
	v_pk_add_f32 v[8:9], v[8:9], v[0:1]
	v_pk_fma_f32 v[0:1], v[24:25], v[8:9], v[22:23] op_sel_hi:[0,1,1] neg_lo:[0,0,1] neg_hi:[0,0,1]
	v_cvt_pk_bf16_f32 v39, v0, v1
	global_store_dwordx4 v[6:7], v[36:39], off nt
	s_waitcnt vmcnt(31)
	v_lshlrev_b32_e32 v10, 16, v164
	v_and_b32_e32 v11, 0xffff0000, v164
	v_cndmask_b32_e32 v35, v128, v96, vcc
	v_lshlrev_b32_e32 v0, 16, v35
	v_and_b32_e32 v1, 0xffff0000, v35
	v_pk_add_f32 v[0:1], v[10:11], v[0:1] neg_lo:[0,1] neg_hi:[0,1]
	v_pk_add_f32 v[26:27], v[26:27], v[0:1]
	v_pk_fma_f32 v[0:1], v[24:25], v[26:27], v[10:11] op_sel_hi:[0,1,1] neg_lo:[0,0,1] neg_hi:[0,0,1]
	v_cvt_pk_bf16_f32 v36, v0, v1
	v_lshlrev_b32_e32 v12, 16, v165
	v_and_b32_e32 v13, 0xffff0000, v165
	v_cndmask_b32_e32 v35, v129, v97, vcc
	v_lshlrev_b32_e32 v0, 16, v35
	v_and_b32_e32 v1, 0xffff0000, v35
	v_pk_add_f32 v[0:1], v[12:13], v[0:1] neg_lo:[0,1] neg_hi:[0,1]
	v_pk_add_f32 v[28:29], v[28:29], v[0:1]
	v_pk_fma_f32 v[0:1], v[24:25], v[28:29], v[12:13] op_sel_hi:[0,1,1] neg_lo:[0,0,1] neg_hi:[0,0,1]
	v_cvt_pk_bf16_f32 v37, v0, v1
	v_lshlrev_b32_e32 v14, 16, v166
	v_and_b32_e32 v15, 0xffff0000, v166
	v_cndmask_b32_e32 v35, v130, v98, vcc
	v_lshlrev_b32_e32 v0, 16, v35
	v_and_b32_e32 v1, 0xffff0000, v35
	v_pk_add_f32 v[0:1], v[14:15], v[0:1] neg_lo:[0,1] neg_hi:[0,1]
	v_pk_add_f32 v[30:31], v[30:31], v[0:1]
	v_pk_fma_f32 v[0:1], v[24:25], v[30:31], v[14:15] op_sel_hi:[0,1,1] neg_lo:[0,0,1] neg_hi:[0,0,1]
	v_cvt_pk_bf16_f32 v38, v0, v1
	v_lshlrev_b32_e32 v22, 16, v167
	v_and_b32_e32 v23, 0xffff0000, v167
	v_cndmask_b32_e32 v35, v131, v99, vcc
	v_lshlrev_b32_e32 v0, 16, v35
	v_and_b32_e32 v1, 0xffff0000, v35
	v_pk_add_f32 v[0:1], v[22:23], v[0:1] neg_lo:[0,1] neg_hi:[0,1]
	v_pk_add_f32 v[8:9], v[8:9], v[0:1]
	v_pk_fma_f32 v[0:1], v[24:25], v[8:9], v[22:23] op_sel_hi:[0,1,1] neg_lo:[0,0,1] neg_hi:[0,0,1]
	v_cvt_pk_bf16_f32 v39, v0, v1
	global_store_dwordx4 v[6:7], v[36:39], off offset:2048 nt
	s_waitcnt vmcnt(31)
; __device__ __forceinline__ unsigned cvtpk(float lo, float hi) { return pg8::cvt_pk_bf16(lo, hi); }
; __device__ __forceinline__ float bflo(unsigned u) { return __uint_as_float(u << 16); }
; __device__ __forceinline__ float bfhi(unsigned u) { return __uint_as_float(u & 0xffff0000u); }
; __device__ __forceinline__ void pool_pass(const bf16* __restrict__ U, bf16* __restrict__ Y, int gtid, int gthreads) {
;     ...
;         for (int t = t0; t < t0 + 32; ++t) {
;             const v4u v = *(const v4u*)(up + (size_t)t * 1024);
;             const int tb = t - w; v4u vb = {0u, 0u, 0u, 0u};
;             if (t > t0 && tb >= 0) vb = *(const v4u*)(up + (size_t)tb * 1024);
;             const float rc = 1.0f / (float)((t + 1 < w) ? (t + 1) : w);
;             v4u o;
; #pragma unroll
;             for (int j = 0; j < 4; ++j) { const float c0 = bflo(v[j]), c1 = bfhi(v[j]);
;                 sum[2 * j] += c0 - bflo(vb[j]); sum[2 * j + 1] += c1 - bfhi(vb[j]);
;                 o[j] = cvtpk(sum[2 * j] * rc - c0, sum[2 * j + 1] * rc - c1); }
;             __builtin_nontemporal_store(o, (v4u*)(yp + (size_t)t * 1024));
	v_lshlrev_b32_e32 v10, 16, v168
	v_and_b32_e32 v11, 0xffff0000, v168
	v_cndmask_b32_e32 v35, v132, v100, vcc
	v_lshlrev_b32_e32 v0, 16, v35
	v_and_b32_e32 v1, 0xffff0000, v35
	v_pk_add_f32 v[0:1], v[10:11], v[0:1] neg_lo:[0,1] neg_hi:[0,1]
	v_pk_add_f32 v[26:27], v[26:27], v[0:1]
	v_pk_fma_f32 v[0:1], v[24:25], v[26:27], v[10:11] op_sel_hi:[0,1,1] neg_lo:[0,0,1] neg_hi:[0,0,1]
	v_cvt_pk_bf16_f32 v36, v0, v1
	v_lshlrev_b32_e32 v12, 16, v169
	v_and_b32_e32 v13, 0xffff0000, v169
	v_cndmask_b32_e32 v35, v133, v101, vcc
	v_lshlrev_b32_e32 v0, 16, v35
	v_and_b32_e32 v1, 0xffff0000, v35
	v_pk_add_f32 v[0:1], v[12:13], v[0:1] neg_lo:[0,1] neg_hi:[0,1]
	v_pk_add_f32 v[28:29], v[28:29], v[0:1]
	v_pk_fma_f32 v[0:1], v[24:25], v[28:29], v[12:13] op_sel_hi:[0,1,1] neg_lo:[0,0,1] neg_hi:[0,0,1]
	v_cvt_pk_bf16_f32 v37, v0, v1
	v_lshlrev_b32_e32 v14, 16, v170
	v_and_b32_e32 v15, 0xffff0000, v170
	v_cndmask_b32_e32 v35, v134, v102, vcc
	v_lshlrev_b32_e32 v0, 16, v35
	v_and_b32_e32 v1, 0xffff0000, v35
	v_pk_add_f32 v[0:1], v[14:15], v[0:1] neg_lo:[0,1] neg_hi:[0,1]
	v_pk_add_f32 v[30:31], v[30:31], v[0:1]
	v_pk_fma_f32 v[0:1], v[24:25], v[30:31], v[14:15] op_sel_hi:[0,1,1] neg_lo:[0,0,1] neg_hi:[0,0,1]
	v_cvt_pk_bf16_f32 v38, v0, v1
	v_lshlrev_b32_e32 v22, 16, v171
	v_and_b32_e32 v23, 0xffff0000, v171
	v_cndmask_b32_e32 v35, v135, v103, vcc
	v_lshlrev_b32_e32 v0, 16, v35
	v_and_b32_e32 v1, 0xffff0000, v35
	v_pk_add_f32 v[0:1], v[22:23], v[0:1] neg_lo:[0,1] neg_hi:[0,1]
	v_pk_add_f32 v[8:9], v[8:9], v[0:1]
	v_pk_fma_f32 v[0:1], v[24:25], v[8:9], v[22:23] op_sel_hi:[0,1,1] neg_lo:[0,0,1] neg_hi:[0,0,1]
	v_cvt_pk_bf16_f32 v39, v0, v1
	v_lshl_add_u64 v[6:7], v[6:7], 0, s[16:17]
	global_store_dwordx4 v[6:7], v[36:39], off offset:-4096 nt
	s_waitcnt vmcnt(31)
	v_lshlrev_b32_e32 v10, 16, v172
	v_and_b32_e32 v11, 0xffff0000, v172
	v_cndmask_b32_e32 v35, v136, v104, vcc
	v_lshlrev_b32_e32 v0, 16, v35
	v_and_b32_e32 v1, 0xffff0000, v35
	v_pk_add_f32 v[0:1], v[10:11], v[0:1] neg_lo:[0,1] neg_hi:[0,1]
	v_pk_add_f32 v[26:27], v[26:27], v[0:1]
	v_pk_fma_f32 v[0:1], v[24:25], v[26:27], v[10:11] op_sel_hi:[0,1,1] neg_lo:[0,0,1] neg_hi:[0,0,1]
	v_cvt_pk_bf16_f32 v36, v0, v1
	v_lshlrev_b32_e32 v12, 16, v173
	v_and_b32_e32 v13, 0xffff0000, v173
	v_cndmask_b32_e32 v35, v137, v105, vcc
	v_lshlrev_b32_e32 v0, 16, v35
	v_and_b32_e32 v1, 0xffff0000, v35
	v_pk_add_f32 v[0:1], v[12:13], v[0:1] neg_lo:[0,1] neg_hi:[0,1]
	v_pk_add_f32 v[28:29], v[28:29], v[0:1]
	v_pk_fma_f32 v[0:1], v[24:25], v[28:29], v[12:13] op_sel_hi:[0,1,1] neg_lo:[0,0,1] neg_hi:[0,0,1]
	v_cvt_pk_bf16_f32 v37, v0, v1
	v_lshlrev_b32_e32 v14, 16, v174
	v_and_b32_e32 v15, 0xffff0000, v174
	v_cndmask_b32_e32 v35, v138, v106, vcc
	v_lshlrev_b32_e32 v0, 16, v35
	v_and_b32_e32 v1, 0xffff0000, v35
	v_pk_add_f32 v[0:1], v[14:15], v[0:1] neg_lo:[0,1] neg_hi:[0,1]
	v_pk_add_f32 v[30:31], v[30:31], v[0:1]
	v_pk_fma_f32 v[0:1], v[24:25], v[30:31], v[14:15] op_sel_hi:[0,1,1] neg_lo:[0,0,1] neg_hi:[0,0,1]
	v_cvt_pk_bf16_f32 v38, v0, v1
	v_lshlrev_b32_e32 v22, 16, v175
	v_and_b32_e32 v23, 0xffff0000, v175
	v_cndmask_b32_e32 v35, v139, v107, vcc
	v_lshlrev_b32_e32 v0, 16, v35
	v_and_b32_e32 v1, 0xffff0000, v35
	v_pk_add_f32 v[0:1], v[22:23], v[0:1] neg_lo:[0,1] neg_hi:[0,1]
	v_pk_add_f32 v[8:9], v[8:9], v[0:1]
	v_pk_fma_f32 v[0:1], v[24:25], v[8:9], v[22:23] op_sel_hi:[0,1,1] neg_lo:[0,0,1] neg_hi:[0,0,1]
	v_cvt_pk_bf16_f32 v39, v0, v1
	global_store_dwordx4 v[6:7], v[36:39], off offset:-2048 nt
	s_waitcnt vmcnt(31)
	v_lshlrev_b32_e32 v10, 16, v176
	v_and_b32_e32 v11, 0xffff0000, v176
	v_cndmask_b32_e32 v35, v140, v108, vcc
	v_lshlrev_b32_e32 v0, 16, v35
	v_and_b32_e32 v1, 0xffff0000, v35
	v_pk_add_f32 v[0:1], v[10:11], v[0:1] neg_lo:[0,1] neg_hi:[0,1]
	v_pk_add_f32 v[26:27], v[26:27], v[0:1]
	v_pk_fma_f32 v[0:1], v[24:25], v[26:27], v[10:11] op_sel_hi:[0,1,1] neg_lo:[0,0,1] neg_hi:[0,0,1]
	v_cvt_pk_bf16_f32 v36, v0, v1
	v_lshlrev_b32_e32 v12, 16, v177
	v_and_b32_e32 v13, 0xffff0000, v177
	v_cndmask_b32_e32 v35, v141, v109, vcc
	v_lshlrev_b32_e32 v0, 16, v35
	v_and_b32_e32 v1, 0xffff0000, v35
	v_pk_add_f32 v[0:1], v[12:13], v[0:1] neg_lo:[0,1] neg_hi:[0,1]
	v_pk_add_f32 v[28:29], v[28:29], v[0:1]
	v_pk_fma_f32 v[0:1], v[24:25], v[28:29], v[12:13] op_sel_hi:[0,1,1] neg_lo:[0,0,1] neg_hi:[0,0,1]
	v_cvt_pk_bf16_f32 v37, v0, v1
	v_lshlrev_b32_e32 v14, 16, v178
	v_and_b32_e32 v15, 0xffff0000, v178
	v_cndmask_b32_e32 v35, v142, v110, vcc
	v_lshlrev_b32_e32 v0, 16, v35
	v_and_b32_e32 v1, 0xffff0000, v35
	v_pk_add_f32 v[0:1], v[14:15], v[0:1] neg_lo:[0,1] neg_hi:[0,1]
	v_pk_add_f32 v[30:31], v[30:31], v[0:1]
	v_pk_fma_f32 v[0:1], v[24:25], v[30:31], v[14:15] op_sel_hi:[0,1,1] neg_lo:[0,0,1] neg_hi:[0,0,1]
	v_cvt_pk_bf16_f32 v38, v0, v1
	v_lshlrev_b32_e32 v22, 16, v179
	v_and_b32_e32 v23, 0xffff0000, v179
	v_cndmask_b32_e32 v35, v143, v111, vcc
	v_lshlrev_b32_e32 v0, 16, v35
	v_and_b32_e32 v1, 0xffff0000, v35
	v_pk_add_f32 v[0:1], v[22:23], v[0:1] neg_lo:[0,1] neg_hi:[0,1]
	v_pk_add_f32 v[8:9], v[8:9], v[0:1]
	v_pk_fma_f32 v[0:1], v[24:25], v[8:9], v[22:23] op_sel_hi:[0,1,1] neg_lo:[0,0,1] neg_hi:[0,0,1]
	v_cvt_pk_bf16_f32 v39, v0, v1
	global_store_dwordx4 v[6:7], v[36:39], off nt
	s_waitcnt vmcnt(31)
; __device__ __forceinline__ unsigned cvtpk(float lo, float hi) { return pg8::cvt_pk_bf16(lo, hi); }
; __device__ __forceinline__ float bflo(unsigned u) { return __uint_as_float(u << 16); }
; __device__ __forceinline__ float bfhi(unsigned u) { return __uint_as_float(u & 0xffff0000u); }
; __device__ __forceinline__ void pool_pass(const bf16* __restrict__ U, bf16* __restrict__ Y, int gtid, int gthreads) {
;     ...
;         for (int t = t0; t < t0 + 32; ++t) {
;             const v4u v = *(const v4u*)(up + (size_t)t * 1024);
;             const int tb = t - w; v4u vb = {0u, 0u, 0u, 0u};
;             if (t > t0 && tb >= 0) vb = *(const v4u*)(up + (size_t)tb * 1024);
;             const float rc = 1.0f / (float)((t + 1 < w) ? (t + 1) : w);
;             v4u o;
; #pragma unroll
;             for (int j = 0; j < 4; ++j) { const float c0 = bflo(v[j]), c1 = bfhi(v[j]);
;                 sum[2 * j] += c0 - bflo(vb[j]); sum[2 * j + 1] += c1 - bfhi(vb[j]);
;                 o[j] = cvtpk(sum[2 * j] * rc - c0, sum[2 * j + 1] * rc - c1); }
;             __builtin_nontemporal_store(o, (v4u*)(yp + (size_t)t * 1024));
	v_lshlrev_b32_e32 v10, 16, v180
	v_and_b32_e32 v11, 0xffff0000, v180
	v_cndmask_b32_e32 v35, v144, v112, vcc
	v_lshlrev_b32_e32 v0, 16, v35
	v_and_b32_e32 v1, 0xffff0000, v35
	v_pk_add_f32 v[0:1], v[10:11], v[0:1] neg_lo:[0,1] neg_hi:[0,1]
	v_pk_add_f32 v[26:27], v[26:27], v[0:1]
	v_pk_fma_f32 v[0:1], v[24:25], v[26:27], v[10:11] op_sel_hi:[0,1,1] neg_lo:[0,0,1] neg_hi:[0,0,1]
	v_cvt_pk_bf16_f32 v36, v0, v1
	v_lshlrev_b32_e32 v12, 16, v181
	v_and_b32_e32 v13, 0xffff0000, v181
	v_cndmask_b32_e32 v35, v145, v113, vcc
	v_lshlrev_b32_e32 v0, 16, v35
	v_and_b32_e32 v1, 0xffff0000, v35
	v_pk_add_f32 v[0:1], v[12:13], v[0:1] neg_lo:[0,1] neg_hi:[0,1]
	v_pk_add_f32 v[28:29], v[28:29], v[0:1]
	v_pk_fma_f32 v[0:1], v[24:25], v[28:29], v[12:13] op_sel_hi:[0,1,1] neg_lo:[0,0,1] neg_hi:[0,0,1]
	v_cvt_pk_bf16_f32 v37, v0, v1
	v_lshlrev_b32_e32 v14, 16, v182
	v_and_b32_e32 v15, 0xffff0000, v182
	v_cndmask_b32_e32 v35, v146, v114, vcc
	v_lshlrev_b32_e32 v0, 16, v35
	v_and_b32_e32 v1, 0xffff0000, v35
	v_pk_add_f32 v[0:1], v[14:15], v[0:1] neg_lo:[0,1] neg_hi:[0,1]
	v_pk_add_f32 v[30:31], v[30:31], v[0:1]
	v_pk_fma_f32 v[0:1], v[24:25], v[30:31], v[14:15] op_sel_hi:[0,1,1] neg_lo:[0,0,1] neg_hi:[0,0,1]
	v_cvt_pk_bf16_f32 v38, v0, v1
	v_lshlrev_b32_e32 v22, 16, v183
	v_and_b32_e32 v23, 0xffff0000, v183
	v_cndmask_b32_e32 v35, v147, v115, vcc
	v_lshlrev_b32_e32 v0, 16, v35
	v_and_b32_e32 v1, 0xffff0000, v35
	v_pk_add_f32 v[0:1], v[22:23], v[0:1] neg_lo:[0,1] neg_hi:[0,1]
	v_pk_add_f32 v[8:9], v[8:9], v[0:1]
	v_pk_fma_f32 v[0:1], v[24:25], v[8:9], v[22:23] op_sel_hi:[0,1,1] neg_lo:[0,0,1] neg_hi:[0,0,1]
	v_cvt_pk_bf16_f32 v39, v0, v1
	global_store_dwordx4 v[6:7], v[36:39], off offset:2048 nt
	s_waitcnt vmcnt(31)
	v_lshlrev_b32_e32 v10, 16, v184
	v_and_b32_e32 v11, 0xffff0000, v184
	v_cndmask_b32_e32 v35, v148, v116, vcc
	v_lshlrev_b32_e32 v0, 16, v35
	v_and_b32_e32 v1, 0xffff0000, v35
	v_pk_add_f32 v[0:1], v[10:11], v[0:1] neg_lo:[0,1] neg_hi:[0,1]
	v_pk_add_f32 v[26:27], v[26:27], v[0:1]
	v_pk_fma_f32 v[0:1], v[24:25], v[26:27], v[10:11] op_sel_hi:[0,1,1] neg_lo:[0,0,1] neg_hi:[0,0,1]
	v_cvt_pk_bf16_f32 v36, v0, v1
	v_lshlrev_b32_e32 v12, 16, v185
	v_and_b32_e32 v13, 0xffff0000, v185
	v_cndmask_b32_e32 v35, v149, v117, vcc
	v_lshlrev_b32_e32 v0, 16, v35
	v_and_b32_e32 v1, 0xffff0000, v35
	v_pk_add_f32 v[0:1], v[12:13], v[0:1] neg_lo:[0,1] neg_hi:[0,1]
	v_pk_add_f32 v[28:29], v[28:29], v[0:1]
	v_pk_fma_f32 v[0:1], v[24:25], v[28:29], v[12:13] op_sel_hi:[0,1,1] neg_lo:[0,0,1] neg_hi:[0,0,1]
	v_cvt_pk_bf16_f32 v37, v0, v1
	v_lshlrev_b32_e32 v14, 16, v186
	v_and_b32_e32 v15, 0xffff0000, v186
	v_cndmask_b32_e32 v35, v150, v118, vcc
	v_lshlrev_b32_e32 v0, 16, v35
	v_and_b32_e32 v1, 0xffff0000, v35
	v_pk_add_f32 v[0:1], v[14:15], v[0:1] neg_lo:[0,1] neg_hi:[0,1]
	v_pk_add_f32 v[30:31], v[30:31], v[0:1]
	v_pk_fma_f32 v[0:1], v[24:25], v[30:31], v[14:15] op_sel_hi:[0,1,1] neg_lo:[0,0,1] neg_hi:[0,0,1]
	v_cvt_pk_bf16_f32 v38, v0, v1
	v_lshlrev_b32_e32 v22, 16, v187
	v_and_b32_e32 v23, 0xffff0000, v187
	v_cndmask_b32_e32 v35, v151, v119, vcc
	v_lshlrev_b32_e32 v0, 16, v35
	v_and_b32_e32 v1, 0xffff0000, v35
	v_pk_add_f32 v[0:1], v[22:23], v[0:1] neg_lo:[0,1] neg_hi:[0,1]
	v_pk_add_f32 v[8:9], v[8:9], v[0:1]
	v_pk_fma_f32 v[0:1], v[24:25], v[8:9], v[22:23] op_sel_hi:[0,1,1] neg_lo:[0,0,1] neg_hi:[0,0,1]
	v_cvt_pk_bf16_f32 v39, v0, v1
	v_lshl_add_u64 v[6:7], v[6:7], 0, s[16:17]
	global_store_dwordx4 v[6:7], v[36:39], off offset:-4096 nt
	s_waitcnt vmcnt(31)
	v_lshlrev_b32_e32 v10, 16, v188
	v_and_b32_e32 v11, 0xffff0000, v188
	v_cndmask_b32_e32 v35, v156, v120, vcc
	v_lshlrev_b32_e32 v0, 16, v35
	v_and_b32_e32 v1, 0xffff0000, v35
	v_pk_add_f32 v[0:1], v[10:11], v[0:1] neg_lo:[0,1] neg_hi:[0,1]
	v_pk_add_f32 v[26:27], v[26:27], v[0:1]
	v_pk_fma_f32 v[0:1], v[24:25], v[26:27], v[10:11] op_sel_hi:[0,1,1] neg_lo:[0,0,1] neg_hi:[0,0,1]
	v_cvt_pk_bf16_f32 v36, v0, v1
	v_lshlrev_b32_e32 v12, 16, v189
	v_and_b32_e32 v13, 0xffff0000, v189
	v_cndmask_b32_e32 v35, v157, v121, vcc
	v_lshlrev_b32_e32 v0, 16, v35
	v_and_b32_e32 v1, 0xffff0000, v35
	v_pk_add_f32 v[0:1], v[12:13], v[0:1] neg_lo:[0,1] neg_hi:[0,1]
	v_pk_add_f32 v[28:29], v[28:29], v[0:1]
	v_pk_fma_f32 v[0:1], v[24:25], v[28:29], v[12:13] op_sel_hi:[0,1,1] neg_lo:[0,0,1] neg_hi:[0,0,1]
	v_cvt_pk_bf16_f32 v37, v0, v1
	v_lshlrev_b32_e32 v14, 16, v190
	v_and_b32_e32 v15, 0xffff0000, v190
	v_cndmask_b32_e32 v35, v158, v122, vcc
	v_lshlrev_b32_e32 v0, 16, v35
	v_and_b32_e32 v1, 0xffff0000, v35
	v_pk_add_f32 v[0:1], v[14:15], v[0:1] neg_lo:[0,1] neg_hi:[0,1]
	v_pk_add_f32 v[30:31], v[30:31], v[0:1]
	v_pk_fma_f32 v[0:1], v[24:25], v[30:31], v[14:15] op_sel_hi:[0,1,1] neg_lo:[0,0,1] neg_hi:[0,0,1]
	v_cvt_pk_bf16_f32 v38, v0, v1
	v_lshlrev_b32_e32 v22, 16, v191
	v_and_b32_e32 v23, 0xffff0000, v191
	v_cndmask_b32_e32 v35, v159, v123, vcc
	v_lshlrev_b32_e32 v0, 16, v35
	v_and_b32_e32 v1, 0xffff0000, v35
	v_pk_add_f32 v[0:1], v[22:23], v[0:1] neg_lo:[0,1] neg_hi:[0,1]
	v_pk_add_f32 v[8:9], v[8:9], v[0:1]
	v_pk_fma_f32 v[0:1], v[24:25], v[8:9], v[22:23] op_sel_hi:[0,1,1] neg_lo:[0,0,1] neg_hi:[0,0,1]
	v_cvt_pk_bf16_f32 v39, v0, v1
	global_store_dwordx4 v[6:7], v[36:39], off offset:-2048 nt
	s_waitcnt vmcnt(31)
; __device__ __forceinline__ unsigned cvtpk(float lo, float hi) { return pg8::cvt_pk_bf16(lo, hi); }
; __device__ __forceinline__ float bflo(unsigned u) { return __uint_as_float(u << 16); }
; __device__ __forceinline__ float bfhi(unsigned u) { return __uint_as_float(u & 0xffff0000u); }
; __device__ __forceinline__ void pool_pass(const bf16* __restrict__ U, bf16* __restrict__ Y, int gtid, int gthreads) {
;     ...
;         for (int t = t0; t < t0 + 32; ++t) {
;             const v4u v = *(const v4u*)(up + (size_t)t * 1024);
;             const int tb = t - w; v4u vb = {0u, 0u, 0u, 0u};
;             if (t > t0 && tb >= 0) vb = *(const v4u*)(up + (size_t)tb * 1024);
;             const float rc = 1.0f / (float)((t + 1 < w) ? (t + 1) : w);
;             v4u o;
; #pragma unroll
;             for (int j = 0; j < 4; ++j) { const float c0 = bflo(v[j]), c1 = bfhi(v[j]);
;                 sum[2 * j] += c0 - bflo(vb[j]); sum[2 * j + 1] += c1 - bfhi(vb[j]);
;                 o[j] = cvtpk(sum[2 * j] * rc - c0, sum[2 * j + 1] * rc - c1); }
;             __builtin_nontemporal_store(o, (v4u*)(yp + (size_t)t * 1024));
	v_lshlrev_b32_e32 v10, 16, v192
	v_and_b32_e32 v11, 0xffff0000, v192
	v_cndmask_b32_e32 v35, v160, v124, vcc
	v_lshlrev_b32_e32 v0, 16, v35
	v_and_b32_e32 v1, 0xffff0000, v35
	v_pk_add_f32 v[0:1], v[10:11], v[0:1] neg_lo:[0,1] neg_hi:[0,1]
	v_pk_add_f32 v[26:27], v[26:27], v[0:1]
	v_pk_fma_f32 v[0:1], v[24:25], v[26:27], v[10:11] op_sel_hi:[0,1,1] neg_lo:[0,0,1] neg_hi:[0,0,1]
	v_cvt_pk_bf16_f32 v36, v0, v1
	v_lshlrev_b32_e32 v12, 16, v193
	v_and_b32_e32 v13, 0xffff0000, v193
	v_cndmask_b32_e32 v35, v161, v125, vcc
	v_lshlrev_b32_e32 v0, 16, v35
	v_and_b32_e32 v1, 0xffff0000, v35
	v_pk_add_f32 v[0:1], v[12:13], v[0:1] neg_lo:[0,1] neg_hi:[0,1]
	v_pk_add_f32 v[28:29], v[28:29], v[0:1]
	v_pk_fma_f32 v[0:1], v[24:25], v[28:29], v[12:13] op_sel_hi:[0,1,1] neg_lo:[0,0,1] neg_hi:[0,0,1]
	v_cvt_pk_bf16_f32 v37, v0, v1
	v_lshlrev_b32_e32 v14, 16, v194
	v_and_b32_e32 v15, 0xffff0000, v194
	v_cndmask_b32_e32 v35, v162, v126, vcc
	v_lshlrev_b32_e32 v0, 16, v35
	v_and_b32_e32 v1, 0xffff0000, v35
	v_pk_add_f32 v[0:1], v[14:15], v[0:1] neg_lo:[0,1] neg_hi:[0,1]
	v_pk_add_f32 v[30:31], v[30:31], v[0:1]
	v_pk_fma_f32 v[0:1], v[24:25], v[30:31], v[14:15] op_sel_hi:[0,1,1] neg_lo:[0,0,1] neg_hi:[0,0,1]
	v_cvt_pk_bf16_f32 v38, v0, v1
	v_lshlrev_b32_e32 v22, 16, v195
	v_and_b32_e32 v23, 0xffff0000, v195
	v_cndmask_b32_e32 v35, v163, v127, vcc
	v_lshlrev_b32_e32 v0, 16, v35
	v_and_b32_e32 v1, 0xffff0000, v35
	v_pk_add_f32 v[0:1], v[22:23], v[0:1] neg_lo:[0,1] neg_hi:[0,1]
	v_pk_add_f32 v[8:9], v[8:9], v[0:1]
	v_pk_fma_f32 v[0:1], v[24:25], v[8:9], v[22:23] op_sel_hi:[0,1,1] neg_lo:[0,0,1] neg_hi:[0,0,1]
	v_cvt_pk_bf16_f32 v39, v0, v1
	global_store_dwordx4 v[6:7], v[36:39], off nt
	s_waitcnt vmcnt(31)
	v_lshlrev_b32_e32 v10, 16, v196
	v_and_b32_e32 v11, 0xffff0000, v196
	v_cndmask_b32_e32 v35, v164, v128, vcc
	v_lshlrev_b32_e32 v0, 16, v35
	v_and_b32_e32 v1, 0xffff0000, v35
	v_pk_add_f32 v[0:1], v[10:11], v[0:1] neg_lo:[0,1] neg_hi:[0,1]
	v_pk_add_f32 v[26:27], v[26:27], v[0:1]
	v_pk_fma_f32 v[0:1], v[24:25], v[26:27], v[10:11] op_sel_hi:[0,1,1] neg_lo:[0,0,1] neg_hi:[0,0,1]
	v_cvt_pk_bf16_f32 v36, v0, v1
	v_lshlrev_b32_e32 v12, 16, v197
	v_and_b32_e32 v13, 0xffff0000, v197
	v_cndmask_b32_e32 v35, v165, v129, vcc
	v_lshlrev_b32_e32 v0, 16, v35
	v_and_b32_e32 v1, 0xffff0000, v35
	v_pk_add_f32 v[0:1], v[12:13], v[0:1] neg_lo:[0,1] neg_hi:[0,1]
	v_pk_add_f32 v[28:29], v[28:29], v[0:1]
	v_pk_fma_f32 v[0:1], v[24:25], v[28:29], v[12:13] op_sel_hi:[0,1,1] neg_lo:[0,0,1] neg_hi:[0,0,1]
	v_cvt_pk_bf16_f32 v37, v0, v1
	v_lshlrev_b32_e32 v14, 16, v198
	v_and_b32_e32 v15, 0xffff0000, v198
	v_cndmask_b32_e32 v35, v166, v130, vcc
	v_lshlrev_b32_e32 v0, 16, v35
	v_and_b32_e32 v1, 0xffff0000, v35
	v_pk_add_f32 v[0:1], v[14:15], v[0:1] neg_lo:[0,1] neg_hi:[0,1]
	v_pk_add_f32 v[30:31], v[30:31], v[0:1]
	v_pk_fma_f32 v[0:1], v[24:25], v[30:31], v[14:15] op_sel_hi:[0,1,1] neg_lo:[0,0,1] neg_hi:[0,0,1]
	v_cvt_pk_bf16_f32 v38, v0, v1
	v_lshlrev_b32_e32 v22, 16, v199
	v_and_b32_e32 v23, 0xffff0000, v199
	v_cndmask_b32_e32 v35, v167, v131, vcc
	v_lshlrev_b32_e32 v0, 16, v35
	v_and_b32_e32 v1, 0xffff0000, v35
	v_pk_add_f32 v[0:1], v[22:23], v[0:1] neg_lo:[0,1] neg_hi:[0,1]
	v_pk_add_f32 v[8:9], v[8:9], v[0:1]
	v_pk_fma_f32 v[0:1], v[24:25], v[8:9], v[22:23] op_sel_hi:[0,1,1] neg_lo:[0,0,1] neg_hi:[0,0,1]
	v_cvt_pk_bf16_f32 v39, v0, v1
	global_store_dwordx4 v[6:7], v[36:39], off offset:2048 nt
	s_waitcnt vmcnt(31)
	v_lshlrev_b32_e32 v10, 16, v200
	v_and_b32_e32 v11, 0xffff0000, v200
	v_cndmask_b32_e32 v35, v168, v132, vcc
	v_lshlrev_b32_e32 v0, 16, v35
	v_and_b32_e32 v1, 0xffff0000, v35
	v_pk_add_f32 v[0:1], v[10:11], v[0:1] neg_lo:[0,1] neg_hi:[0,1]
	v_pk_add_f32 v[26:27], v[26:27], v[0:1]
	v_pk_fma_f32 v[0:1], v[24:25], v[26:27], v[10:11] op_sel_hi:[0,1,1] neg_lo:[0,0,1] neg_hi:[0,0,1]
	v_cvt_pk_bf16_f32 v36, v0, v1
	v_lshlrev_b32_e32 v12, 16, v201
	v_and_b32_e32 v13, 0xffff0000, v201
	v_cndmask_b32_e32 v35, v169, v133, vcc
	v_lshlrev_b32_e32 v0, 16, v35
	v_and_b32_e32 v1, 0xffff0000, v35
	v_pk_add_f32 v[0:1], v[12:13], v[0:1] neg_lo:[0,1] neg_hi:[0,1]
	v_pk_add_f32 v[28:29], v[28:29], v[0:1]
	v_pk_fma_f32 v[0:1], v[24:25], v[28:29], v[12:13] op_sel_hi:[0,1,1] neg_lo:[0,0,1] neg_hi:[0,0,1]
	v_cvt_pk_bf16_f32 v37, v0, v1
	v_lshlrev_b32_e32 v14, 16, v202
	v_and_b32_e32 v15, 0xffff0000, v202
	v_cndmask_b32_e32 v35, v170, v134, vcc
	v_lshlrev_b32_e32 v0, 16, v35
	v_and_b32_e32 v1, 0xffff0000, v35
	v_pk_add_f32 v[0:1], v[14:15], v[0:1] neg_lo:[0,1] neg_hi:[0,1]
	v_pk_add_f32 v[30:31], v[30:31], v[0:1]
	v_pk_fma_f32 v[0:1], v[24:25], v[30:31], v[14:15] op_sel_hi:[0,1,1] neg_lo:[0,0,1] neg_hi:[0,0,1]
	v_cvt_pk_bf16_f32 v38, v0, v1
	v_lshlrev_b32_e32 v22, 16, v203
	v_and_b32_e32 v23, 0xffff0000, v203
	v_cndmask_b32_e32 v35, v171, v135, vcc
	v_lshlrev_b32_e32 v0, 16, v35
	v_and_b32_e32 v1, 0xffff0000, v35
	v_pk_add_f32 v[0:1], v[22:23], v[0:1] neg_lo:[0,1] neg_hi:[0,1]
	v_pk_add_f32 v[8:9], v[8:9], v[0:1]
	v_pk_fma_f32 v[0:1], v[24:25], v[8:9], v[22:23] op_sel_hi:[0,1,1] neg_lo:[0,0,1] neg_hi:[0,0,1]
	v_cvt_pk_bf16_f32 v39, v0, v1
	v_lshl_add_u64 v[6:7], v[6:7], 0, s[16:17]
	global_store_dwordx4 v[6:7], v[36:39], off offset:-4096 nt
	s_waitcnt vmcnt(31)
; __device__ __forceinline__ unsigned cvtpk(float lo, float hi) { return pg8::cvt_pk_bf16(lo, hi); }
; __device__ __forceinline__ float bflo(unsigned u) { return __uint_as_float(u << 16); }
; __device__ __forceinline__ float bfhi(unsigned u) { return __uint_as_float(u & 0xffff0000u); }
; __device__ __forceinline__ void pool_pass(const bf16* __restrict__ U, bf16* __restrict__ Y, int gtid, int gthreads) {
;     ...
;         for (int t = t0; t < t0 + 32; ++t) {
;             const v4u v = *(const v4u*)(up + (size_t)t * 1024);
;             const int tb = t - w; v4u vb = {0u, 0u, 0u, 0u};
;             if (t > t0 && tb >= 0) vb = *(const v4u*)(up + (size_t)tb * 1024);
;             const float rc = 1.0f / (float)((t + 1 < w) ? (t + 1) : w);
;             v4u o;
; #pragma unroll
;             for (int j = 0; j < 4; ++j) { const float c0 = bflo(v[j]), c1 = bfhi(v[j]);
;                 sum[2 * j] += c0 - bflo(vb[j]); sum[2 * j + 1] += c1 - bfhi(vb[j]);
;                 o[j] = cvtpk(sum[2 * j] * rc - c0, sum[2 * j + 1] * rc - c1); }
;             __builtin_nontemporal_store(o, (v4u*)(yp + (size_t)t * 1024));
	v_lshlrev_b32_e32 v10, 16, v204
	v_and_b32_e32 v11, 0xffff0000, v204
	v_cndmask_b32_e32 v35, v172, v136, vcc
	v_lshlrev_b32_e32 v0, 16, v35
	v_and_b32_e32 v1, 0xffff0000, v35
	v_pk_add_f32 v[0:1], v[10:11], v[0:1] neg_lo:[0,1] neg_hi:[0,1]
	v_pk_add_f32 v[26:27], v[26:27], v[0:1]
	v_pk_fma_f32 v[0:1], v[24:25], v[26:27], v[10:11] op_sel_hi:[0,1,1] neg_lo:[0,0,1] neg_hi:[0,0,1]
	v_cvt_pk_bf16_f32 v36, v0, v1
	v_lshlrev_b32_e32 v12, 16, v205
	v_and_b32_e32 v13, 0xffff0000, v205
	v_cndmask_b32_e32 v35, v173, v137, vcc
	v_lshlrev_b32_e32 v0, 16, v35
	v_and_b32_e32 v1, 0xffff0000, v35
	v_pk_add_f32 v[0:1], v[12:13], v[0:1] neg_lo:[0,1] neg_hi:[0,1]
	v_pk_add_f32 v[28:29], v[28:29], v[0:1]
	v_pk_fma_f32 v[0:1], v[24:25], v[28:29], v[12:13] op_sel_hi:[0,1,1] neg_lo:[0,0,1] neg_hi:[0,0,1]
	v_cvt_pk_bf16_f32 v37, v0, v1
	v_lshlrev_b32_e32 v14, 16, v206
	v_and_b32_e32 v15, 0xffff0000, v206
	v_cndmask_b32_e32 v35, v174, v138, vcc
	v_lshlrev_b32_e32 v0, 16, v35
	v_and_b32_e32 v1, 0xffff0000, v35
	v_pk_add_f32 v[0:1], v[14:15], v[0:1] neg_lo:[0,1] neg_hi:[0,1]
	v_pk_add_f32 v[30:31], v[30:31], v[0:1]
	v_pk_fma_f32 v[0:1], v[24:25], v[30:31], v[14:15] op_sel_hi:[0,1,1] neg_lo:[0,0,1] neg_hi:[0,0,1]
	v_cvt_pk_bf16_f32 v38, v0, v1
	v_lshlrev_b32_e32 v22, 16, v207
	v_and_b32_e32 v23, 0xffff0000, v207
	v_cndmask_b32_e32 v35, v175, v139, vcc
	v_lshlrev_b32_e32 v0, 16, v35
	v_and_b32_e32 v1, 0xffff0000, v35
	v_pk_add_f32 v[0:1], v[22:23], v[0:1] neg_lo:[0,1] neg_hi:[0,1]
	v_pk_add_f32 v[8:9], v[8:9], v[0:1]
	v_pk_fma_f32 v[0:1], v[24:25], v[8:9], v[22:23] op_sel_hi:[0,1,1] neg_lo:[0,0,1] neg_hi:[0,0,1]
	v_cvt_pk_bf16_f32 v39, v0, v1
	global_store_dwordx4 v[6:7], v[36:39], off offset:-2048 nt
	s_waitcnt vmcnt(31)
	v_lshlrev_b32_e32 v10, 16, v208
	v_and_b32_e32 v11, 0xffff0000, v208
	v_cndmask_b32_e32 v35, v176, v140, vcc
	v_lshlrev_b32_e32 v0, 16, v35
	v_and_b32_e32 v1, 0xffff0000, v35
	v_pk_add_f32 v[0:1], v[10:11], v[0:1] neg_lo:[0,1] neg_hi:[0,1]
	v_pk_add_f32 v[26:27], v[26:27], v[0:1]
	v_pk_fma_f32 v[0:1], v[24:25], v[26:27], v[10:11] op_sel_hi:[0,1,1] neg_lo:[0,0,1] neg_hi:[0,0,1]
	v_cvt_pk_bf16_f32 v36, v0, v1
	v_lshlrev_b32_e32 v12, 16, v209
	v_and_b32_e32 v13, 0xffff0000, v209
	v_cndmask_b32_e32 v35, v177, v141, vcc
	v_lshlrev_b32_e32 v0, 16, v35
	v_and_b32_e32 v1, 0xffff0000, v35
	v_pk_add_f32 v[0:1], v[12:13], v[0:1] neg_lo:[0,1] neg_hi:[0,1]
	v_pk_add_f32 v[28:29], v[28:29], v[0:1]
	v_pk_fma_f32 v[0:1], v[24:25], v[28:29], v[12:13] op_sel_hi:[0,1,1] neg_lo:[0,0,1] neg_hi:[0,0,1]
	v_cvt_pk_bf16_f32 v37, v0, v1
	v_lshlrev_b32_e32 v14, 16, v210
	v_and_b32_e32 v15, 0xffff0000, v210
	v_cndmask_b32_e32 v35, v178, v142, vcc
	v_lshlrev_b32_e32 v0, 16, v35
	v_and_b32_e32 v1, 0xffff0000, v35
	v_pk_add_f32 v[0:1], v[14:15], v[0:1] neg_lo:[0,1] neg_hi:[0,1]
	v_pk_add_f32 v[30:31], v[30:31], v[0:1]
	v_pk_fma_f32 v[0:1], v[24:25], v[30:31], v[14:15] op_sel_hi:[0,1,1] neg_lo:[0,0,1] neg_hi:[0,0,1]
	v_cvt_pk_bf16_f32 v38, v0, v1
	v_lshlrev_b32_e32 v22, 16, v211
	v_and_b32_e32 v23, 0xffff0000, v211
	v_cndmask_b32_e32 v35, v179, v143, vcc
	v_lshlrev_b32_e32 v0, 16, v35
	v_and_b32_e32 v1, 0xffff0000, v35
	v_pk_add_f32 v[0:1], v[22:23], v[0:1] neg_lo:[0,1] neg_hi:[0,1]
	v_pk_add_f32 v[8:9], v[8:9], v[0:1]
	v_pk_fma_f32 v[0:1], v[24:25], v[8:9], v[22:23] op_sel_hi:[0,1,1] neg_lo:[0,0,1] neg_hi:[0,0,1]
	v_cvt_pk_bf16_f32 v39, v0, v1
	global_store_dwordx4 v[6:7], v[36:39], off nt
	s_waitcnt vmcnt(31)
	v_lshlrev_b32_e32 v10, 16, v212
	v_and_b32_e32 v11, 0xffff0000, v212
	v_cndmask_b32_e32 v35, v180, v144, vcc
	v_lshlrev_b32_e32 v0, 16, v35
	v_and_b32_e32 v1, 0xffff0000, v35
	v_pk_add_f32 v[0:1], v[10:11], v[0:1] neg_lo:[0,1] neg_hi:[0,1]
	v_pk_add_f32 v[26:27], v[26:27], v[0:1]
	v_pk_fma_f32 v[0:1], v[24:25], v[26:27], v[10:11] op_sel_hi:[0,1,1] neg_lo:[0,0,1] neg_hi:[0,0,1]
	v_cvt_pk_bf16_f32 v36, v0, v1
	v_lshlrev_b32_e32 v12, 16, v213
	v_and_b32_e32 v13, 0xffff0000, v213
	v_cndmask_b32_e32 v35, v181, v145, vcc
	v_lshlrev_b32_e32 v0, 16, v35
	v_and_b32_e32 v1, 0xffff0000, v35
	v_pk_add_f32 v[0:1], v[12:13], v[0:1] neg_lo:[0,1] neg_hi:[0,1]
	v_pk_add_f32 v[28:29], v[28:29], v[0:1]
	v_pk_fma_f32 v[0:1], v[24:25], v[28:29], v[12:13] op_sel_hi:[0,1,1] neg_lo:[0,0,1] neg_hi:[0,0,1]
	v_cvt_pk_bf16_f32 v37, v0, v1
	v_lshlrev_b32_e32 v14, 16, v214
	v_and_b32_e32 v15, 0xffff0000, v214
	v_cndmask_b32_e32 v35, v182, v146, vcc
	v_lshlrev_b32_e32 v0, 16, v35
	v_and_b32_e32 v1, 0xffff0000, v35
	v_pk_add_f32 v[0:1], v[14:15], v[0:1] neg_lo:[0,1] neg_hi:[0,1]
	v_pk_add_f32 v[30:31], v[30:31], v[0:1]
	v_pk_fma_f32 v[0:1], v[24:25], v[30:31], v[14:15] op_sel_hi:[0,1,1] neg_lo:[0,0,1] neg_hi:[0,0,1]
	v_cvt_pk_bf16_f32 v38, v0, v1
	v_lshlrev_b32_e32 v22, 16, v215
	v_and_b32_e32 v23, 0xffff0000, v215
	v_cndmask_b32_e32 v35, v183, v147, vcc
	v_lshlrev_b32_e32 v0, 16, v35
	v_and_b32_e32 v1, 0xffff0000, v35
	v_pk_add_f32 v[0:1], v[22:23], v[0:1] neg_lo:[0,1] neg_hi:[0,1]
	v_pk_add_f32 v[8:9], v[8:9], v[0:1]
	v_pk_fma_f32 v[0:1], v[24:25], v[8:9], v[22:23] op_sel_hi:[0,1,1] neg_lo:[0,0,1] neg_hi:[0,0,1]
	v_cvt_pk_bf16_f32 v39, v0, v1
	global_store_dwordx4 v[6:7], v[36:39], off offset:2048 nt
	s_waitcnt vmcnt(31)
; __device__ __forceinline__ unsigned cvtpk(float lo, float hi) { return pg8::cvt_pk_bf16(lo, hi); }
; __device__ __forceinline__ float bflo(unsigned u) { return __uint_as_float(u << 16); }
; __device__ __forceinline__ float bfhi(unsigned u) { return __uint_as_float(u & 0xffff0000u); }
; __device__ __forceinline__ void pool_pass(const bf16* __restrict__ U, bf16* __restrict__ Y, int gtid, int gthreads) {
;     ...
;         for (int t = t0; t < t0 + 32; ++t) {
;             const v4u v = *(const v4u*)(up + (size_t)t * 1024);
;             const int tb = t - w; v4u vb = {0u, 0u, 0u, 0u};
;             if (t > t0 && tb >= 0) vb = *(const v4u*)(up + (size_t)tb * 1024);
;             const float rc = 1.0f / (float)((t + 1 < w) ? (t + 1) : w);
;             v4u o;
; #pragma unroll
;             for (int j = 0; j < 4; ++j) { const float c0 = bflo(v[j]), c1 = bfhi(v[j]);
;                 sum[2 * j] += c0 - bflo(vb[j]); sum[2 * j + 1] += c1 - bfhi(vb[j]);
;                 o[j] = cvtpk(sum[2 * j] * rc - c0, sum[2 * j + 1] * rc - c1); }
;             __builtin_nontemporal_store(o, (v4u*)(yp + (size_t)t * 1024));
;         }
;     }
	v_lshlrev_b32_e32 v10, 16, v216
	v_and_b32_e32 v11, 0xffff0000, v216
	v_cndmask_b32_e32 v35, v184, v148, vcc
	v_lshlrev_b32_e32 v0, 16, v35
	v_and_b32_e32 v1, 0xffff0000, v35
	v_pk_add_f32 v[0:1], v[10:11], v[0:1] neg_lo:[0,1] neg_hi:[0,1]
	v_pk_add_f32 v[26:27], v[26:27], v[0:1]
	v_pk_fma_f32 v[0:1], v[24:25], v[26:27], v[10:11] op_sel_hi:[0,1,1] neg_lo:[0,0,1] neg_hi:[0,0,1]
	v_cvt_pk_bf16_f32 v36, v0, v1
	v_lshlrev_b32_e32 v12, 16, v217
	v_and_b32_e32 v13, 0xffff0000, v217
	v_cndmask_b32_e32 v35, v185, v149, vcc
	v_lshlrev_b32_e32 v0, 16, v35
	v_and_b32_e32 v1, 0xffff0000, v35
	v_pk_add_f32 v[0:1], v[12:13], v[0:1] neg_lo:[0,1] neg_hi:[0,1]
	v_pk_add_f32 v[28:29], v[28:29], v[0:1]
	v_pk_fma_f32 v[0:1], v[24:25], v[28:29], v[12:13] op_sel_hi:[0,1,1] neg_lo:[0,0,1] neg_hi:[0,0,1]
	v_cvt_pk_bf16_f32 v37, v0, v1
	v_lshlrev_b32_e32 v14, 16, v218
	v_and_b32_e32 v15, 0xffff0000, v218
	v_cndmask_b32_e32 v35, v186, v150, vcc
	v_lshlrev_b32_e32 v0, 16, v35
	v_and_b32_e32 v1, 0xffff0000, v35
	v_pk_add_f32 v[0:1], v[14:15], v[0:1] neg_lo:[0,1] neg_hi:[0,1]
	v_pk_add_f32 v[30:31], v[30:31], v[0:1]
	v_pk_fma_f32 v[0:1], v[24:25], v[30:31], v[14:15] op_sel_hi:[0,1,1] neg_lo:[0,0,1] neg_hi:[0,0,1]
	v_cvt_pk_bf16_f32 v38, v0, v1
	v_lshlrev_b32_e32 v22, 16, v219
	v_and_b32_e32 v23, 0xffff0000, v219
	v_cndmask_b32_e32 v35, v187, v151, vcc
	v_lshlrev_b32_e32 v0, 16, v35
	v_and_b32_e32 v1, 0xffff0000, v35
	v_pk_add_f32 v[0:1], v[22:23], v[0:1] neg_lo:[0,1] neg_hi:[0,1]
	v_pk_add_f32 v[8:9], v[8:9], v[0:1]
	v_pk_fma_f32 v[0:1], v[24:25], v[8:9], v[22:23] op_sel_hi:[0,1,1] neg_lo:[0,0,1] neg_hi:[0,0,1]
	v_cvt_pk_bf16_f32 v39, v0, v1
	v_lshl_add_u64 v[6:7], v[6:7], 0, s[16:17]
	global_store_dwordx4 v[6:7], v[36:39], off offset:-4096 nt
	s_waitcnt vmcnt(31)
	v_lshlrev_b32_e32 v10, 16, v220
	v_and_b32_e32 v11, 0xffff0000, v220
	v_cndmask_b32_e32 v35, v188, v156, vcc
	v_lshlrev_b32_e32 v0, 16, v35
	v_and_b32_e32 v1, 0xffff0000, v35
	v_pk_add_f32 v[0:1], v[10:11], v[0:1] neg_lo:[0,1] neg_hi:[0,1]
	v_pk_add_f32 v[26:27], v[26:27], v[0:1]
	v_pk_fma_f32 v[0:1], v[24:25], v[26:27], v[10:11] op_sel_hi:[0,1,1] neg_lo:[0,0,1] neg_hi:[0,0,1]
	v_cvt_pk_bf16_f32 v36, v0, v1
	v_lshlrev_b32_e32 v12, 16, v221
	v_and_b32_e32 v13, 0xffff0000, v221
	v_cndmask_b32_e32 v35, v189, v157, vcc
	v_lshlrev_b32_e32 v0, 16, v35
	v_and_b32_e32 v1, 0xffff0000, v35
	v_pk_add_f32 v[0:1], v[12:13], v[0:1] neg_lo:[0,1] neg_hi:[0,1]
	v_pk_add_f32 v[28:29], v[28:29], v[0:1]
	v_pk_fma_f32 v[0:1], v[24:25], v[28:29], v[12:13] op_sel_hi:[0,1,1] neg_lo:[0,0,1] neg_hi:[0,0,1]
	v_cvt_pk_bf16_f32 v37, v0, v1
	v_lshlrev_b32_e32 v14, 16, v222
	v_and_b32_e32 v15, 0xffff0000, v222
	v_cndmask_b32_e32 v35, v190, v158, vcc
	v_lshlrev_b32_e32 v0, 16, v35
	v_and_b32_e32 v1, 0xffff0000, v35
	v_pk_add_f32 v[0:1], v[14:15], v[0:1] neg_lo:[0,1] neg_hi:[0,1]
	v_pk_add_f32 v[30:31], v[30:31], v[0:1]
	v_pk_fma_f32 v[0:1], v[24:25], v[30:31], v[14:15] op_sel_hi:[0,1,1] neg_lo:[0,0,1] neg_hi:[0,0,1]
	v_cvt_pk_bf16_f32 v38, v0, v1
	v_lshlrev_b32_e32 v22, 16, v223
	v_and_b32_e32 v23, 0xffff0000, v223
	v_cndmask_b32_e32 v35, v191, v159, vcc
	v_lshlrev_b32_e32 v0, 16, v35
	v_and_b32_e32 v1, 0xffff0000, v35
	v_pk_add_f32 v[0:1], v[22:23], v[0:1] neg_lo:[0,1] neg_hi:[0,1]
	v_pk_add_f32 v[8:9], v[8:9], v[0:1]
	v_pk_fma_f32 v[0:1], v[24:25], v[8:9], v[22:23] op_sel_hi:[0,1,1] neg_lo:[0,0,1] neg_hi:[0,0,1]
	v_cvt_pk_bf16_f32 v39, v0, v1
	global_store_dwordx4 v[6:7], v[36:39], off offset:-2048 nt
	s_waitcnt vmcnt(31)
	v_lshlrev_b32_e32 v10, 16, v224
	v_and_b32_e32 v11, 0xffff0000, v224
	v_cndmask_b32_e32 v35, v192, v160, vcc
	v_lshlrev_b32_e32 v0, 16, v35
	v_and_b32_e32 v1, 0xffff0000, v35
	v_pk_add_f32 v[0:1], v[10:11], v[0:1] neg_lo:[0,1] neg_hi:[0,1]
	v_pk_add_f32 v[26:27], v[26:27], v[0:1]
	v_pk_fma_f32 v[0:1], v[24:25], v[26:27], v[10:11] op_sel_hi:[0,1,1] neg_lo:[0,0,1] neg_hi:[0,0,1]
	v_cvt_pk_bf16_f32 v36, v0, v1
	v_lshlrev_b32_e32 v12, 16, v225
	v_and_b32_e32 v13, 0xffff0000, v225
	v_cndmask_b32_e32 v35, v193, v161, vcc
	v_lshlrev_b32_e32 v0, 16, v35
	v_and_b32_e32 v1, 0xffff0000, v35
	v_pk_add_f32 v[0:1], v[12:13], v[0:1] neg_lo:[0,1] neg_hi:[0,1]
	v_pk_add_f32 v[28:29], v[28:29], v[0:1]
	v_pk_fma_f32 v[0:1], v[24:25], v[28:29], v[12:13] op_sel_hi:[0,1,1] neg_lo:[0,0,1] neg_hi:[0,0,1]
	v_cvt_pk_bf16_f32 v37, v0, v1
	v_lshlrev_b32_e32 v14, 16, v226
	v_and_b32_e32 v15, 0xffff0000, v226
	v_cndmask_b32_e32 v35, v194, v162, vcc
	v_lshlrev_b32_e32 v0, 16, v35
	v_and_b32_e32 v1, 0xffff0000, v35
	v_pk_add_f32 v[0:1], v[14:15], v[0:1] neg_lo:[0,1] neg_hi:[0,1]
	v_pk_add_f32 v[30:31], v[30:31], v[0:1]
	v_pk_fma_f32 v[0:1], v[24:25], v[30:31], v[14:15] op_sel_hi:[0,1,1] neg_lo:[0,0,1] neg_hi:[0,0,1]
	v_cvt_pk_bf16_f32 v38, v0, v1
	v_lshlrev_b32_e32 v22, 16, v227
	v_and_b32_e32 v23, 0xffff0000, v227
	v_cndmask_b32_e32 v35, v195, v163, vcc
	v_lshlrev_b32_e32 v0, 16, v35
	v_and_b32_e32 v1, 0xffff0000, v35
	v_pk_add_f32 v[0:1], v[22:23], v[0:1] neg_lo:[0,1] neg_hi:[0,1]
	v_pk_add_f32 v[8:9], v[8:9], v[0:1]
	v_pk_fma_f32 v[0:1], v[24:25], v[8:9], v[22:23] op_sel_hi:[0,1,1] neg_lo:[0,0,1] neg_hi:[0,0,1]
	v_cvt_pk_bf16_f32 v39, v0, v1
	global_store_dwordx4 v[6:7], v[36:39], off nt
	s_waitcnt vmcnt(31)
	v_lshlrev_b32_e32 v10, 16, v228
	v_and_b32_e32 v11, 0xffff0000, v228
	v_cndmask_b32_e32 v35, v196, v164, vcc
	v_lshlrev_b32_e32 v0, 16, v35
	v_and_b32_e32 v1, 0xffff0000, v35
	v_pk_add_f32 v[0:1], v[10:11], v[0:1] neg_lo:[0,1] neg_hi:[0,1]
	v_pk_add_f32 v[26:27], v[26:27], v[0:1]
	v_pk_fma_f32 v[0:1], v[24:25], v[26:27], v[10:11] op_sel_hi:[0,1,1] neg_lo:[0,0,1] neg_hi:[0,0,1]
	v_cvt_pk_bf16_f32 v36, v0, v1
	v_lshlrev_b32_e32 v12, 16, v229
	v_and_b32_e32 v13, 0xffff0000, v229
	v_cndmask_b32_e32 v35, v197, v165, vcc
	v_lshlrev_b32_e32 v0, 16, v35
	v_and_b32_e32 v1, 0xffff0000, v35
	v_pk_add_f32 v[0:1], v[12:13], v[0:1] neg_lo:[0,1] neg_hi:[0,1]
	v_pk_add_f32 v[28:29], v[28:29], v[0:1]
	v_pk_fma_f32 v[0:1], v[24:25], v[28:29], v[12:13] op_sel_hi:[0,1,1] neg_lo:[0,0,1] neg_hi:[0,0,1]
	v_cvt_pk_bf16_f32 v37, v0, v1
	v_lshlrev_b32_e32 v14, 16, v230
	v_and_b32_e32 v15, 0xffff0000, v230
	v_cndmask_b32_e32 v35, v198, v166, vcc
	v_lshlrev_b32_e32 v0, 16, v35
	v_and_b32_e32 v1, 0xffff0000, v35
	v_pk_add_f32 v[0:1], v[14:15], v[0:1] neg_lo:[0,1] neg_hi:[0,1]
	v_pk_add_f32 v[30:31], v[30:31], v[0:1]
	v_pk_fma_f32 v[0:1], v[24:25], v[30:31], v[14:15] op_sel_hi:[0,1,1] neg_lo:[0,0,1] neg_hi:[0,0,1]
	v_cvt_pk_bf16_f32 v38, v0, v1
	v_lshlrev_b32_e32 v22, 16, v231
	v_and_b32_e32 v23, 0xffff0000, v231
	v_cndmask_b32_e32 v35, v199, v167, vcc
	v_lshlrev_b32_e32 v0, 16, v35
	v_and_b32_e32 v1, 0xffff0000, v35
	v_pk_add_f32 v[0:1], v[22:23], v[0:1] neg_lo:[0,1] neg_hi:[0,1]
	v_pk_add_f32 v[8:9], v[8:9], v[0:1]
	v_pk_fma_f32 v[0:1], v[24:25], v[8:9], v[22:23] op_sel_hi:[0,1,1] neg_lo:[0,0,1] neg_hi:[0,0,1]
	v_cvt_pk_bf16_f32 v39, v0, v1
	global_store_dwordx4 v[6:7], v[36:39], off offset:2048 nt
	s_branch .LBB0_930
